# merged K-loop + issue first 4 MFMAs of each 32-MFMA step before the barrier (hide barrier release latency)
# speedup vs baseline: 1.0309x; 1.0084x over previous
; #define PG8_STAGE(bufoff, gbase, voff) do { _Pragma("unroll") for (int _i = 0; _i < 2; ++_i) \
;         __builtin_amdgcn_global_load_lds((const unsigned*)((const char*)(gbase) + (voff)[_i]), (LAS unsigned*)(lds + (bufoff) + ldsw + _i * 8192), 16, 0, 0); } while (0)
; #define PG8_LDA(dst, b, h) do { _Pragma("unroll") for (int m = 0; m < 4; ++m) _Pragma("unroll") for (int k = 0; k < 2; ++k) dst[m][k] = *(const LAS bf16x8*)(lds + PG8_SA(b, h) + aoff + m * 2048 + k * 1024); } while (0)
; #define PG8_LDB(dst, b, h) do { _Pragma("unroll") for (int n = 0; n < 2; ++n) _Pragma("unroll") for (int k = 0; k < 2; ++k) dst[n][k] = *(const LAS bf16x8*)(lds + PG8_SB(b, h) + boff + n * 2048 + k * 1024); } while (0)
; #define PG8_MMA(ai, bj, At, Bt) do { __builtin_amdgcn_s_setprio(1); _Pragma("unroll") for (int m = 0; m < 4; ++m) _Pragma("unroll") for (int n = 0; n < 2; ++n) _Pragma("unroll") for (int k = 0; k < 2; ++k) \
;         acc[ai][bj][m][n] = __builtin_amdgcn_mfma_f32_16x16x32_bf16(Bt[n][k], At[m][k], acc[ai][bj][m][n], 0, 0, 0); __builtin_amdgcn_s_setprio(0); } while (0)
; #define PG8_WAIT_L(n) asm volatile("s_waitcnt lgkmcnt(" #n ")" ::: "memory")
; #define PG8_BAR __builtin_amdgcn_s_barrier()
; #define PG8_SCHED __builtin_amdgcn_sched_barrier(0)
; template <class Epi>
; __device__ __forceinline__ void gemm_phase(LAS unsigned char* lds, const Gemm g, const Sched& S, const Epi& E) {
;     ...
;         for (int t = 0; t < nt; t += 2) {
;             const bool last = (t == nt - 2);
;             const char* a1 = cA + (size_t)(t + 1) * kstep;
;             const char* a2 = last ? nA : cA + (size_t)(t + 2) * kstep; const char* b2 = last ? nB : cB + (size_t)(t + 2) * kstep;
;             const char* a3 = a2 + kstep; const char* b3 = b2 + kstep;
;             PG8_LDB(B0, 0, 0); PG8_SCHED; PG8_LDA(At, 0, 0); PG8_STAGE(PG8_SA(1, 1), a1 + hstepA, voffA);
;             PG8_WAIT_L(8); PG8_BAR; PG8_WAIT_L(0); PG8_MMA(0, 0, At, B0); PG8_BAR; PG8_SCHED;
;             PG8_LDB(B1, 0, 1); PG8_STAGE(PG8_SB(0, 0), b2, voffB);
;             PG8_BAR; PG8_WAIT_L(0); PG8_MMA(0, 1, At, B1); PG8_BAR;
;             PG8_LDA(At, 0, 1); PG8_STAGE(PG8_SA(0, 0), a2, voffA);
;             PG8_BAR; PG8_WAIT_L(0); PG8_MMA(1, 0, At, B0); PG8_BAR; PG8_SCHED;
.LBB0_400:
	s_add_i32 s14, s66, 2
	s_add_u32 s8, s92, 0x80
	s_addc_u32 s9, s93, 0
	s_add_i32 s15, 0, 0x10000
	v_add_u32_e32 v148, s15, v152
	ds_read_b128 v[144:147], v148
	ds_read_b128 v[172:175], v148 offset:1024
	ds_read_b128 v[176:179], v148 offset:2048
	ds_read_b128 v[180:183], v148 offset:3072
	s_cmp_eq_u32 s71, s66
	s_cselect_b32 s95, s55, s9
	s_cselect_b32 s94, s57, s8
	s_cselect_b32 s97, s59, s35
	s_cselect_b32 s96, s65, s34
	v_lshl_add_u64 v[148:149], s[92:93], 0, v[138:139]
	s_add_i32 m0, s42, 0xc000
	ds_read_b128 v[184:187], v171
	ds_read_b128 v[188:191], v171 offset:1024
	ds_read_b128 v[196:199], v171 offset:2048
	ds_read_b128 v[200:203], v171 offset:3072
	ds_read_b128 v[204:207], v171 offset:4096
	ds_read_b128 v[208:211], v171 offset:5120
	ds_read_b128 v[212:215], v171 offset:6144
	ds_read_b128 v[222:225], v171 offset:7168
	global_load_lds_dwordx4 v[148:149], off
	v_lshl_add_u64 v[148:149], s[92:93], 0, v[140:141]
	s_add_i32 m0, s42, 0xe000
	s_nop 0
	global_load_lds_dwordx4 v[148:149], off
	s_add_i32 s8, 0, 0x14000
	v_add_u32_e32 v148, s8, v152
	ds_read_b128 v[226:229], v148
	ds_read_b128 v[230:233], v148 offset:1024
	ds_read_b128 v[234:237], v148 offset:2048
	ds_read_b128 v[238:241], v148 offset:3072
	s_waitcnt vmcnt(8)
	s_waitcnt lgkmcnt(0)
	v_mfma_f32_16x16x32_bf16 v[126:129], v[144:147], v[184:187], v[126:129]
	v_mfma_f32_16x16x32_bf16 v[122:125], v[176:179], v[184:187], v[122:125]
	v_mfma_f32_16x16x32_bf16 v[110:113], v[144:147], v[196:199], v[110:113]
	v_mfma_f32_16x16x32_bf16 v[106:109], v[176:179], v[196:199], v[106:109]
	s_barrier
	s_setprio 1
	v_mfma_f32_16x16x32_bf16 v[94:97], v[144:147], v[204:207], v[94:97]
	v_mfma_f32_16x16x32_bf16 v[90:93], v[176:179], v[204:207], v[90:93]
	v_mfma_f32_16x16x32_bf16 v[78:81], v[144:147], v[212:215], v[78:81]
	v_mfma_f32_16x16x32_bf16 v[74:77], v[176:179], v[212:215], v[74:77]
	v_mfma_f32_16x16x32_bf16 v[126:129], v[172:175], v[188:191], v[126:129]
	v_mfma_f32_16x16x32_bf16 v[122:125], v[180:183], v[188:191], v[122:125]
	v_mfma_f32_16x16x32_bf16 v[110:113], v[172:175], v[200:203], v[110:113]
	v_mfma_f32_16x16x32_bf16 v[106:109], v[180:183], v[200:203], v[106:109]
	v_mfma_f32_16x16x32_bf16 v[94:97], v[172:175], v[208:211], v[94:97]
	v_mfma_f32_16x16x32_bf16 v[90:93], v[180:183], v[208:211], v[90:93]
	v_mfma_f32_16x16x32_bf16 v[78:81], v[172:175], v[222:225], v[78:81]
	v_mfma_f32_16x16x32_bf16 v[74:77], v[180:183], v[222:225], v[74:77]
	v_mfma_f32_16x16x32_bf16 v[118:121], v[226:229], v[184:187], v[118:121]
	v_mfma_f32_16x16x32_bf16 v[114:117], v[234:237], v[184:187], v[114:117]
	v_mfma_f32_16x16x32_bf16 v[102:105], v[226:229], v[196:199], v[102:105]
	v_mfma_f32_16x16x32_bf16 v[98:101], v[234:237], v[196:199], v[98:101]
	v_mfma_f32_16x16x32_bf16 v[86:89], v[226:229], v[204:207], v[86:89]
	v_mfma_f32_16x16x32_bf16 v[82:85], v[234:237], v[204:207], v[82:85]
	v_mfma_f32_16x16x32_bf16 v[70:73], v[226:229], v[212:215], v[70:73]
	v_mfma_f32_16x16x32_bf16 v[66:69], v[234:237], v[212:215], v[66:69]
	v_mfma_f32_16x16x32_bf16 v[118:121], v[230:233], v[188:191], v[118:121]
	v_mfma_f32_16x16x32_bf16 v[114:117], v[238:241], v[188:191], v[114:117]
	v_mfma_f32_16x16x32_bf16 v[102:105], v[230:233], v[200:203], v[102:105]
	v_mfma_f32_16x16x32_bf16 v[98:101], v[238:241], v[200:203], v[98:101]
	v_mfma_f32_16x16x32_bf16 v[86:89], v[230:233], v[208:211], v[86:89]
	v_mfma_f32_16x16x32_bf16 v[82:85], v[238:241], v[208:211], v[82:85]
	v_mfma_f32_16x16x32_bf16 v[70:73], v[230:233], v[222:225], v[70:73]
	v_mfma_f32_16x16x32_bf16 v[66:69], v[238:241], v[222:225], v[66:69]
	s_setprio 0
	s_barrier
	s_add_i32 s9, s15, s39
	v_lshl_add_u64 v[148:149], s[96:97], 0, v[132:133]
	s_mov_b32 m0, s9
	v_lshl_add_u64 v[192:193], s[96:97], 0, v[136:137]
	global_load_lds_dwordx4 v[148:149], off
	s_add_i32 m0, s9, 0x2000
	s_nop 0
	global_load_lds_dwordx4 v[192:193], off
	s_mov_b32 m0, s42
	v_lshl_add_u64 v[194:195], s[94:95], 0, v[130:131]
	ds_read_b128 v[184:187], v171 offset:16384
	ds_read_b128 v[188:191], v171 offset:17408
	ds_read_b128 v[196:199], v171 offset:18432
	ds_read_b128 v[200:203], v171 offset:19456
	ds_read_b128 v[204:207], v171 offset:20480
	ds_read_b128 v[208:211], v171 offset:21504
	ds_read_b128 v[212:215], v171 offset:22528
	ds_read_b128 v[222:225], v171 offset:23552
	global_load_lds_dwordx4 v[194:195], off
	v_lshl_add_u64 v[216:217], s[94:95], 0, v[134:135]
	s_mov_b32 m0, s43
	s_nop 0
	global_load_lds_dwordx4 v[216:217], off
	s_add_u32 s96, s96, s78
	s_addc_u32 s97, s97, s79
	s_add_i32 s8, s8, s39
	v_lshl_add_u64 v[242:243], s[96:97], 0, v[132:133]
	s_mov_b32 m0, s8
	v_lshl_add_u64 v[244:245], s[96:97], 0, v[136:137]
	global_load_lds_dwordx4 v[242:243], off
	s_add_i32 m0, s8, 0x2000
	s_nop 0
	global_load_lds_dwordx4 v[244:245], off
	s_waitcnt vmcnt(8)
	s_waitcnt lgkmcnt(0)
	v_mfma_f32_16x16x32_bf16 v[62:65], v[144:147], v[184:187], v[62:65]
	v_mfma_f32_16x16x32_bf16 v[58:61], v[176:179], v[184:187], v[58:61]
	v_mfma_f32_16x16x32_bf16 v[50:53], v[144:147], v[196:199], v[50:53]
	v_mfma_f32_16x16x32_bf16 v[42:45], v[176:179], v[196:199], v[42:45]
	s_barrier
; #define PG8_STAGE(bufoff, gbase, voff) do { _Pragma("unroll") for (int _i = 0; _i < 2; ++_i) \
;         __builtin_amdgcn_global_load_lds((const unsigned*)((const char*)(gbase) + (voff)[_i]), (LAS unsigned*)(lds + (bufoff) + ldsw + _i * 8192), 16, 0, 0); } while (0)
; #define PG8_LDA(dst, b, h) do { _Pragma("unroll") for (int m = 0; m < 4; ++m) _Pragma("unroll") for (int k = 0; k < 2; ++k) dst[m][k] = *(const LAS bf16x8*)(lds + PG8_SA(b, h) + aoff + m * 2048 + k * 1024); } while (0)
; #define PG8_LDB(dst, b, h) do { _Pragma("unroll") for (int n = 0; n < 2; ++n) _Pragma("unroll") for (int k = 0; k < 2; ++k) dst[n][k] = *(const LAS bf16x8*)(lds + PG8_SB(b, h) + boff + n * 2048 + k * 1024); } while (0)
; #define PG8_MMA(ai, bj, At, Bt) do { __builtin_amdgcn_s_setprio(1); _Pragma("unroll") for (int m = 0; m < 4; ++m) _Pragma("unroll") for (int n = 0; n < 2; ++n) _Pragma("unroll") for (int k = 0; k < 2; ++k) \
;         acc[ai][bj][m][n] = __builtin_amdgcn_mfma_f32_16x16x32_bf16(Bt[n][k], At[m][k], acc[ai][bj][m][n], 0, 0, 0); __builtin_amdgcn_s_setprio(0); } while (0)
; #define PG8_WAIT_V(n) asm volatile("s_waitcnt vmcnt(" #n ")" ::: "memory")
; #define PG8_WAIT_L(n) asm volatile("s_waitcnt lgkmcnt(" #n ")" ::: "memory")
; #define PG8_BAR __builtin_amdgcn_s_barrier()
; #define PG8_SCHED __builtin_amdgcn_sched_barrier(0)
; template <class Epi>
; __device__ __forceinline__ void gemm_phase(LAS unsigned char* lds, const Gemm g, const Sched& S, const Epi& E) {
;     ...
;             PG8_BAR; PG8_WAIT_L(0); PG8_MMA(1, 0, At, B0); PG8_BAR; PG8_SCHED;
;             PG8_STAGE(PG8_SB(0, 1), b2 + hstepB, voffB);
;             PG8_WAIT_V(6); PG8_BAR; PG8_MMA(1, 1, At, B1); PG8_BAR;
;             PG8_LDB(B0, 1, 0); PG8_SCHED; PG8_LDA(At, 1, 0); PG8_STAGE(PG8_SA(0, 1), a2 + hstepA, voffA);
;             PG8_WAIT_L(8); PG8_BAR; PG8_WAIT_L(0); PG8_MMA(0, 0, At, B0); PG8_BAR; PG8_SCHED;
;             PG8_LDB(B1, 1, 1); PG8_STAGE(PG8_SB(1, 0), b3, voffB);
;             PG8_BAR; PG8_WAIT_L(0); PG8_MMA(0, 1, At, B1); PG8_BAR;
;             PG8_LDA(At, 1, 1); PG8_STAGE(PG8_SA(1, 0), a3, voffA);
;             PG8_BAR; PG8_WAIT_L(0); PG8_MMA(1, 0, At, B0); PG8_BAR; PG8_SCHED;
	s_setprio 1
	v_mfma_f32_16x16x32_bf16 v[34:37], v[144:147], v[204:207], v[34:37]
	v_mfma_f32_16x16x32_bf16 v[26:29], v[176:179], v[204:207], v[26:29]
	v_mfma_f32_16x16x32_bf16 v[18:21], v[144:147], v[212:215], v[18:21]
	v_mfma_f32_16x16x32_bf16 v[10:13], v[176:179], v[212:215], v[10:13]
	v_mfma_f32_16x16x32_bf16 v[62:65], v[172:175], v[188:191], v[62:65]
	v_mfma_f32_16x16x32_bf16 v[58:61], v[180:183], v[188:191], v[58:61]
	v_mfma_f32_16x16x32_bf16 v[50:53], v[172:175], v[200:203], v[50:53]
	v_mfma_f32_16x16x32_bf16 v[42:45], v[180:183], v[200:203], v[42:45]
	v_mfma_f32_16x16x32_bf16 v[34:37], v[172:175], v[208:211], v[34:37]
	v_mfma_f32_16x16x32_bf16 v[26:29], v[180:183], v[208:211], v[26:29]
	v_mfma_f32_16x16x32_bf16 v[18:21], v[172:175], v[222:225], v[18:21]
	v_mfma_f32_16x16x32_bf16 v[10:13], v[180:183], v[222:225], v[10:13]
	v_mfma_f32_16x16x32_bf16 v[54:57], v[226:229], v[184:187], v[54:57]
	v_mfma_f32_16x16x32_bf16 v[46:49], v[234:237], v[184:187], v[46:49]
	v_mfma_f32_16x16x32_bf16 v[38:41], v[226:229], v[196:199], v[38:41]
	v_mfma_f32_16x16x32_bf16 v[30:33], v[234:237], v[196:199], v[30:33]
	v_mfma_f32_16x16x32_bf16 v[22:25], v[226:229], v[204:207], v[22:25]
	v_mfma_f32_16x16x32_bf16 v[14:17], v[234:237], v[204:207], v[14:17]
	v_mfma_f32_16x16x32_bf16 v[6:9], v[226:229], v[212:215], v[6:9]
	v_mfma_f32_16x16x32_bf16 v[2:5], v[234:237], v[212:215], v[2:5]
	v_mfma_f32_16x16x32_bf16 v[54:57], v[230:233], v[188:191], v[54:57]
	v_mfma_f32_16x16x32_bf16 v[46:49], v[238:241], v[188:191], v[46:49]
	v_mfma_f32_16x16x32_bf16 v[38:41], v[230:233], v[200:203], v[38:41]
	v_mfma_f32_16x16x32_bf16 v[30:33], v[238:241], v[200:203], v[30:33]
	v_mfma_f32_16x16x32_bf16 v[22:25], v[230:233], v[208:211], v[22:25]
	v_mfma_f32_16x16x32_bf16 v[14:17], v[238:241], v[208:211], v[14:17]
	v_mfma_f32_16x16x32_bf16 v[6:9], v[230:233], v[222:225], v[6:9]
	v_mfma_f32_16x16x32_bf16 v[2:5], v[238:241], v[222:225], v[2:5]
	s_setprio 0
	s_barrier
	s_add_i32 s8, 0, 0x18000
	v_add_u32_e32 v180, s8, v152
	ds_read_b128 v[144:147], v180
	ds_read_b128 v[172:175], v180 offset:1024
	ds_read_b128 v[176:179], v180 offset:2048
	ds_read_b128 v[180:183], v180 offset:3072
	s_add_u32 s94, s94, s4
	s_addc_u32 s95, s95, s5
	s_mov_b32 m0, s52
	v_lshl_add_u64 v[226:227], s[94:95], 0, v[130:131]
	ds_read_b128 v[184:187], v171 offset:32768
	ds_read_b128 v[188:191], v171 offset:33792
	ds_read_b128 v[196:199], v171 offset:34816
	ds_read_b128 v[200:203], v171 offset:35840
	ds_read_b128 v[204:207], v171 offset:36864
	ds_read_b128 v[208:211], v171 offset:37888
	ds_read_b128 v[212:215], v171 offset:38912
	ds_read_b128 v[222:225], v171 offset:39936
	global_load_lds_dwordx4 v[226:227], off
	v_lshl_add_u64 v[226:227], s[94:95], 0, v[134:135]
	s_mov_b32 m0, s53
	s_nop 0
	global_load_lds_dwordx4 v[226:227], off
	s_add_i32 s9, 0, 0x1c000
	v_add_u32_e32 v218, s9, v152
	ds_read_b128 v[226:229], v218
	ds_read_b128 v[230:233], v218 offset:1024
	ds_read_b128 v[234:237], v218 offset:2048
	ds_read_b128 v[238:241], v218 offset:3072
	s_waitcnt vmcnt(8)
	s_waitcnt lgkmcnt(0)
	v_mfma_f32_16x16x32_bf16 v[126:129], v[144:147], v[184:187], v[126:129]
	v_mfma_f32_16x16x32_bf16 v[122:125], v[176:179], v[184:187], v[122:125]
	v_mfma_f32_16x16x32_bf16 v[110:113], v[144:147], v[196:199], v[110:113]
	v_mfma_f32_16x16x32_bf16 v[106:109], v[176:179], v[196:199], v[106:109]
	s_barrier
	s_setprio 1
	v_mfma_f32_16x16x32_bf16 v[94:97], v[144:147], v[204:207], v[94:97]
	v_mfma_f32_16x16x32_bf16 v[90:93], v[176:179], v[204:207], v[90:93]
	v_mfma_f32_16x16x32_bf16 v[78:81], v[144:147], v[212:215], v[78:81]
	v_mfma_f32_16x16x32_bf16 v[74:77], v[176:179], v[212:215], v[74:77]
	v_mfma_f32_16x16x32_bf16 v[126:129], v[172:175], v[188:191], v[126:129]
	v_mfma_f32_16x16x32_bf16 v[122:125], v[180:183], v[188:191], v[122:125]
	v_mfma_f32_16x16x32_bf16 v[110:113], v[172:175], v[200:203], v[110:113]
	v_mfma_f32_16x16x32_bf16 v[106:109], v[180:183], v[200:203], v[106:109]
	v_mfma_f32_16x16x32_bf16 v[94:97], v[172:175], v[208:211], v[94:97]
	v_mfma_f32_16x16x32_bf16 v[90:93], v[180:183], v[208:211], v[90:93]
	v_mfma_f32_16x16x32_bf16 v[78:81], v[172:175], v[222:225], v[78:81]
	v_mfma_f32_16x16x32_bf16 v[74:77], v[180:183], v[222:225], v[74:77]
	v_mfma_f32_16x16x32_bf16 v[118:121], v[226:229], v[184:187], v[118:121]
	v_mfma_f32_16x16x32_bf16 v[114:117], v[234:237], v[184:187], v[114:117]
	v_mfma_f32_16x16x32_bf16 v[102:105], v[226:229], v[196:199], v[102:105]
	v_mfma_f32_16x16x32_bf16 v[98:101], v[234:237], v[196:199], v[98:101]
	v_mfma_f32_16x16x32_bf16 v[86:89], v[226:229], v[204:207], v[86:89]
	v_mfma_f32_16x16x32_bf16 v[82:85], v[234:237], v[204:207], v[82:85]
	v_mfma_f32_16x16x32_bf16 v[70:73], v[226:229], v[212:215], v[70:73]
	v_mfma_f32_16x16x32_bf16 v[66:69], v[234:237], v[212:215], v[66:69]
	v_mfma_f32_16x16x32_bf16 v[118:121], v[230:233], v[188:191], v[118:121]
	v_mfma_f32_16x16x32_bf16 v[114:117], v[238:241], v[188:191], v[114:117]
	v_mfma_f32_16x16x32_bf16 v[102:105], v[230:233], v[200:203], v[102:105]
	v_mfma_f32_16x16x32_bf16 v[98:101], v[238:241], v[200:203], v[98:101]
	v_mfma_f32_16x16x32_bf16 v[86:89], v[230:233], v[208:211], v[86:89]
	v_mfma_f32_16x16x32_bf16 v[82:85], v[238:241], v[208:211], v[82:85]
	v_mfma_f32_16x16x32_bf16 v[70:73], v[230:233], v[222:225], v[70:73]
	v_mfma_f32_16x16x32_bf16 v[66:69], v[238:241], v[222:225], v[66:69]
	s_setprio 0
	s_barrier
; __device__ __forceinline__ float pre_get(const Pre& p, int ai, int m, int fr) { return __shfl(p.v[ai], m * 16 + fr); }
; __device__ __forceinline__ float rstd_pre(const float* ss, float v) { return ss ? rsqrtf(v * (1.0f / 2048.0f) + 1e-6f) : 1.0f; }
; #define PG8_STAGE(bufoff, gbase, voff) do { _Pragma("unroll") for (int _i = 0; _i < 2; ++_i) \
;         __builtin_amdgcn_global_load_lds((const unsigned*)((const char*)(gbase) + (voff)[_i]), (LAS unsigned*)(lds + (bufoff) + ldsw + _i * 8192), 16, 0, 0); } while (0)
; #define PG8_LDA(dst, b, h) do { _Pragma("unroll") for (int m = 0; m < 4; ++m) _Pragma("unroll") for (int k = 0; k < 2; ++k) dst[m][k] = *(const LAS bf16x8*)(lds + PG8_SA(b, h) + aoff + m * 2048 + k * 1024); } while (0)
; #define PG8_LDB(dst, b, h) do { _Pragma("unroll") for (int n = 0; n < 2; ++n) _Pragma("unroll") for (int k = 0; k < 2; ++k) dst[n][k] = *(const LAS bf16x8*)(lds + PG8_SB(b, h) + boff + n * 2048 + k * 1024); } while (0)
; #define PG8_BAR __builtin_amdgcn_s_barrier()
; template <class Epi>
; __device__ __forceinline__ void gemm_phase(LAS unsigned char* lds, const Gemm g, const Sched& S, const Epi& E) {
;     ...
;             PG8_LDB(B1, 1, 1); PG8_STAGE(PG8_SB(1, 0), b3, voffB);
;             PG8_BAR; PG8_WAIT_L(0); PG8_MMA(0, 1, At, B1); PG8_BAR;
;             PG8_LDA(At, 1, 1); PG8_STAGE(PG8_SA(1, 0), a3, voffA);
;             PG8_BAR; PG8_WAIT_L(0); PG8_MMA(1, 0, At, B0); PG8_BAR; PG8_SCHED;
;             PG8_STAGE(PG8_SB(1, 1), b3 + hstepB, voffB);
;             PG8_WAIT_V(6); PG8_BAR; PG8_MMA(1, 1, At, B1); PG8_BAR;
;         }
;     __device__ __forceinline__ void operator()(const Acc& acc, const Unit& u, int wr, int wc, int fr, int fq, const Pre& pre) const {
;     ...
;             for (int m = 0; m < 4; ++m) rs[ai][m] = rstd_pre(ss, pre_get(pre, ai, m, fr));
; #pragma unroll
;         for (int ai = 0; ai < 2; ++ai)
; #pragma unroll
;             for (int m = 0; m < 4; ++m) { float mx = -INFINITY;
; #pragma unroll
;                 for (int bj = 0; bj < 2; ++bj)
; #pragma unroll
;                     for (int n = 0; n < 2; ++n) { const f32x4 a = acc[ai][bj][m][n]; mx = fmaxf(mx, fmaxf(fmaxf(a[0], a[1]), fmaxf(a[2], a[3]))); }
;                 mx *= rs[ai][m];
;                 mx = fmaxf(mx, __shfl_xor(mx, 16)); mx = fmaxf(mx, __shfl_xor(mx, 32));
;                 if (fq == 0) X[(ai * 128 + wr * 64 + m * 16 + fr) * 4 + wc] = mx; }
	s_add_i32 s8, s8, s39
	v_lshl_add_u64 v[148:149], v[148:149], 0, s[60:61]
	s_mov_b32 m0, s8
	s_nop 0
	global_load_lds_dwordx4 v[148:149], off
	v_lshl_add_u64 v[148:149], v[192:193], 0, s[60:61]
	s_add_i32 m0, s8, 0x2000
	s_nop 0
	global_load_lds_dwordx4 v[148:149], off
	s_mov_b32 m0, s67
	v_lshl_add_u64 v[148:149], v[194:195], 0, s[60:61]
	ds_read_b128 v[184:187], v171 offset:49152
	ds_read_b128 v[188:191], v171 offset:50176
	ds_read_b128 v[196:199], v171 offset:51200
	ds_read_b128 v[200:203], v171 offset:52224
	ds_read_b128 v[204:207], v171 offset:53248
	ds_read_b128 v[208:211], v171 offset:54272
	ds_read_b128 v[212:215], v171 offset:55296
	ds_read_b128 v[222:225], v171 offset:56320
	global_load_lds_dwordx4 v[148:149], off
	v_lshl_add_u64 v[148:149], v[216:217], 0, s[60:61]
	s_mov_b32 m0, s2
	s_nop 0
	global_load_lds_dwordx4 v[148:149], off
	s_add_i32 s8, s9, s39
	v_lshl_add_u64 v[148:149], v[242:243], 0, s[60:61]
	s_mov_b32 m0, s8
	s_nop 0
	global_load_lds_dwordx4 v[148:149], off
	v_lshl_add_u64 v[148:149], v[244:245], 0, s[60:61]
	s_add_i32 m0, s8, 0x2000
	s_nop 0
	global_load_lds_dwordx4 v[148:149], off
	s_waitcnt vmcnt(8)
	s_waitcnt lgkmcnt(0)
	v_mfma_f32_16x16x32_bf16 v[62:65], v[144:147], v[184:187], v[62:65]
	v_mfma_f32_16x16x32_bf16 v[58:61], v[176:179], v[184:187], v[58:61]
	v_mfma_f32_16x16x32_bf16 v[50:53], v[144:147], v[196:199], v[50:53]
	v_mfma_f32_16x16x32_bf16 v[42:45], v[176:179], v[196:199], v[42:45]
	s_barrier
	s_setprio 1
	v_mfma_f32_16x16x32_bf16 v[34:37], v[144:147], v[204:207], v[34:37]
	v_mfma_f32_16x16x32_bf16 v[26:29], v[176:179], v[204:207], v[26:29]
	v_mfma_f32_16x16x32_bf16 v[18:21], v[144:147], v[212:215], v[18:21]
	v_mfma_f32_16x16x32_bf16 v[10:13], v[176:179], v[212:215], v[10:13]
	v_mfma_f32_16x16x32_bf16 v[62:65], v[172:175], v[188:191], v[62:65]
	v_mfma_f32_16x16x32_bf16 v[58:61], v[180:183], v[188:191], v[58:61]
	v_mfma_f32_16x16x32_bf16 v[50:53], v[172:175], v[200:203], v[50:53]
	v_mfma_f32_16x16x32_bf16 v[42:45], v[180:183], v[200:203], v[42:45]
	v_mfma_f32_16x16x32_bf16 v[34:37], v[172:175], v[208:211], v[34:37]
	v_mfma_f32_16x16x32_bf16 v[26:29], v[180:183], v[208:211], v[26:29]
	v_mfma_f32_16x16x32_bf16 v[18:21], v[172:175], v[222:225], v[18:21]
	v_mfma_f32_16x16x32_bf16 v[10:13], v[180:183], v[222:225], v[10:13]
	v_mfma_f32_16x16x32_bf16 v[54:57], v[226:229], v[184:187], v[54:57]
	v_mfma_f32_16x16x32_bf16 v[46:49], v[234:237], v[184:187], v[46:49]
	v_mfma_f32_16x16x32_bf16 v[38:41], v[226:229], v[196:199], v[38:41]
	v_mfma_f32_16x16x32_bf16 v[30:33], v[234:237], v[196:199], v[30:33]
	v_mfma_f32_16x16x32_bf16 v[22:25], v[226:229], v[204:207], v[22:25]
	v_mfma_f32_16x16x32_bf16 v[14:17], v[234:237], v[204:207], v[14:17]
	v_mfma_f32_16x16x32_bf16 v[6:9], v[226:229], v[212:215], v[6:9]
	v_mfma_f32_16x16x32_bf16 v[2:5], v[234:237], v[212:215], v[2:5]
	v_mfma_f32_16x16x32_bf16 v[54:57], v[230:233], v[188:191], v[54:57]
	v_mfma_f32_16x16x32_bf16 v[46:49], v[238:241], v[188:191], v[46:49]
	v_mfma_f32_16x16x32_bf16 v[38:41], v[230:233], v[200:203], v[38:41]
	v_mfma_f32_16x16x32_bf16 v[30:33], v[238:241], v[200:203], v[30:33]
	v_mfma_f32_16x16x32_bf16 v[22:25], v[230:233], v[208:211], v[22:25]
	v_mfma_f32_16x16x32_bf16 v[14:17], v[238:241], v[208:211], v[14:17]
	v_mfma_f32_16x16x32_bf16 v[6:9], v[230:233], v[222:225], v[6:9]
	v_mfma_f32_16x16x32_bf16 v[2:5], v[238:241], v[222:225], v[2:5]
	s_setprio 0
	s_add_u32 s92, s92, 0x100
	s_addc_u32 s93, s93, 0
	s_add_u32 s34, s34, 0x100
	s_addc_u32 s35, s35, 0
	s_cmp_ge_u32 s14, s73
	s_mov_b32 s66, s14
	s_barrier
	s_cbranch_scc0 .LBB0_400
	v_and_b32_e32 v144, 64, v220
	v_or_b32_e32 v144, v144, v150
	v_lshlrev_b32_e32 v172, 2, v144
	ds_bpermute_b32 v145, v172, v143
	ds_bpermute_b32 v144, v172, v143 offset:64
	s_mov_b32 s8, 0x3a000000
	v_mov_b32_e32 v232, 0x358637bd
	s_mov_b32 s97, 0x800000
	ds_bpermute_b32 v147, v172, v143 offset:128
	s_waitcnt lgkmcnt(0)
	v_pk_fma_f32 v[148:149], v[144:145], s[8:9], v[232:233] op_sel_hi:[1,0,0]
	ds_bpermute_b32 v146, v172, v143 offset:192
	v_mul_f32_e32 v143, 0x4b800000, v149
	v_cmp_gt_f32_e32 vcc, s97, v149
	v_max_f32_e32 v174, v128, v128
	v_max_f32_e32 v175, v124, v124
	v_cndmask_b32_e32 v143, v149, v143, vcc
	v_rsq_f32_e32 v149, v143
	v_max_f32_e32 v176, v116, v116
	ds_bpermute_b32 v145, v172, v142
	ds_bpermute_b32 v144, v172, v142 offset:64
	v_mul_f32_e32 v173, 0x45800000, v149
	v_cndmask_b32_e32 v149, v149, v173, vcc
	v_max_f32_e32 v173, v129, v129
	v_max_f32_e32 v173, v174, v173
	v_max_f32_e32 v174, v125, v125
	v_max_f32_e32 v174, v175, v174
	v_max3_f32 v173, v126, v127, v173
	v_max3_f32 v174, v122, v123, v174
	v_max3_f32 v173, v173, s72, v174
	v_max_f32_e32 v174, v121, v121
	v_max_f32_e32 v175, v120, v120
	v_max_f32_e32 v174, v175, v174
	v_max_f32_e32 v175, v117, v117
	v_max_f32_e32 v175, v176, v175
	v_cmp_lt_i32_e32 vcc, v221, v247
	v_max3_f32 v174, v118, v119, v174
	v_max3_f32 v175, v114, v115, v175
	v_cndmask_b32_e64 v177, v149, 1.0, s[80:81]
	v_cndmask_b32_e32 v149, v220, v221, vcc
	v_max3_f32 v173, v173, v174, v175
	v_lshlrev_b32_e32 v149, 2, v149
	v_mul_f32_e32 v173, v173, v177
	ds_bpermute_b32 v174, v149, v173
	v_cmp_lt_i32_e32 vcc, v248, v247
	ds_bpermute_b32 v143, v172, v142 offset:128
	ds_bpermute_b32 v142, v172, v142 offset:192
	v_cndmask_b32_e32 v172, v220, v248, vcc
	s_waitcnt lgkmcnt(0)
	v_max_f32_e32 v174, v174, v174
	v_lshlrev_b32_e32 v172, 2, v172
	v_max_f32_e32 v173, v173, v174
	ds_bpermute_b32 v174, v172, v173
	v_cmp_gt_f32_e32 vcc, s97, v148
	v_add_u32_e32 v178, s51, v154
	s_and_saveexec_b64 s[92:93], s[0:1]
	s_cbranch_execz .LBB0_403
	s_waitcnt lgkmcnt(0)
	v_max_f32_e32 v174, v174, v174
	v_max_f32_e32 v173, v173, v173
	v_max_f32_e32 v173, v173, v174
	ds_write_b32 v178, v173

; #define PG8_STAGE(bufoff, gbase, voff) do { _Pragma("unroll") for (int _i = 0; _i < 2; ++_i) \
;         __builtin_amdgcn_global_load_lds((const unsigned*)((const char*)(gbase) + (voff)[_i]), (LAS unsigned*)(lds + (bufoff) + ldsw + _i * 8192), 16, 0, 0); } while (0)
; #define PG8_LDA(dst, b, h) do { _Pragma("unroll") for (int m = 0; m < 4; ++m) _Pragma("unroll") for (int k = 0; k < 2; ++k) dst[m][k] = *(const LAS bf16x8*)(lds + PG8_SA(b, h) + aoff + m * 2048 + k * 1024); } while (0)
; #define PG8_LDB(dst, b, h) do { _Pragma("unroll") for (int n = 0; n < 2; ++n) _Pragma("unroll") for (int k = 0; k < 2; ++k) dst[n][k] = *(const LAS bf16x8*)(lds + PG8_SB(b, h) + boff + n * 2048 + k * 1024); } while (0)
; #define PG8_MMA(ai, bj, At, Bt) do { __builtin_amdgcn_s_setprio(1); _Pragma("unroll") for (int m = 0; m < 4; ++m) _Pragma("unroll") for (int n = 0; n < 2; ++n) _Pragma("unroll") for (int k = 0; k < 2; ++k) \
;         acc[ai][bj][m][n] = __builtin_amdgcn_mfma_f32_16x16x32_bf16(Bt[n][k], At[m][k], acc[ai][bj][m][n], 0, 0, 0); __builtin_amdgcn_s_setprio(0); } while (0)
; #define PG8_WAIT_L(n) asm volatile("s_waitcnt lgkmcnt(" #n ")" ::: "memory")
; #define PG8_BAR __builtin_amdgcn_s_barrier()
; #define PG8_SCHED __builtin_amdgcn_sched_barrier(0)
; template <class Epi>
; __device__ __forceinline__ void gemm_phase(LAS unsigned char* lds, const Gemm g, const Sched& S, const Epi& E) {
;     ...
;         for (int t = 0; t < nt; t += 2) {
;             const bool last = (t == nt - 2);
;             const char* a1 = cA + (size_t)(t + 1) * kstep;
;             const char* a2 = last ? nA : cA + (size_t)(t + 2) * kstep; const char* b2 = last ? nB : cB + (size_t)(t + 2) * kstep;
;             const char* a3 = a2 + kstep; const char* b3 = b2 + kstep;
;             PG8_LDB(B0, 0, 0); PG8_SCHED; PG8_LDA(At, 0, 0); PG8_STAGE(PG8_SA(1, 1), a1 + hstepA, voffA);
;             PG8_WAIT_L(8); PG8_BAR; PG8_WAIT_L(0); PG8_MMA(0, 0, At, B0); PG8_BAR; PG8_SCHED;
;             PG8_LDB(B1, 0, 1); PG8_STAGE(PG8_SB(0, 0), b2, voffB);
;             PG8_BAR; PG8_WAIT_L(0); PG8_MMA(0, 1, At, B1); PG8_BAR;
;             PG8_LDA(At, 0, 1); PG8_STAGE(PG8_SA(0, 0), a2, voffA);
;             PG8_BAR; PG8_WAIT_L(0); PG8_MMA(1, 0, At, B0); PG8_BAR; PG8_SCHED;
.LBB0_461:
	s_add_i32 s14, s88, 2
	s_add_u32 s8, s4, 0x80
	s_addc_u32 s9, s5, 0
	s_add_i32 s15, 0, 0x10000
	v_add_u32_e32 v114, s15, v211
	ds_read_b128 v[82:85], v114
	ds_read_b128 v[94:97], v114 offset:1024
	ds_read_b128 v[98:101], v114 offset:2048
	ds_read_b128 v[114:117], v114 offset:3072
	s_cmp_eq_u32 s42, s88
	s_cselect_b32 s88, s57, s8
	s_cselect_b32 s89, s71, s9
	s_cselect_b32 s91, s59, s35
	s_cselect_b32 s90, s72, s34
	v_lshl_add_u64 v[178:179], s[4:5], 0, v[202:203]
	s_add_i32 m0, s24, 0xc000
	ds_read_b128 v[122:125], v213
	ds_read_b128 v[130:133], v213 offset:1024
	ds_read_b128 v[146:149], v213 offset:2048
	ds_read_b128 v[150:153], v213 offset:3072
	ds_read_b128 v[162:165], v213 offset:4096
	ds_read_b128 v[166:169], v213 offset:5120
	ds_read_b128 v[170:173], v213 offset:6144
	ds_read_b128 v[174:177], v213 offset:7168
	global_load_lds_dwordx4 v[178:179], off
	v_lshl_add_u64 v[178:179], s[4:5], 0, v[204:205]
	s_add_i32 m0, s24, 0xe000
	s_nop 0
	global_load_lds_dwordx4 v[178:179], off
	s_add_i32 s8, 0, 0x14000
	v_add_u32_e32 v190, s8, v211
	ds_read_b128 v[178:181], v190
	ds_read_b128 v[182:185], v190 offset:1024
	ds_read_b128 v[186:189], v190 offset:2048
	ds_read_b128 v[190:193], v190 offset:3072
	s_waitcnt vmcnt(8)
	s_waitcnt lgkmcnt(0)
	v_mfma_f32_16x16x32_bf16 v[158:161], v[82:85], v[122:125], v[158:161]
	v_mfma_f32_16x16x32_bf16 v[154:157], v[98:101], v[122:125], v[154:157]
	v_mfma_f32_16x16x32_bf16 v[134:137], v[82:85], v[146:149], v[134:137]
	v_mfma_f32_16x16x32_bf16 v[126:129], v[98:101], v[146:149], v[126:129]
	s_barrier
	s_setprio 1
	v_mfma_f32_16x16x32_bf16 v[106:109], v[82:85], v[162:165], v[106:109]
	v_mfma_f32_16x16x32_bf16 v[102:105], v[98:101], v[162:165], v[102:105]
	v_mfma_f32_16x16x32_bf16 v[78:81], v[82:85], v[170:173], v[78:81]
	v_mfma_f32_16x16x32_bf16 v[74:77], v[98:101], v[170:173], v[74:77]
	v_mfma_f32_16x16x32_bf16 v[158:161], v[94:97], v[130:133], v[158:161]
	v_mfma_f32_16x16x32_bf16 v[154:157], v[114:117], v[130:133], v[154:157]
	v_mfma_f32_16x16x32_bf16 v[134:137], v[94:97], v[150:153], v[134:137]
	v_mfma_f32_16x16x32_bf16 v[126:129], v[114:117], v[150:153], v[126:129]
	v_mfma_f32_16x16x32_bf16 v[106:109], v[94:97], v[166:169], v[106:109]
	v_mfma_f32_16x16x32_bf16 v[102:105], v[114:117], v[166:169], v[102:105]
	v_mfma_f32_16x16x32_bf16 v[78:81], v[94:97], v[174:177], v[78:81]
	v_mfma_f32_16x16x32_bf16 v[74:77], v[114:117], v[174:177], v[74:77]
	v_mfma_f32_16x16x32_bf16 v[142:145], v[178:181], v[122:125], v[142:145]
	v_mfma_f32_16x16x32_bf16 v[118:121], v[178:181], v[146:149], v[118:121]
	v_mfma_f32_16x16x32_bf16 v[110:113], v[186:189], v[146:149], v[110:113]
	v_mfma_f32_16x16x32_bf16 v[90:93], v[178:181], v[162:165], v[90:93]
	v_mfma_f32_16x16x32_bf16 v[86:89], v[186:189], v[162:165], v[86:89]
	v_mfma_f32_16x16x32_bf16 v[70:73], v[178:181], v[170:173], v[70:73]
	v_mfma_f32_16x16x32_bf16 v[66:69], v[186:189], v[170:173], v[66:69]
	v_mfma_f32_16x16x32_bf16 v[142:145], v[182:185], v[130:133], v[142:145]
	v_mfma_f32_16x16x32_bf16 v[122:125], v[186:189], v[122:125], v[138:141]
	v_mfma_f32_16x16x32_bf16 v[118:121], v[182:185], v[150:153], v[118:121]
	v_mfma_f32_16x16x32_bf16 v[110:113], v[190:193], v[150:153], v[110:113]
	v_mfma_f32_16x16x32_bf16 v[90:93], v[182:185], v[166:169], v[90:93]
	v_mfma_f32_16x16x32_bf16 v[86:89], v[190:193], v[166:169], v[86:89]
	v_mfma_f32_16x16x32_bf16 v[70:73], v[182:185], v[174:177], v[70:73]
	v_mfma_f32_16x16x32_bf16 v[66:69], v[190:193], v[174:177], v[66:69]
	v_mfma_f32_16x16x32_bf16 v[122:125], v[190:193], v[130:133], v[122:125]
	s_setprio 0
	s_barrier
	s_add_i32 s9, s15, s3
	v_lshl_add_u64 v[194:195], s[90:91], 0, v[0:1]
	s_mov_b32 m0, s9
	s_nop 0
	global_load_lds_dwordx4 v[194:195], off
	v_lshl_add_u64 v[206:207], s[90:91], 0, v[200:201]
	s_add_i32 m0, s9, 0x2000
	s_nop 0
	global_load_lds_dwordx4 v[206:207], off
	s_mov_b32 m0, s24
	v_lshl_add_u64 v[208:209], s[88:89], 0, v[196:197]
	ds_read_b128 v[130:133], v213 offset:16384
	ds_read_b128 v[138:141], v213 offset:17408
	ds_read_b128 v[146:149], v213 offset:18432
	ds_read_b128 v[150:153], v213 offset:19456
	ds_read_b128 v[162:165], v213 offset:20480
	ds_read_b128 v[166:169], v213 offset:21504
	ds_read_b128 v[170:173], v213 offset:22528
	ds_read_b128 v[174:177], v213 offset:23552
	global_load_lds_dwordx4 v[208:209], off
	v_lshl_add_u64 v[214:215], s[88:89], 0, v[198:199]
	s_mov_b32 m0, s33
	s_nop 0
	global_load_lds_dwordx4 v[214:215], off
	s_add_u32 s90, s90, s78
	s_addc_u32 s91, s91, s79
	s_add_i32 s8, s8, s3
	v_lshl_add_u64 v[216:217], s[90:91], 0, v[0:1]
	s_mov_b32 m0, s8
	v_lshl_add_u64 v[222:223], s[90:91], 0, v[200:201]
	global_load_lds_dwordx4 v[216:217], off
	s_add_i32 m0, s8, 0x2000
	s_nop 0
	global_load_lds_dwordx4 v[222:223], off
	s_waitcnt vmcnt(8)
	s_waitcnt lgkmcnt(0)
	v_mfma_f32_16x16x32_bf16 v[62:65], v[82:85], v[130:133], v[62:65]
	v_mfma_f32_16x16x32_bf16 v[58:61], v[98:101], v[130:133], v[58:61]
	v_mfma_f32_16x16x32_bf16 v[46:49], v[82:85], v[146:149], v[46:49]
	v_mfma_f32_16x16x32_bf16 v[42:45], v[98:101], v[146:149], v[42:45]
	s_barrier
; #define PG8_STAGE(bufoff, gbase, voff) do { _Pragma("unroll") for (int _i = 0; _i < 2; ++_i) \
;         __builtin_amdgcn_global_load_lds((const unsigned*)((const char*)(gbase) + (voff)[_i]), (LAS unsigned*)(lds + (bufoff) + ldsw + _i * 8192), 16, 0, 0); } while (0)
; #define PG8_LDA(dst, b, h) do { _Pragma("unroll") for (int m = 0; m < 4; ++m) _Pragma("unroll") for (int k = 0; k < 2; ++k) dst[m][k] = *(const LAS bf16x8*)(lds + PG8_SA(b, h) + aoff + m * 2048 + k * 1024); } while (0)
; #define PG8_LDB(dst, b, h) do { _Pragma("unroll") for (int n = 0; n < 2; ++n) _Pragma("unroll") for (int k = 0; k < 2; ++k) dst[n][k] = *(const LAS bf16x8*)(lds + PG8_SB(b, h) + boff + n * 2048 + k * 1024); } while (0)
; #define PG8_MMA(ai, bj, At, Bt) do { __builtin_amdgcn_s_setprio(1); _Pragma("unroll") for (int m = 0; m < 4; ++m) _Pragma("unroll") for (int n = 0; n < 2; ++n) _Pragma("unroll") for (int k = 0; k < 2; ++k) \
;         acc[ai][bj][m][n] = __builtin_amdgcn_mfma_f32_16x16x32_bf16(Bt[n][k], At[m][k], acc[ai][bj][m][n], 0, 0, 0); __builtin_amdgcn_s_setprio(0); } while (0)
; #define PG8_WAIT_V(n) asm volatile("s_waitcnt vmcnt(" #n ")" ::: "memory")
; #define PG8_WAIT_L(n) asm volatile("s_waitcnt lgkmcnt(" #n ")" ::: "memory")
; #define PG8_BAR __builtin_amdgcn_s_barrier()
; #define PG8_SCHED __builtin_amdgcn_sched_barrier(0)
; template <class Epi>
; __device__ __forceinline__ void gemm_phase(LAS unsigned char* lds, const Gemm g, const Sched& S, const Epi& E) {
;     ...
;             PG8_BAR; PG8_WAIT_L(0); PG8_MMA(1, 0, At, B0); PG8_BAR; PG8_SCHED;
;             PG8_STAGE(PG8_SB(0, 1), b2 + hstepB, voffB);
;             PG8_WAIT_V(6); PG8_BAR; PG8_MMA(1, 1, At, B1); PG8_BAR;
;             PG8_LDB(B0, 1, 0); PG8_SCHED; PG8_LDA(At, 1, 0); PG8_STAGE(PG8_SA(0, 1), a2 + hstepA, voffA);
;             PG8_WAIT_L(8); PG8_BAR; PG8_WAIT_L(0); PG8_MMA(0, 0, At, B0); PG8_BAR; PG8_SCHED;
;             PG8_LDB(B1, 1, 1); PG8_STAGE(PG8_SB(1, 0), b3, voffB);
;             PG8_BAR; PG8_WAIT_L(0); PG8_MMA(0, 1, At, B1); PG8_BAR;
;             PG8_LDA(At, 1, 1); PG8_STAGE(PG8_SA(1, 0), a3, voffA);
;             PG8_BAR; PG8_WAIT_L(0); PG8_MMA(1, 0, At, B0); PG8_BAR; PG8_SCHED;
	s_setprio 1
	v_mfma_f32_16x16x32_bf16 v[30:33], v[82:85], v[162:165], v[30:33]
	v_mfma_f32_16x16x32_bf16 v[26:29], v[98:101], v[162:165], v[26:29]
	v_mfma_f32_16x16x32_bf16 v[14:17], v[82:85], v[170:173], v[14:17]
	v_mfma_f32_16x16x32_bf16 v[10:13], v[98:101], v[170:173], v[10:13]
	v_mfma_f32_16x16x32_bf16 v[62:65], v[94:97], v[138:141], v[62:65]
	v_mfma_f32_16x16x32_bf16 v[58:61], v[114:117], v[138:141], v[58:61]
	v_mfma_f32_16x16x32_bf16 v[46:49], v[94:97], v[150:153], v[46:49]
	v_mfma_f32_16x16x32_bf16 v[42:45], v[114:117], v[150:153], v[42:45]
	v_mfma_f32_16x16x32_bf16 v[30:33], v[94:97], v[166:169], v[30:33]
	v_mfma_f32_16x16x32_bf16 v[26:29], v[114:117], v[166:169], v[26:29]
	v_mfma_f32_16x16x32_bf16 v[14:17], v[94:97], v[174:177], v[14:17]
	v_mfma_f32_16x16x32_bf16 v[10:13], v[114:117], v[174:177], v[10:13]
	v_mfma_f32_16x16x32_bf16 v[54:57], v[178:181], v[130:133], v[54:57]
	v_mfma_f32_16x16x32_bf16 v[50:53], v[186:189], v[130:133], v[50:53]
	v_mfma_f32_16x16x32_bf16 v[38:41], v[178:181], v[146:149], v[38:41]
	v_mfma_f32_16x16x32_bf16 v[34:37], v[186:189], v[146:149], v[34:37]
	v_mfma_f32_16x16x32_bf16 v[22:25], v[178:181], v[162:165], v[22:25]
	v_mfma_f32_16x16x32_bf16 v[18:21], v[186:189], v[162:165], v[18:21]
	v_mfma_f32_16x16x32_bf16 v[6:9], v[178:181], v[170:173], v[6:9]
	v_mfma_f32_16x16x32_bf16 v[2:5], v[186:189], v[170:173], v[2:5]
	v_mfma_f32_16x16x32_bf16 v[54:57], v[182:185], v[138:141], v[54:57]
	v_mfma_f32_16x16x32_bf16 v[50:53], v[190:193], v[138:141], v[50:53]
	v_mfma_f32_16x16x32_bf16 v[38:41], v[182:185], v[150:153], v[38:41]
	v_mfma_f32_16x16x32_bf16 v[34:37], v[190:193], v[150:153], v[34:37]
	v_mfma_f32_16x16x32_bf16 v[22:25], v[182:185], v[166:169], v[22:25]
	v_mfma_f32_16x16x32_bf16 v[18:21], v[190:193], v[166:169], v[18:21]
	v_mfma_f32_16x16x32_bf16 v[6:9], v[182:185], v[174:177], v[6:9]
	v_mfma_f32_16x16x32_bf16 v[2:5], v[190:193], v[174:177], v[2:5]
	s_setprio 0
	s_barrier
	s_add_i32 s8, 0, 0x18000
	v_add_u32_e32 v114, s8, v211
	ds_read_b128 v[82:85], v114
	ds_read_b128 v[94:97], v114 offset:1024
	ds_read_b128 v[98:101], v114 offset:2048
	ds_read_b128 v[114:117], v114 offset:3072
	s_add_u32 s88, s88, s36
	s_addc_u32 s89, s89, s37
	s_mov_b32 m0, s38
	v_lshl_add_u64 v[178:179], s[88:89], 0, v[196:197]
	ds_read_b128 v[130:133], v213 offset:32768
	ds_read_b128 v[138:141], v213 offset:33792
	ds_read_b128 v[146:149], v213 offset:34816
	ds_read_b128 v[150:153], v213 offset:35840
	ds_read_b128 v[162:165], v213 offset:36864
	ds_read_b128 v[166:169], v213 offset:37888
	ds_read_b128 v[170:173], v213 offset:38912
	ds_read_b128 v[174:177], v213 offset:39936
	global_load_lds_dwordx4 v[178:179], off
	v_lshl_add_u64 v[178:179], s[88:89], 0, v[198:199]
	s_mov_b32 m0, s39
	s_nop 0
	global_load_lds_dwordx4 v[178:179], off
	s_add_i32 s9, 0, 0x1c000
	v_add_u32_e32 v190, s9, v211
	ds_read_b128 v[178:181], v190
	ds_read_b128 v[182:185], v190 offset:1024
	ds_read_b128 v[186:189], v190 offset:2048
	ds_read_b128 v[190:193], v190 offset:3072
	s_waitcnt vmcnt(8)
	s_waitcnt lgkmcnt(0)
	v_mfma_f32_16x16x32_bf16 v[158:161], v[82:85], v[130:133], v[158:161]
	v_mfma_f32_16x16x32_bf16 v[154:157], v[98:101], v[130:133], v[154:157]
	v_mfma_f32_16x16x32_bf16 v[134:137], v[82:85], v[146:149], v[134:137]
	v_mfma_f32_16x16x32_bf16 v[126:129], v[98:101], v[146:149], v[126:129]
	s_barrier
	s_setprio 1
	v_mfma_f32_16x16x32_bf16 v[106:109], v[82:85], v[162:165], v[106:109]
	v_mfma_f32_16x16x32_bf16 v[102:105], v[98:101], v[162:165], v[102:105]
	v_mfma_f32_16x16x32_bf16 v[78:81], v[82:85], v[170:173], v[78:81]
	v_mfma_f32_16x16x32_bf16 v[74:77], v[98:101], v[170:173], v[74:77]
	v_mfma_f32_16x16x32_bf16 v[158:161], v[94:97], v[138:141], v[158:161]
	v_mfma_f32_16x16x32_bf16 v[154:157], v[114:117], v[138:141], v[154:157]
	v_mfma_f32_16x16x32_bf16 v[134:137], v[94:97], v[150:153], v[134:137]
	v_mfma_f32_16x16x32_bf16 v[126:129], v[114:117], v[150:153], v[126:129]
	v_mfma_f32_16x16x32_bf16 v[106:109], v[94:97], v[166:169], v[106:109]
	v_mfma_f32_16x16x32_bf16 v[102:105], v[114:117], v[166:169], v[102:105]
	v_mfma_f32_16x16x32_bf16 v[78:81], v[94:97], v[174:177], v[78:81]
	v_mfma_f32_16x16x32_bf16 v[74:77], v[114:117], v[174:177], v[74:77]
	v_mfma_f32_16x16x32_bf16 v[142:145], v[178:181], v[130:133], v[142:145]
	v_mfma_f32_16x16x32_bf16 v[122:125], v[186:189], v[130:133], v[122:125]
	v_mfma_f32_16x16x32_bf16 v[118:121], v[178:181], v[146:149], v[118:121]
	v_mfma_f32_16x16x32_bf16 v[110:113], v[186:189], v[146:149], v[110:113]
	v_mfma_f32_16x16x32_bf16 v[90:93], v[178:181], v[162:165], v[90:93]
	v_mfma_f32_16x16x32_bf16 v[86:89], v[186:189], v[162:165], v[86:89]
	v_mfma_f32_16x16x32_bf16 v[70:73], v[178:181], v[170:173], v[70:73]
	v_mfma_f32_16x16x32_bf16 v[66:69], v[186:189], v[170:173], v[66:69]
	v_mfma_f32_16x16x32_bf16 v[142:145], v[182:185], v[138:141], v[142:145]
	v_mfma_f32_16x16x32_bf16 v[138:141], v[190:193], v[138:141], v[122:125]
	v_mfma_f32_16x16x32_bf16 v[118:121], v[182:185], v[150:153], v[118:121]
	v_mfma_f32_16x16x32_bf16 v[110:113], v[190:193], v[150:153], v[110:113]
	v_mfma_f32_16x16x32_bf16 v[90:93], v[182:185], v[166:169], v[90:93]
	v_mfma_f32_16x16x32_bf16 v[86:89], v[190:193], v[166:169], v[86:89]
	v_mfma_f32_16x16x32_bf16 v[70:73], v[182:185], v[174:177], v[70:73]
	v_mfma_f32_16x16x32_bf16 v[66:69], v[190:193], v[174:177], v[66:69]
	s_setprio 0
	s_barrier
; #define PG8_STAGE(bufoff, gbase, voff) do { _Pragma("unroll") for (int _i = 0; _i < 2; ++_i) \
;         __builtin_amdgcn_global_load_lds((const unsigned*)((const char*)(gbase) + (voff)[_i]), (LAS unsigned*)(lds + (bufoff) + ldsw + _i * 8192), 16, 0, 0); } while (0)
; #define PG8_LDA(dst, b, h) do { _Pragma("unroll") for (int m = 0; m < 4; ++m) _Pragma("unroll") for (int k = 0; k < 2; ++k) dst[m][k] = *(const LAS bf16x8*)(lds + PG8_SA(b, h) + aoff + m * 2048 + k * 1024); } while (0)
; #define PG8_LDB(dst, b, h) do { _Pragma("unroll") for (int n = 0; n < 2; ++n) _Pragma("unroll") for (int k = 0; k < 2; ++k) dst[n][k] = *(const LAS bf16x8*)(lds + PG8_SB(b, h) + boff + n * 2048 + k * 1024); } while (0)
; #define PG8_MMA(ai, bj, At, Bt) do { __builtin_amdgcn_s_setprio(1); _Pragma("unroll") for (int m = 0; m < 4; ++m) _Pragma("unroll") for (int n = 0; n < 2; ++n) _Pragma("unroll") for (int k = 0; k < 2; ++k) \
;         acc[ai][bj][m][n] = __builtin_amdgcn_mfma_f32_16x16x32_bf16(Bt[n][k], At[m][k], acc[ai][bj][m][n], 0, 0, 0); __builtin_amdgcn_s_setprio(0); } while (0)
; #define PG8_WAIT_V(n) asm volatile("s_waitcnt vmcnt(" #n ")" ::: "memory")
; template <class Epi>
; __device__ __forceinline__ void gemm_phase(LAS unsigned char* lds, const Gemm g, const Sched& S, const Epi& E) {
;     ...
;             PG8_LDB(B1, 1, 1); PG8_STAGE(PG8_SB(1, 0), b3, voffB);
;             PG8_BAR; PG8_WAIT_L(0); PG8_MMA(0, 1, At, B1); PG8_BAR;
;             PG8_LDA(At, 1, 1); PG8_STAGE(PG8_SA(1, 0), a3, voffA);
;             PG8_BAR; PG8_WAIT_L(0); PG8_MMA(1, 0, At, B0); PG8_BAR; PG8_SCHED;
;             PG8_STAGE(PG8_SB(1, 1), b3 + hstepB, voffB);
;             PG8_WAIT_V(6); PG8_BAR; PG8_MMA(1, 1, At, B1); PG8_BAR;
;         }
;     __device__ __forceinline__ void operator()(const Acc& acc, const Unit& u, int wr, int wc, int fr, int fq, const Pre& pre) const {
;         const int row0 = u.pm * 256 + wr * 64 + fr, col0 = u.pn * 256 + wc * 32 + 8 * fq;
; #pragma unroll
;         for (int ai = 0; ai < 2; ++ai) {
;             u32x4 gw[4][2], pw[4][2];
; #pragma unroll
;             for (int m = 0; m < 4; ++m)
; #pragma unroll
;                 for (int bj = 0; bj < 2; ++bj) { const size_t off = (size_t)(row0 + ai * 128 + m * 16) * ldc + col0 + bj * 128;
;                     gw[m][bj] = *(const u32x4*)(gate + off); if (add) pw[m][bj] = *(const u32x4*)(O + off); }
	s_add_i32 s8, s8, s3
	v_lshl_add_u64 v[194:195], v[194:195], 0, s[60:61]
	s_mov_b32 m0, s8
	s_nop 0
	global_load_lds_dwordx4 v[194:195], off
	v_lshl_add_u64 v[194:195], v[206:207], 0, s[60:61]
	s_add_i32 m0, s8, 0x2000
	s_nop 0
	global_load_lds_dwordx4 v[194:195], off
	s_mov_b32 m0, s40
	v_lshl_add_u64 v[194:195], v[208:209], 0, s[60:61]
	ds_read_b128 v[122:125], v213 offset:49152
	ds_read_b128 v[130:133], v213 offset:50176
	ds_read_b128 v[146:149], v213 offset:51200
	ds_read_b128 v[150:153], v213 offset:52224
	ds_read_b128 v[162:165], v213 offset:53248
	ds_read_b128 v[166:169], v213 offset:54272
	ds_read_b128 v[170:173], v213 offset:55296
	ds_read_b128 v[174:177], v213 offset:56320
	global_load_lds_dwordx4 v[194:195], off
	v_lshl_add_u64 v[194:195], v[214:215], 0, s[60:61]
	s_mov_b32 m0, s41
	s_nop 0
	global_load_lds_dwordx4 v[194:195], off
	s_add_i32 s8, s9, s3
	v_lshl_add_u64 v[194:195], v[216:217], 0, s[60:61]
	s_mov_b32 m0, s8
	s_nop 0
	global_load_lds_dwordx4 v[194:195], off
	v_lshl_add_u64 v[194:195], v[222:223], 0, s[60:61]
	s_add_i32 m0, s8, 0x2000
	s_nop 0
	global_load_lds_dwordx4 v[194:195], off
	s_waitcnt vmcnt(8)
	s_waitcnt lgkmcnt(0)
	v_mfma_f32_16x16x32_bf16 v[62:65], v[82:85], v[122:125], v[62:65]
	v_mfma_f32_16x16x32_bf16 v[58:61], v[98:101], v[122:125], v[58:61]
	v_mfma_f32_16x16x32_bf16 v[46:49], v[82:85], v[146:149], v[46:49]
	v_mfma_f32_16x16x32_bf16 v[42:45], v[98:101], v[146:149], v[42:45]
	s_barrier
	s_setprio 1
	v_mfma_f32_16x16x32_bf16 v[30:33], v[82:85], v[162:165], v[30:33]
	v_mfma_f32_16x16x32_bf16 v[26:29], v[98:101], v[162:165], v[26:29]
	v_mfma_f32_16x16x32_bf16 v[14:17], v[82:85], v[170:173], v[14:17]
	v_mfma_f32_16x16x32_bf16 v[10:13], v[98:101], v[170:173], v[10:13]
	v_mfma_f32_16x16x32_bf16 v[62:65], v[94:97], v[130:133], v[62:65]
	v_mfma_f32_16x16x32_bf16 v[58:61], v[114:117], v[130:133], v[58:61]
	v_mfma_f32_16x16x32_bf16 v[46:49], v[94:97], v[150:153], v[46:49]
	v_mfma_f32_16x16x32_bf16 v[42:45], v[114:117], v[150:153], v[42:45]
	v_mfma_f32_16x16x32_bf16 v[30:33], v[94:97], v[166:169], v[30:33]
	v_mfma_f32_16x16x32_bf16 v[26:29], v[114:117], v[166:169], v[26:29]
	v_mfma_f32_16x16x32_bf16 v[14:17], v[94:97], v[174:177], v[14:17]
	v_mfma_f32_16x16x32_bf16 v[10:13], v[114:117], v[174:177], v[10:13]
	v_mfma_f32_16x16x32_bf16 v[54:57], v[178:181], v[122:125], v[54:57]
	v_mfma_f32_16x16x32_bf16 v[50:53], v[186:189], v[122:125], v[50:53]
	v_mfma_f32_16x16x32_bf16 v[38:41], v[178:181], v[146:149], v[38:41]
	v_mfma_f32_16x16x32_bf16 v[34:37], v[186:189], v[146:149], v[34:37]
	v_mfma_f32_16x16x32_bf16 v[22:25], v[178:181], v[162:165], v[22:25]
	v_mfma_f32_16x16x32_bf16 v[18:21], v[186:189], v[162:165], v[18:21]
	v_mfma_f32_16x16x32_bf16 v[6:9], v[178:181], v[170:173], v[6:9]
	v_mfma_f32_16x16x32_bf16 v[2:5], v[186:189], v[170:173], v[2:5]
	v_mfma_f32_16x16x32_bf16 v[54:57], v[182:185], v[130:133], v[54:57]
	v_mfma_f32_16x16x32_bf16 v[50:53], v[190:193], v[130:133], v[50:53]
	v_mfma_f32_16x16x32_bf16 v[38:41], v[182:185], v[150:153], v[38:41]
	v_mfma_f32_16x16x32_bf16 v[34:37], v[190:193], v[150:153], v[34:37]
	v_mfma_f32_16x16x32_bf16 v[22:25], v[182:185], v[166:169], v[22:25]
	v_mfma_f32_16x16x32_bf16 v[18:21], v[190:193], v[166:169], v[18:21]
	v_mfma_f32_16x16x32_bf16 v[6:9], v[182:185], v[174:177], v[6:9]
	v_mfma_f32_16x16x32_bf16 v[2:5], v[190:193], v[174:177], v[2:5]
	s_setprio 0
	s_add_u32 s4, s4, 0x100
	s_addc_u32 s5, s5, 0
	s_add_u32 s34, s34, 0x100
	s_addc_u32 s35, s35, 0
	s_cmp_ge_u32 s14, s73
	s_mov_b32 s88, s14
	s_barrier
	s_cbranch_scc0 .LBB0_461
	v_lshl_add_u32 v214, s67, 8, v210
	v_lshl_or_b32 v206, s55, 8, v212
	v_ashrrev_i32_e32 v207, 31, v206
	v_ashrrev_i32_e32 v82, 31, v214
	v_mul_lo_u32 v215, s12, v82
	v_mul_lo_u32 v238, s13, v214
	v_mad_u64_u32 v[82:83], s[4:5], s12, v214, v[206:207]
	v_add3_u32 v83, v238, v83, v215
	v_lshl_add_u64 v[84:85], v[82:83], 1, s[6:7]
	global_load_dwordx4 v[190:193], v[84:85], off
	v_cndmask_b32_e64 v94, 0, 1, s[76:77]
	v_cmp_ne_u32_e64 s[4:5], 1, v94
	s_andn2_b64 vcc, exec, s[76:77]
	v_lshl_add_u64 v[82:83], v[82:83], 1, s[62:63]
	s_cbranch_vccnz .LBB0_464
	global_load_dwordx4 v[150:153], v[82:83], off

; #define PG8_STAGE(bufoff, gbase, voff) do { _Pragma("unroll") for (int _i = 0; _i < 2; ++_i) \
;         __builtin_amdgcn_global_load_lds((const unsigned*)((const char*)(gbase) + (voff)[_i]), (LAS unsigned*)(lds + (bufoff) + ldsw + _i * 8192), 16, 0, 0); } while (0)
; #define PG8_LDA(dst, b, h) do { _Pragma("unroll") for (int m = 0; m < 4; ++m) _Pragma("unroll") for (int k = 0; k < 2; ++k) dst[m][k] = *(const LAS bf16x8*)(lds + PG8_SA(b, h) + aoff + m * 2048 + k * 1024); } while (0)
; #define PG8_LDB(dst, b, h) do { _Pragma("unroll") for (int n = 0; n < 2; ++n) _Pragma("unroll") for (int k = 0; k < 2; ++k) dst[n][k] = *(const LAS bf16x8*)(lds + PG8_SB(b, h) + boff + n * 2048 + k * 1024); } while (0)
; #define PG8_MMA(ai, bj, At, Bt) do { __builtin_amdgcn_s_setprio(1); _Pragma("unroll") for (int m = 0; m < 4; ++m) _Pragma("unroll") for (int n = 0; n < 2; ++n) _Pragma("unroll") for (int k = 0; k < 2; ++k) \
;         acc[ai][bj][m][n] = __builtin_amdgcn_mfma_f32_16x16x32_bf16(Bt[n][k], At[m][k], acc[ai][bj][m][n], 0, 0, 0); __builtin_amdgcn_s_setprio(0); } while (0)
; #define PG8_WAIT_L(n) asm volatile("s_waitcnt lgkmcnt(" #n ")" ::: "memory")
; #define PG8_BAR __builtin_amdgcn_s_barrier()
; #define PG8_SCHED __builtin_amdgcn_sched_barrier(0)
; template <class Epi>
; __device__ __forceinline__ void gemm_phase(LAS unsigned char* lds, const Gemm g, const Sched& S, const Epi& E) {
;     ...
;         for (int t = 0; t < nt; t += 2) {
;             const bool last = (t == nt - 2);
;             const char* a1 = cA + (size_t)(t + 1) * kstep;
;             const char* a2 = last ? nA : cA + (size_t)(t + 2) * kstep; const char* b2 = last ? nB : cB + (size_t)(t + 2) * kstep;
;             const char* a3 = a2 + kstep; const char* b3 = b2 + kstep;
;             PG8_LDB(B0, 0, 0); PG8_SCHED; PG8_LDA(At, 0, 0); PG8_STAGE(PG8_SA(1, 1), a1 + hstepA, voffA);
;             PG8_WAIT_L(8); PG8_BAR; PG8_WAIT_L(0); PG8_MMA(0, 0, At, B0); PG8_BAR; PG8_SCHED;
;             PG8_LDB(B1, 0, 1); PG8_STAGE(PG8_SB(0, 0), b2, voffB);
;             PG8_BAR; PG8_WAIT_L(0); PG8_MMA(0, 1, At, B1); PG8_BAR;
;             PG8_LDA(At, 0, 1); PG8_STAGE(PG8_SA(0, 0), a2, voffA);
;             PG8_BAR; PG8_WAIT_L(0); PG8_MMA(1, 0, At, B0); PG8_BAR; PG8_SCHED;
.LBB0_555:
	s_add_i32 s14, s6, 2
	s_add_u32 s8, s4, 0x80
	s_addc_u32 s7, s5, 0
	s_add_i32 s9, 0, 0x10000
	v_add_u32_e32 v160, s9, v156
	ds_read_b128 v[142:145], v160
	ds_read_b128 v[146:149], v160 offset:1024
	ds_read_b128 v[150:153], v160 offset:2048
	ds_read_b128 v[160:163], v160 offset:3072
	s_cmp_eq_u32 s43, s6
	s_cselect_b32 s6, s57, s8
	s_cselect_b32 s7, s55, s7
	s_cselect_b32 s91, s59, s35
	s_cselect_b32 s90, s95, s34
	v_lshl_add_u64 v[192:193], s[4:5], 0, v[136:137]
	s_add_i32 m0, s33, 0xc000
	ds_read_b128 v[164:167], v159
	ds_read_b128 v[168:171], v159 offset:1024
	ds_read_b128 v[172:175], v159 offset:2048
	ds_read_b128 v[176:179], v159 offset:3072
	ds_read_b128 v[180:183], v159 offset:4096
	ds_read_b128 v[184:187], v159 offset:5120
	ds_read_b128 v[188:191], v159 offset:6144
	ds_read_b128 v[196:199], v159 offset:7168
	global_load_lds_dwordx4 v[192:193], off
	v_lshl_add_u64 v[192:193], s[4:5], 0, v[138:139]
	s_add_i32 m0, s33, 0xe000
	s_nop 0
	global_load_lds_dwordx4 v[192:193], off
	s_add_i32 s8, 0, 0x14000
	v_add_u32_e32 v192, s8, v156
	ds_read_b128 v[200:203], v192
	ds_read_b128 v[204:207], v192 offset:1024
	ds_read_b128 v[208:211], v192 offset:2048
	ds_read_b128 v[212:215], v192 offset:3072
	s_waitcnt vmcnt(8)
	s_waitcnt lgkmcnt(0)
	v_mfma_f32_16x16x32_bf16 v[126:129], v[142:145], v[164:167], v[126:129]
	v_mfma_f32_16x16x32_bf16 v[122:125], v[150:153], v[164:167], v[122:125]
	v_mfma_f32_16x16x32_bf16 v[110:113], v[142:145], v[172:175], v[110:113]
	v_mfma_f32_16x16x32_bf16 v[106:109], v[150:153], v[172:175], v[106:109]
	s_barrier
	s_setprio 1
	v_mfma_f32_16x16x32_bf16 v[94:97], v[142:145], v[180:183], v[94:97]
	v_mfma_f32_16x16x32_bf16 v[90:93], v[150:153], v[180:183], v[90:93]
	v_mfma_f32_16x16x32_bf16 v[78:81], v[142:145], v[188:191], v[78:81]
	v_mfma_f32_16x16x32_bf16 v[74:77], v[150:153], v[188:191], v[74:77]
	v_mfma_f32_16x16x32_bf16 v[126:129], v[146:149], v[168:171], v[126:129]
	v_mfma_f32_16x16x32_bf16 v[122:125], v[160:163], v[168:171], v[122:125]
	v_mfma_f32_16x16x32_bf16 v[110:113], v[146:149], v[176:179], v[110:113]
	v_mfma_f32_16x16x32_bf16 v[106:109], v[160:163], v[176:179], v[106:109]
	v_mfma_f32_16x16x32_bf16 v[94:97], v[146:149], v[184:187], v[94:97]
	v_mfma_f32_16x16x32_bf16 v[90:93], v[160:163], v[184:187], v[90:93]
	v_mfma_f32_16x16x32_bf16 v[78:81], v[146:149], v[196:199], v[78:81]
	v_mfma_f32_16x16x32_bf16 v[74:77], v[160:163], v[196:199], v[74:77]
	v_mfma_f32_16x16x32_bf16 v[118:121], v[200:203], v[164:167], v[118:121]
	v_mfma_f32_16x16x32_bf16 v[114:117], v[208:211], v[164:167], v[114:117]
	v_mfma_f32_16x16x32_bf16 v[102:105], v[200:203], v[172:175], v[102:105]
	v_mfma_f32_16x16x32_bf16 v[98:101], v[208:211], v[172:175], v[98:101]
	v_mfma_f32_16x16x32_bf16 v[86:89], v[200:203], v[180:183], v[86:89]
	v_mfma_f32_16x16x32_bf16 v[82:85], v[208:211], v[180:183], v[82:85]
	v_mfma_f32_16x16x32_bf16 v[70:73], v[200:203], v[188:191], v[70:73]
	v_mfma_f32_16x16x32_bf16 v[66:69], v[208:211], v[188:191], v[66:69]
	v_mfma_f32_16x16x32_bf16 v[118:121], v[204:207], v[168:171], v[118:121]
	v_mfma_f32_16x16x32_bf16 v[114:117], v[212:215], v[168:171], v[114:117]
	v_mfma_f32_16x16x32_bf16 v[102:105], v[204:207], v[176:179], v[102:105]
	v_mfma_f32_16x16x32_bf16 v[98:101], v[212:215], v[176:179], v[98:101]
	v_mfma_f32_16x16x32_bf16 v[86:89], v[204:207], v[184:187], v[86:89]
	v_mfma_f32_16x16x32_bf16 v[82:85], v[212:215], v[184:187], v[82:85]
	v_mfma_f32_16x16x32_bf16 v[70:73], v[204:207], v[196:199], v[70:73]
	v_mfma_f32_16x16x32_bf16 v[66:69], v[212:215], v[196:199], v[66:69]
	s_setprio 0
	s_barrier
	s_add_i32 s9, s9, s3
	v_lshl_add_u64 v[192:193], s[90:91], 0, v[0:1]
	s_mov_b32 m0, s9
	v_lshl_add_u64 v[194:195], s[90:91], 0, v[134:135]
	global_load_lds_dwordx4 v[192:193], off
	s_add_i32 m0, s9, 0x2000
	s_nop 0
	global_load_lds_dwordx4 v[194:195], off
	s_mov_b32 m0, s33
	v_lshl_add_u64 v[216:217], s[6:7], 0, v[130:131]
	ds_read_b128 v[164:167], v159 offset:16384
	ds_read_b128 v[168:171], v159 offset:17408
	ds_read_b128 v[172:175], v159 offset:18432
	ds_read_b128 v[176:179], v159 offset:19456
	ds_read_b128 v[180:183], v159 offset:20480
	ds_read_b128 v[184:187], v159 offset:21504
	ds_read_b128 v[188:191], v159 offset:22528
	ds_read_b128 v[196:199], v159 offset:23552
	global_load_lds_dwordx4 v[216:217], off
	v_lshl_add_u64 v[222:223], s[6:7], 0, v[132:133]
	s_mov_b32 m0, s38
	s_nop 0
	global_load_lds_dwordx4 v[222:223], off
	s_add_u32 s90, s90, s76
	s_addc_u32 s91, s91, s77
	s_add_i32 s8, s8, s3
	v_lshl_add_u64 v[224:225], s[90:91], 0, v[0:1]
	s_mov_b32 m0, s8
	v_lshl_add_u64 v[226:227], s[90:91], 0, v[134:135]
	global_load_lds_dwordx4 v[224:225], off
	s_add_i32 m0, s8, 0x2000
	s_nop 0
	global_load_lds_dwordx4 v[226:227], off
	s_waitcnt vmcnt(8)
	s_waitcnt lgkmcnt(0)
	v_mfma_f32_16x16x32_bf16 v[62:65], v[142:145], v[164:167], v[62:65]
	v_mfma_f32_16x16x32_bf16 v[58:61], v[150:153], v[164:167], v[58:61]
	v_mfma_f32_16x16x32_bf16 v[46:49], v[142:145], v[172:175], v[46:49]
	v_mfma_f32_16x16x32_bf16 v[42:45], v[150:153], v[172:175], v[42:45]
	s_barrier
; #define PG8_STAGE(bufoff, gbase, voff) do { _Pragma("unroll") for (int _i = 0; _i < 2; ++_i) \
;         __builtin_amdgcn_global_load_lds((const unsigned*)((const char*)(gbase) + (voff)[_i]), (LAS unsigned*)(lds + (bufoff) + ldsw + _i * 8192), 16, 0, 0); } while (0)
; #define PG8_LDA(dst, b, h) do { _Pragma("unroll") for (int m = 0; m < 4; ++m) _Pragma("unroll") for (int k = 0; k < 2; ++k) dst[m][k] = *(const LAS bf16x8*)(lds + PG8_SA(b, h) + aoff + m * 2048 + k * 1024); } while (0)
; #define PG8_LDB(dst, b, h) do { _Pragma("unroll") for (int n = 0; n < 2; ++n) _Pragma("unroll") for (int k = 0; k < 2; ++k) dst[n][k] = *(const LAS bf16x8*)(lds + PG8_SB(b, h) + boff + n * 2048 + k * 1024); } while (0)
; #define PG8_MMA(ai, bj, At, Bt) do { __builtin_amdgcn_s_setprio(1); _Pragma("unroll") for (int m = 0; m < 4; ++m) _Pragma("unroll") for (int n = 0; n < 2; ++n) _Pragma("unroll") for (int k = 0; k < 2; ++k) \
;         acc[ai][bj][m][n] = __builtin_amdgcn_mfma_f32_16x16x32_bf16(Bt[n][k], At[m][k], acc[ai][bj][m][n], 0, 0, 0); __builtin_amdgcn_s_setprio(0); } while (0)
; #define PG8_WAIT_V(n) asm volatile("s_waitcnt vmcnt(" #n ")" ::: "memory")
; #define PG8_WAIT_L(n) asm volatile("s_waitcnt lgkmcnt(" #n ")" ::: "memory")
; #define PG8_BAR __builtin_amdgcn_s_barrier()
; #define PG8_SCHED __builtin_amdgcn_sched_barrier(0)
; template <class Epi>
; __device__ __forceinline__ void gemm_phase(LAS unsigned char* lds, const Gemm g, const Sched& S, const Epi& E) {
;     ...
;             PG8_BAR; PG8_WAIT_L(0); PG8_MMA(1, 0, At, B0); PG8_BAR; PG8_SCHED;
;             PG8_STAGE(PG8_SB(0, 1), b2 + hstepB, voffB);
;             PG8_WAIT_V(6); PG8_BAR; PG8_MMA(1, 1, At, B1); PG8_BAR;
;             PG8_LDB(B0, 1, 0); PG8_SCHED; PG8_LDA(At, 1, 0); PG8_STAGE(PG8_SA(0, 1), a2 + hstepA, voffA);
;             PG8_WAIT_L(8); PG8_BAR; PG8_WAIT_L(0); PG8_MMA(0, 0, At, B0); PG8_BAR; PG8_SCHED;
;             PG8_LDB(B1, 1, 1); PG8_STAGE(PG8_SB(1, 0), b3, voffB);
;             PG8_BAR; PG8_WAIT_L(0); PG8_MMA(0, 1, At, B1); PG8_BAR;
;             PG8_LDA(At, 1, 1); PG8_STAGE(PG8_SA(1, 0), a3, voffA);
;             PG8_BAR; PG8_WAIT_L(0); PG8_MMA(1, 0, At, B0); PG8_BAR; PG8_SCHED;
	s_setprio 1
	v_mfma_f32_16x16x32_bf16 v[30:33], v[142:145], v[180:183], v[30:33]
	v_mfma_f32_16x16x32_bf16 v[26:29], v[150:153], v[180:183], v[26:29]
	v_mfma_f32_16x16x32_bf16 v[14:17], v[142:145], v[188:191], v[14:17]
	v_mfma_f32_16x16x32_bf16 v[10:13], v[150:153], v[188:191], v[10:13]
	v_mfma_f32_16x16x32_bf16 v[62:65], v[146:149], v[168:171], v[62:65]
	v_mfma_f32_16x16x32_bf16 v[58:61], v[160:163], v[168:171], v[58:61]
	v_mfma_f32_16x16x32_bf16 v[46:49], v[146:149], v[176:179], v[46:49]
	v_mfma_f32_16x16x32_bf16 v[42:45], v[160:163], v[176:179], v[42:45]
	v_mfma_f32_16x16x32_bf16 v[30:33], v[146:149], v[184:187], v[30:33]
	v_mfma_f32_16x16x32_bf16 v[26:29], v[160:163], v[184:187], v[26:29]
	v_mfma_f32_16x16x32_bf16 v[14:17], v[146:149], v[196:199], v[14:17]
	v_mfma_f32_16x16x32_bf16 v[10:13], v[160:163], v[196:199], v[10:13]
	v_mfma_f32_16x16x32_bf16 v[54:57], v[200:203], v[164:167], v[54:57]
	v_mfma_f32_16x16x32_bf16 v[50:53], v[208:211], v[164:167], v[50:53]
	v_mfma_f32_16x16x32_bf16 v[38:41], v[200:203], v[172:175], v[38:41]
	v_mfma_f32_16x16x32_bf16 v[34:37], v[208:211], v[172:175], v[34:37]
	v_mfma_f32_16x16x32_bf16 v[22:25], v[200:203], v[180:183], v[22:25]
	v_mfma_f32_16x16x32_bf16 v[18:21], v[208:211], v[180:183], v[18:21]
	v_mfma_f32_16x16x32_bf16 v[6:9], v[200:203], v[188:191], v[6:9]
	v_mfma_f32_16x16x32_bf16 v[2:5], v[208:211], v[188:191], v[2:5]
	v_mfma_f32_16x16x32_bf16 v[54:57], v[204:207], v[168:171], v[54:57]
	v_mfma_f32_16x16x32_bf16 v[50:53], v[212:215], v[168:171], v[50:53]
	v_mfma_f32_16x16x32_bf16 v[38:41], v[204:207], v[176:179], v[38:41]
	v_mfma_f32_16x16x32_bf16 v[34:37], v[212:215], v[176:179], v[34:37]
	v_mfma_f32_16x16x32_bf16 v[22:25], v[204:207], v[184:187], v[22:25]
	v_mfma_f32_16x16x32_bf16 v[18:21], v[212:215], v[184:187], v[18:21]
	v_mfma_f32_16x16x32_bf16 v[6:9], v[204:207], v[196:199], v[6:9]
	v_mfma_f32_16x16x32_bf16 v[2:5], v[212:215], v[196:199], v[2:5]
	s_setprio 0
	s_barrier
	s_add_i32 s8, 0, 0x18000
	v_add_u32_e32 v160, s8, v156
	ds_read_b128 v[142:145], v160
	ds_read_b128 v[146:149], v160 offset:1024
	ds_read_b128 v[150:153], v160 offset:2048
	ds_read_b128 v[160:163], v160 offset:3072
	s_add_u32 s6, s6, s36
	s_addc_u32 s7, s7, s37
	s_mov_b32 m0, s39
	v_lshl_add_u64 v[200:201], s[6:7], 0, v[130:131]
	ds_read_b128 v[164:167], v159 offset:32768
	ds_read_b128 v[168:171], v159 offset:33792
	ds_read_b128 v[172:175], v159 offset:34816
	ds_read_b128 v[176:179], v159 offset:35840
	ds_read_b128 v[180:183], v159 offset:36864
	ds_read_b128 v[184:187], v159 offset:37888
	ds_read_b128 v[188:191], v159 offset:38912
	ds_read_b128 v[196:199], v159 offset:39936
	global_load_lds_dwordx4 v[200:201], off
	v_lshl_add_u64 v[200:201], s[6:7], 0, v[132:133]
	s_mov_b32 m0, s40
	s_nop 0
	global_load_lds_dwordx4 v[200:201], off
	s_add_i32 s6, 0, 0x1c000
	v_add_u32_e32 v212, s6, v156
	ds_read_b128 v[200:203], v212
	ds_read_b128 v[204:207], v212 offset:1024
	ds_read_b128 v[208:211], v212 offset:2048
	ds_read_b128 v[212:215], v212 offset:3072
	s_waitcnt vmcnt(8)
	s_waitcnt lgkmcnt(0)
	v_mfma_f32_16x16x32_bf16 v[126:129], v[142:145], v[164:167], v[126:129]
	v_mfma_f32_16x16x32_bf16 v[122:125], v[150:153], v[164:167], v[122:125]
	v_mfma_f32_16x16x32_bf16 v[110:113], v[142:145], v[172:175], v[110:113]
	v_mfma_f32_16x16x32_bf16 v[106:109], v[150:153], v[172:175], v[106:109]
	s_barrier
	s_setprio 1
	v_mfma_f32_16x16x32_bf16 v[94:97], v[142:145], v[180:183], v[94:97]
	v_mfma_f32_16x16x32_bf16 v[90:93], v[150:153], v[180:183], v[90:93]
	v_mfma_f32_16x16x32_bf16 v[78:81], v[142:145], v[188:191], v[78:81]
	v_mfma_f32_16x16x32_bf16 v[74:77], v[150:153], v[188:191], v[74:77]
	v_mfma_f32_16x16x32_bf16 v[126:129], v[146:149], v[168:171], v[126:129]
	v_mfma_f32_16x16x32_bf16 v[122:125], v[160:163], v[168:171], v[122:125]
	v_mfma_f32_16x16x32_bf16 v[110:113], v[146:149], v[176:179], v[110:113]
	v_mfma_f32_16x16x32_bf16 v[106:109], v[160:163], v[176:179], v[106:109]
	v_mfma_f32_16x16x32_bf16 v[94:97], v[146:149], v[184:187], v[94:97]
	v_mfma_f32_16x16x32_bf16 v[90:93], v[160:163], v[184:187], v[90:93]
	v_mfma_f32_16x16x32_bf16 v[78:81], v[146:149], v[196:199], v[78:81]
	v_mfma_f32_16x16x32_bf16 v[74:77], v[160:163], v[196:199], v[74:77]
	v_mfma_f32_16x16x32_bf16 v[118:121], v[200:203], v[164:167], v[118:121]
	v_mfma_f32_16x16x32_bf16 v[114:117], v[208:211], v[164:167], v[114:117]
	v_mfma_f32_16x16x32_bf16 v[102:105], v[200:203], v[172:175], v[102:105]
	v_mfma_f32_16x16x32_bf16 v[98:101], v[208:211], v[172:175], v[98:101]
	v_mfma_f32_16x16x32_bf16 v[86:89], v[200:203], v[180:183], v[86:89]
	v_mfma_f32_16x16x32_bf16 v[82:85], v[208:211], v[180:183], v[82:85]
	v_mfma_f32_16x16x32_bf16 v[70:73], v[200:203], v[188:191], v[70:73]
	v_mfma_f32_16x16x32_bf16 v[66:69], v[208:211], v[188:191], v[66:69]
	v_mfma_f32_16x16x32_bf16 v[118:121], v[204:207], v[168:171], v[118:121]
	v_mfma_f32_16x16x32_bf16 v[114:117], v[212:215], v[168:171], v[114:117]
	v_mfma_f32_16x16x32_bf16 v[102:105], v[204:207], v[176:179], v[102:105]
	v_mfma_f32_16x16x32_bf16 v[98:101], v[212:215], v[176:179], v[98:101]
	v_mfma_f32_16x16x32_bf16 v[86:89], v[204:207], v[184:187], v[86:89]
	v_mfma_f32_16x16x32_bf16 v[82:85], v[212:215], v[184:187], v[82:85]
	v_mfma_f32_16x16x32_bf16 v[70:73], v[204:207], v[196:199], v[70:73]
	v_mfma_f32_16x16x32_bf16 v[66:69], v[212:215], v[196:199], v[66:69]
	s_setprio 0
	s_barrier
; __device__ __forceinline__ float pre_get(const Pre& p, int ai, int m, int fr) { return __shfl(p.v[ai], m * 16 + fr); }
; __device__ __forceinline__ float rstd_pre(const float* ss, float v) { return ss ? rsqrtf(v * (1.0f / 2048.0f) + 1e-6f) : 1.0f; }
; #define PG8_STAGE(bufoff, gbase, voff) do { _Pragma("unroll") for (int _i = 0; _i < 2; ++_i) \
;         __builtin_amdgcn_global_load_lds((const unsigned*)((const char*)(gbase) + (voff)[_i]), (LAS unsigned*)(lds + (bufoff) + ldsw + _i * 8192), 16, 0, 0); } while (0)
; #define PG8_LDA(dst, b, h) do { _Pragma("unroll") for (int m = 0; m < 4; ++m) _Pragma("unroll") for (int k = 0; k < 2; ++k) dst[m][k] = *(const LAS bf16x8*)(lds + PG8_SA(b, h) + aoff + m * 2048 + k * 1024); } while (0)
; #define PG8_LDB(dst, b, h) do { _Pragma("unroll") for (int n = 0; n < 2; ++n) _Pragma("unroll") for (int k = 0; k < 2; ++k) dst[n][k] = *(const LAS bf16x8*)(lds + PG8_SB(b, h) + boff + n * 2048 + k * 1024); } while (0)
; template <class Epi>
; __device__ __forceinline__ void gemm_phase(LAS unsigned char* lds, const Gemm g, const Sched& S, const Epi& E) {
;     ...
;             PG8_LDB(B1, 1, 1); PG8_STAGE(PG8_SB(1, 0), b3, voffB);
;             PG8_BAR; PG8_WAIT_L(0); PG8_MMA(0, 1, At, B1); PG8_BAR;
;             PG8_LDA(At, 1, 1); PG8_STAGE(PG8_SA(1, 0), a3, voffA);
;             PG8_BAR; PG8_WAIT_L(0); PG8_MMA(1, 0, At, B0); PG8_BAR; PG8_SCHED;
;             PG8_STAGE(PG8_SB(1, 1), b3 + hstepB, voffB);
;             PG8_WAIT_V(6); PG8_BAR; PG8_MMA(1, 1, At, B1); PG8_BAR;
;         }
;     __device__ __forceinline__ void operator()(const Acc& acc, const Unit& u, int wr, int wc, int fr, int fq, const Pre& pre) const {
;         const int colt = (u.pn < split) ? base0 + u.pn * 256 : base1 + (u.pn - split) * 256;
;         const int row0 = u.pm * 256 + wr * 64 + fr, col0 = colt + wc * 32 + 8 * fq;
;         bf16_t* Oz = O + (size_t)(u.zb * sOb + u.zh * sOh);
;         float rsq[2][4];
; #pragma unroll
;         for (int ai = 0; ai < 2; ++ai)
; #pragma unroll
;             for (int m = 0; m < 4; ++m) rsq[ai][m] = rstd_pre(ss, pre_get(pre, ai, m, fr));
; #pragma unroll
;         for (int ai = 0; ai < 2; ++ai)
; #pragma unroll
;             for (int m = 0; m < 4; ++m) { const float rs = scale * rsq[ai][m];
; #pragma unroll
;                 for (int bj = 0; bj < 2; ++bj) { f32x4 v0 = acc[ai][bj][m][0] * rs, v1 = acc[ai][bj][m][1] * rs;
	s_add_i32 s7, s8, s3
	v_lshl_add_u64 v[192:193], v[192:193], 0, s[60:61]
	s_mov_b32 m0, s7
	s_nop 0
	global_load_lds_dwordx4 v[192:193], off
	v_lshl_add_u64 v[192:193], v[194:195], 0, s[60:61]
	s_add_i32 m0, s7, 0x2000
	s_nop 0
	global_load_lds_dwordx4 v[192:193], off
	s_mov_b32 m0, s41
	v_lshl_add_u64 v[192:193], v[216:217], 0, s[60:61]
	ds_read_b128 v[164:167], v159 offset:49152
	ds_read_b128 v[168:171], v159 offset:50176
	ds_read_b128 v[172:175], v159 offset:51200
	ds_read_b128 v[176:179], v159 offset:52224
	ds_read_b128 v[180:183], v159 offset:53248
	ds_read_b128 v[184:187], v159 offset:54272
	ds_read_b128 v[188:191], v159 offset:55296
	ds_read_b128 v[196:199], v159 offset:56320
	global_load_lds_dwordx4 v[192:193], off
	v_lshl_add_u64 v[192:193], v[222:223], 0, s[60:61]
	s_mov_b32 m0, s42
	s_nop 0
	global_load_lds_dwordx4 v[192:193], off
	s_add_i32 s6, s6, s3
	v_lshl_add_u64 v[192:193], v[224:225], 0, s[60:61]
	s_mov_b32 m0, s6
	s_nop 0
	global_load_lds_dwordx4 v[192:193], off
	v_lshl_add_u64 v[192:193], v[226:227], 0, s[60:61]
	s_add_i32 m0, s6, 0x2000
	s_nop 0
	global_load_lds_dwordx4 v[192:193], off
	s_waitcnt vmcnt(8)
	s_waitcnt lgkmcnt(0)
	v_mfma_f32_16x16x32_bf16 v[62:65], v[142:145], v[164:167], v[62:65]
	v_mfma_f32_16x16x32_bf16 v[58:61], v[150:153], v[164:167], v[58:61]
	v_mfma_f32_16x16x32_bf16 v[46:49], v[142:145], v[172:175], v[46:49]
	v_mfma_f32_16x16x32_bf16 v[42:45], v[150:153], v[172:175], v[42:45]
	s_barrier
	s_setprio 1
	v_mfma_f32_16x16x32_bf16 v[30:33], v[142:145], v[180:183], v[30:33]
	v_mfma_f32_16x16x32_bf16 v[26:29], v[150:153], v[180:183], v[26:29]
	v_mfma_f32_16x16x32_bf16 v[14:17], v[142:145], v[188:191], v[14:17]
	v_mfma_f32_16x16x32_bf16 v[10:13], v[150:153], v[188:191], v[10:13]
	v_mfma_f32_16x16x32_bf16 v[62:65], v[146:149], v[168:171], v[62:65]
	v_mfma_f32_16x16x32_bf16 v[58:61], v[160:163], v[168:171], v[58:61]
	v_mfma_f32_16x16x32_bf16 v[46:49], v[146:149], v[176:179], v[46:49]
	v_mfma_f32_16x16x32_bf16 v[42:45], v[160:163], v[176:179], v[42:45]
	v_mfma_f32_16x16x32_bf16 v[30:33], v[146:149], v[184:187], v[30:33]
	v_mfma_f32_16x16x32_bf16 v[26:29], v[160:163], v[184:187], v[26:29]
	v_mfma_f32_16x16x32_bf16 v[14:17], v[146:149], v[196:199], v[14:17]
	v_mfma_f32_16x16x32_bf16 v[10:13], v[160:163], v[196:199], v[10:13]
	v_mfma_f32_16x16x32_bf16 v[54:57], v[200:203], v[164:167], v[54:57]
	v_mfma_f32_16x16x32_bf16 v[50:53], v[208:211], v[164:167], v[50:53]
	v_mfma_f32_16x16x32_bf16 v[38:41], v[200:203], v[172:175], v[38:41]
	v_mfma_f32_16x16x32_bf16 v[34:37], v[208:211], v[172:175], v[34:37]
	v_mfma_f32_16x16x32_bf16 v[22:25], v[200:203], v[180:183], v[22:25]
	v_mfma_f32_16x16x32_bf16 v[18:21], v[208:211], v[180:183], v[18:21]
	v_mfma_f32_16x16x32_bf16 v[6:9], v[200:203], v[188:191], v[6:9]
	v_mfma_f32_16x16x32_bf16 v[2:5], v[208:211], v[188:191], v[2:5]
	v_mfma_f32_16x16x32_bf16 v[54:57], v[204:207], v[168:171], v[54:57]
	v_mfma_f32_16x16x32_bf16 v[50:53], v[212:215], v[168:171], v[50:53]
	v_mfma_f32_16x16x32_bf16 v[38:41], v[204:207], v[176:179], v[38:41]
	v_mfma_f32_16x16x32_bf16 v[34:37], v[212:215], v[176:179], v[34:37]
	v_mfma_f32_16x16x32_bf16 v[22:25], v[204:207], v[184:187], v[22:25]
	v_mfma_f32_16x16x32_bf16 v[18:21], v[212:215], v[184:187], v[18:21]
	v_mfma_f32_16x16x32_bf16 v[6:9], v[204:207], v[196:199], v[6:9]
	v_mfma_f32_16x16x32_bf16 v[2:5], v[212:215], v[196:199], v[2:5]
	s_setprio 0
	s_add_u32 s4, s4, 0x100
	s_addc_u32 s5, s5, 0
	s_add_u32 s34, s34, 0x100
	s_addc_u32 s35, s35, 0
	s_cmp_ge_u32 s14, s73
	s_mov_b32 s6, s14
	s_barrier
	s_cbranch_scc0 .LBB0_555
	v_and_or_b32 v142, v220, 64, v154
	v_lshlrev_b32_e32 v148, 2, v142
	ds_bpermute_b32 v143, v148, v141
	ds_bpermute_b32 v142, v148, v141 offset:64
	s_mov_b32 s4, 0x3a000000
	ds_bpermute_b32 v145, v148, v141 offset:128
	ds_bpermute_b32 v144, v148, v141 offset:192
	v_readlane_b32 s8, v254, 29
	s_waitcnt lgkmcnt(0)
	v_pk_fma_f32 v[146:147], v[142:143], s[4:5], v[232:233] op_sel_hi:[1,0,0]
	ds_bpermute_b32 v143, v148, v140
	v_mul_f32_e32 v141, 0x4b800000, v147
	v_cmp_gt_f32_e32 vcc, s97, v147
	ds_bpermute_b32 v142, v148, v140 offset:64
	v_readlane_b32 s9, v254, 30
	v_cndmask_b32_e32 v141, v147, v141, vcc
	v_rsq_f32_e32 v141, v141
	v_cmp_gt_f32_e64 s[4:5], s97, v146
	s_mov_b64 s[90:91], -1
	v_mul_f32_e32 v147, 0x45800000, v141
	v_cndmask_b32_e32 v141, v141, v147, vcc
	v_cndmask_b32_e64 v147, v141, 1.0, s[78:79]
	ds_bpermute_b32 v141, v148, v140 offset:128
	ds_bpermute_b32 v140, v148, v140 offset:192
	v_mul_f32_e32 v148, s70, v147
	v_pk_mul_f32 v[152:153], v[122:123], v[148:149] op_sel_hi:[1,0]
	v_cndmask_b32_e64 v122, 0, 1, s[8:9]
	v_pk_mul_f32 v[128:129], v[128:129], v[148:149] op_sel_hi:[1,0]
	v_pk_mul_f32 v[150:151], v[126:127], v[148:149] op_sel_hi:[1,0]
	v_pk_mul_f32 v[126:127], v[124:125], v[148:149] op_sel_hi:[1,0]
	v_cmp_ne_u32_e64 s[6:7], 1, v122
	s_andn2_b64 vcc, exec, s[8:9]
	s_cbranch_vccnz .LBB0_558
	s_mov_b64 s[90:91], 0

; #define PG8_STAGE(bufoff, gbase, voff) do { _Pragma("unroll") for (int _i = 0; _i < 2; ++_i) \
;         __builtin_amdgcn_global_load_lds((const unsigned*)((const char*)(gbase) + (voff)[_i]), (LAS unsigned*)(lds + (bufoff) + ldsw + _i * 8192), 16, 0, 0); } while (0)
; #define PG8_LDA(dst, b, h) do { _Pragma("unroll") for (int m = 0; m < 4; ++m) _Pragma("unroll") for (int k = 0; k < 2; ++k) dst[m][k] = *(const LAS bf16x8*)(lds + PG8_SA(b, h) + aoff + m * 2048 + k * 1024); } while (0)
; #define PG8_LDB(dst, b, h) do { _Pragma("unroll") for (int n = 0; n < 2; ++n) _Pragma("unroll") for (int k = 0; k < 2; ++k) dst[n][k] = *(const LAS bf16x8*)(lds + PG8_SB(b, h) + boff + n * 2048 + k * 1024); } while (0)
; #define PG8_MMA(ai, bj, At, Bt) do { __builtin_amdgcn_s_setprio(1); _Pragma("unroll") for (int m = 0; m < 4; ++m) _Pragma("unroll") for (int n = 0; n < 2; ++n) _Pragma("unroll") for (int k = 0; k < 2; ++k) \
;         acc[ai][bj][m][n] = __builtin_amdgcn_mfma_f32_16x16x32_bf16(Bt[n][k], At[m][k], acc[ai][bj][m][n], 0, 0, 0); __builtin_amdgcn_s_setprio(0); } while (0)
; #define PG8_WAIT_L(n) asm volatile("s_waitcnt lgkmcnt(" #n ")" ::: "memory")
; #define PG8_BAR __builtin_amdgcn_s_barrier()
; #define PG8_SCHED __builtin_amdgcn_sched_barrier(0)
; template <class Epi>
; __device__ __forceinline__ void gemm_phase(LAS unsigned char* lds, const Gemm g, const Sched& S, const Epi& E) {
;     ...
;         for (int t = 0; t < nt; t += 2) {
;             const bool last = (t == nt - 2);
;             const char* a1 = cA + (size_t)(t + 1) * kstep;
;             const char* a2 = last ? nA : cA + (size_t)(t + 2) * kstep; const char* b2 = last ? nB : cB + (size_t)(t + 2) * kstep;
;             const char* a3 = a2 + kstep; const char* b3 = b2 + kstep;
;             PG8_LDB(B0, 0, 0); PG8_SCHED; PG8_LDA(At, 0, 0); PG8_STAGE(PG8_SA(1, 1), a1 + hstepA, voffA);
;             PG8_WAIT_L(8); PG8_BAR; PG8_WAIT_L(0); PG8_MMA(0, 0, At, B0); PG8_BAR; PG8_SCHED;
;             PG8_LDB(B1, 0, 1); PG8_STAGE(PG8_SB(0, 0), b2, voffB);
;             PG8_BAR; PG8_WAIT_L(0); PG8_MMA(0, 1, At, B1); PG8_BAR;
;             PG8_LDA(At, 0, 1); PG8_STAGE(PG8_SA(0, 0), a2, voffA);
;             PG8_BAR; PG8_WAIT_L(0); PG8_MMA(1, 0, At, B0); PG8_BAR; PG8_SCHED;
.LBB0_649:
	s_add_i32 s14, s4, 2
	s_add_u32 s8, s0, 0x80
	s_addc_u32 s5, s1, 0
	s_add_i32 s9, 0, 0x10000
	v_add_u32_e32 v144, s9, v236
	ds_read_b128 v[132:135], v144
	ds_read_b128 v[136:139], v144 offset:1024
	ds_read_b128 v[140:143], v144 offset:2048
	ds_read_b128 v[144:147], v144 offset:3072
	s_cmp_eq_u32 s95, s4
	s_cselect_b32 s4, s48, s8
	s_cselect_b32 s5, s33, s5
	s_cselect_b32 s87, s51, s35
	s_cselect_b32 s86, s55, s34
	v_lshl_add_u64 v[176:177], s[0:1], 0, v[188:189]
	s_add_i32 m0, s89, 0xc000
	ds_read_b128 v[148:151], v239
	ds_read_b128 v[152:155], v239 offset:1024
	ds_read_b128 v[156:159], v239 offset:2048
	ds_read_b128 v[160:163], v239 offset:3072
	ds_read_b128 v[164:167], v239 offset:4096
	ds_read_b128 v[168:171], v239 offset:5120
	ds_read_b128 v[172:175], v239 offset:6144
	ds_read_b128 v[196:199], v239 offset:7168
	global_load_lds_dwordx4 v[176:177], off
	v_lshl_add_u64 v[176:177], s[0:1], 0, v[190:191]
	s_add_i32 m0, s89, 0xe000
	s_nop 0
	global_load_lds_dwordx4 v[176:177], off
	s_add_i32 s8, 0, 0x14000
	v_add_u32_e32 v176, s8, v236
	ds_read_b128 v[200:203], v176
	ds_read_b128 v[204:207], v176 offset:1024
	ds_read_b128 v[208:211], v176 offset:2048
	ds_read_b128 v[212:215], v176 offset:3072
	s_waitcnt vmcnt(8)
	s_waitcnt lgkmcnt(0)
	v_mfma_f32_16x16x32_bf16 v[126:129], v[132:135], v[148:151], v[126:129]
	v_mfma_f32_16x16x32_bf16 v[122:125], v[140:143], v[148:151], v[122:125]
	v_mfma_f32_16x16x32_bf16 v[110:113], v[132:135], v[156:159], v[110:113]
	v_mfma_f32_16x16x32_bf16 v[106:109], v[140:143], v[156:159], v[106:109]
	s_barrier
	s_setprio 1
	v_mfma_f32_16x16x32_bf16 v[94:97], v[132:135], v[164:167], v[94:97]
	v_mfma_f32_16x16x32_bf16 v[90:93], v[140:143], v[164:167], v[90:93]
	v_mfma_f32_16x16x32_bf16 v[78:81], v[132:135], v[172:175], v[78:81]
	v_mfma_f32_16x16x32_bf16 v[74:77], v[140:143], v[172:175], v[74:77]
	v_mfma_f32_16x16x32_bf16 v[126:129], v[136:139], v[152:155], v[126:129]
	v_mfma_f32_16x16x32_bf16 v[122:125], v[144:147], v[152:155], v[122:125]
	v_mfma_f32_16x16x32_bf16 v[110:113], v[136:139], v[160:163], v[110:113]
	v_mfma_f32_16x16x32_bf16 v[106:109], v[144:147], v[160:163], v[106:109]
	v_mfma_f32_16x16x32_bf16 v[94:97], v[136:139], v[168:171], v[94:97]
	v_mfma_f32_16x16x32_bf16 v[90:93], v[144:147], v[168:171], v[90:93]
	v_mfma_f32_16x16x32_bf16 v[78:81], v[136:139], v[196:199], v[78:81]
	v_mfma_f32_16x16x32_bf16 v[74:77], v[144:147], v[196:199], v[74:77]
	v_mfma_f32_16x16x32_bf16 v[118:121], v[200:203], v[148:151], v[118:121]
	v_mfma_f32_16x16x32_bf16 v[114:117], v[208:211], v[148:151], v[114:117]
	v_mfma_f32_16x16x32_bf16 v[102:105], v[200:203], v[156:159], v[102:105]
	v_mfma_f32_16x16x32_bf16 v[98:101], v[208:211], v[156:159], v[98:101]
	v_mfma_f32_16x16x32_bf16 v[86:89], v[200:203], v[164:167], v[86:89]
	v_mfma_f32_16x16x32_bf16 v[82:85], v[208:211], v[164:167], v[82:85]
	v_mfma_f32_16x16x32_bf16 v[70:73], v[200:203], v[172:175], v[70:73]
	v_mfma_f32_16x16x32_bf16 v[66:69], v[208:211], v[172:175], v[66:69]
	v_mfma_f32_16x16x32_bf16 v[118:121], v[204:207], v[152:155], v[118:121]
	v_mfma_f32_16x16x32_bf16 v[114:117], v[212:215], v[152:155], v[114:117]
	v_mfma_f32_16x16x32_bf16 v[102:105], v[204:207], v[160:163], v[102:105]
	v_mfma_f32_16x16x32_bf16 v[98:101], v[212:215], v[160:163], v[98:101]
	v_mfma_f32_16x16x32_bf16 v[86:89], v[204:207], v[168:171], v[86:89]
	v_mfma_f32_16x16x32_bf16 v[82:85], v[212:215], v[168:171], v[82:85]
	v_mfma_f32_16x16x32_bf16 v[70:73], v[204:207], v[196:199], v[70:73]
	v_mfma_f32_16x16x32_bf16 v[66:69], v[212:215], v[196:199], v[66:69]
	s_setprio 0
	s_barrier
	s_add_i32 s9, s9, s88
	v_lshl_add_u64 v[176:177], s[86:87], 0, v[180:181]
	s_mov_b32 m0, s9
	v_lshl_add_u64 v[192:193], s[86:87], 0, v[184:185]
	global_load_lds_dwordx4 v[176:177], off
	s_add_i32 m0, s9, 0x2000
	s_nop 0
	global_load_lds_dwordx4 v[192:193], off
	s_mov_b32 m0, s89
	v_lshl_add_u64 v[194:195], s[4:5], 0, v[178:179]
	ds_read_b128 v[148:151], v239 offset:16384
	ds_read_b128 v[152:155], v239 offset:17408
	ds_read_b128 v[156:159], v239 offset:18432
	ds_read_b128 v[160:163], v239 offset:19456
	ds_read_b128 v[164:167], v239 offset:20480
	ds_read_b128 v[168:171], v239 offset:21504
	ds_read_b128 v[172:175], v239 offset:22528
	ds_read_b128 v[196:199], v239 offset:23552
	global_load_lds_dwordx4 v[194:195], off
	v_lshl_add_u64 v[216:217], s[4:5], 0, v[182:183]
	s_mov_b32 m0, s90
	s_nop 0
	global_load_lds_dwordx4 v[216:217], off
	s_add_u32 s56, s86, s36
	s_addc_u32 s57, s87, s37
	s_add_i32 s8, s8, s88
	v_lshl_add_u64 v[222:223], s[56:57], 0, v[180:181]
	s_mov_b32 m0, s8
	v_lshl_add_u64 v[224:225], s[56:57], 0, v[184:185]
	global_load_lds_dwordx4 v[222:223], off
	s_add_i32 m0, s8, 0x2000
	s_nop 0
	global_load_lds_dwordx4 v[224:225], off
	s_waitcnt vmcnt(8)
	s_waitcnt lgkmcnt(0)
	v_mfma_f32_16x16x32_bf16 v[62:65], v[132:135], v[148:151], v[62:65]
	v_mfma_f32_16x16x32_bf16 v[58:61], v[140:143], v[148:151], v[58:61]
	v_mfma_f32_16x16x32_bf16 v[46:49], v[132:135], v[156:159], v[46:49]
	v_mfma_f32_16x16x32_bf16 v[42:45], v[140:143], v[156:159], v[42:45]
	s_barrier
; #define PG8_STAGE(bufoff, gbase, voff) do { _Pragma("unroll") for (int _i = 0; _i < 2; ++_i) \
;         __builtin_amdgcn_global_load_lds((const unsigned*)((const char*)(gbase) + (voff)[_i]), (LAS unsigned*)(lds + (bufoff) + ldsw + _i * 8192), 16, 0, 0); } while (0)
; #define PG8_LDA(dst, b, h) do { _Pragma("unroll") for (int m = 0; m < 4; ++m) _Pragma("unroll") for (int k = 0; k < 2; ++k) dst[m][k] = *(const LAS bf16x8*)(lds + PG8_SA(b, h) + aoff + m * 2048 + k * 1024); } while (0)
; #define PG8_LDB(dst, b, h) do { _Pragma("unroll") for (int n = 0; n < 2; ++n) _Pragma("unroll") for (int k = 0; k < 2; ++k) dst[n][k] = *(const LAS bf16x8*)(lds + PG8_SB(b, h) + boff + n * 2048 + k * 1024); } while (0)
; #define PG8_MMA(ai, bj, At, Bt) do { __builtin_amdgcn_s_setprio(1); _Pragma("unroll") for (int m = 0; m < 4; ++m) _Pragma("unroll") for (int n = 0; n < 2; ++n) _Pragma("unroll") for (int k = 0; k < 2; ++k) \
;         acc[ai][bj][m][n] = __builtin_amdgcn_mfma_f32_16x16x32_bf16(Bt[n][k], At[m][k], acc[ai][bj][m][n], 0, 0, 0); __builtin_amdgcn_s_setprio(0); } while (0)
; #define PG8_WAIT_V(n) asm volatile("s_waitcnt vmcnt(" #n ")" ::: "memory")
; #define PG8_WAIT_L(n) asm volatile("s_waitcnt lgkmcnt(" #n ")" ::: "memory")
; #define PG8_BAR __builtin_amdgcn_s_barrier()
; #define PG8_SCHED __builtin_amdgcn_sched_barrier(0)
; template <class Epi>
; __device__ __forceinline__ void gemm_phase(LAS unsigned char* lds, const Gemm g, const Sched& S, const Epi& E) {
;     ...
;             PG8_BAR; PG8_WAIT_L(0); PG8_MMA(1, 0, At, B0); PG8_BAR; PG8_SCHED;
;             PG8_STAGE(PG8_SB(0, 1), b2 + hstepB, voffB);
;             PG8_WAIT_V(6); PG8_BAR; PG8_MMA(1, 1, At, B1); PG8_BAR;
;             PG8_LDB(B0, 1, 0); PG8_SCHED; PG8_LDA(At, 1, 0); PG8_STAGE(PG8_SA(0, 1), a2 + hstepA, voffA);
;             PG8_WAIT_L(8); PG8_BAR; PG8_WAIT_L(0); PG8_MMA(0, 0, At, B0); PG8_BAR; PG8_SCHED;
;             PG8_LDB(B1, 1, 1); PG8_STAGE(PG8_SB(1, 0), b3, voffB);
;             PG8_BAR; PG8_WAIT_L(0); PG8_MMA(0, 1, At, B1); PG8_BAR;
;             PG8_LDA(At, 1, 1); PG8_STAGE(PG8_SA(1, 0), a3, voffA);
;             PG8_BAR; PG8_WAIT_L(0); PG8_MMA(1, 0, At, B0); PG8_BAR; PG8_SCHED;
	s_setprio 1
	v_mfma_f32_16x16x32_bf16 v[30:33], v[132:135], v[164:167], v[30:33]
	v_mfma_f32_16x16x32_bf16 v[26:29], v[140:143], v[164:167], v[26:29]
	v_mfma_f32_16x16x32_bf16 v[14:17], v[132:135], v[172:175], v[14:17]
	v_mfma_f32_16x16x32_bf16 v[10:13], v[140:143], v[172:175], v[10:13]
	v_mfma_f32_16x16x32_bf16 v[62:65], v[136:139], v[152:155], v[62:65]
	v_mfma_f32_16x16x32_bf16 v[58:61], v[144:147], v[152:155], v[58:61]
	v_mfma_f32_16x16x32_bf16 v[46:49], v[136:139], v[160:163], v[46:49]
	v_mfma_f32_16x16x32_bf16 v[42:45], v[144:147], v[160:163], v[42:45]
	v_mfma_f32_16x16x32_bf16 v[30:33], v[136:139], v[168:171], v[30:33]
	v_mfma_f32_16x16x32_bf16 v[26:29], v[144:147], v[168:171], v[26:29]
	v_mfma_f32_16x16x32_bf16 v[14:17], v[136:139], v[196:199], v[14:17]
	v_mfma_f32_16x16x32_bf16 v[10:13], v[144:147], v[196:199], v[10:13]
	v_mfma_f32_16x16x32_bf16 v[54:57], v[200:203], v[148:151], v[54:57]
	v_mfma_f32_16x16x32_bf16 v[50:53], v[208:211], v[148:151], v[50:53]
	v_mfma_f32_16x16x32_bf16 v[38:41], v[200:203], v[156:159], v[38:41]
	v_mfma_f32_16x16x32_bf16 v[34:37], v[208:211], v[156:159], v[34:37]
	v_mfma_f32_16x16x32_bf16 v[22:25], v[200:203], v[164:167], v[22:25]
	v_mfma_f32_16x16x32_bf16 v[18:21], v[208:211], v[164:167], v[18:21]
	v_mfma_f32_16x16x32_bf16 v[6:9], v[200:203], v[172:175], v[6:9]
	v_mfma_f32_16x16x32_bf16 v[2:5], v[208:211], v[172:175], v[2:5]
	v_mfma_f32_16x16x32_bf16 v[54:57], v[204:207], v[152:155], v[54:57]
	v_mfma_f32_16x16x32_bf16 v[50:53], v[212:215], v[152:155], v[50:53]
	v_mfma_f32_16x16x32_bf16 v[38:41], v[204:207], v[160:163], v[38:41]
	v_mfma_f32_16x16x32_bf16 v[34:37], v[212:215], v[160:163], v[34:37]
	v_mfma_f32_16x16x32_bf16 v[22:25], v[204:207], v[168:171], v[22:25]
	v_mfma_f32_16x16x32_bf16 v[18:21], v[212:215], v[168:171], v[18:21]
	v_mfma_f32_16x16x32_bf16 v[6:9], v[204:207], v[196:199], v[6:9]
	v_mfma_f32_16x16x32_bf16 v[2:5], v[212:215], v[196:199], v[2:5]
	s_setprio 0
	s_barrier
	s_add_i32 s8, 0, 0x18000
	v_add_u32_e32 v144, s8, v236
	ds_read_b128 v[132:135], v144
	ds_read_b128 v[136:139], v144 offset:1024
	ds_read_b128 v[140:143], v144 offset:2048
	ds_read_b128 v[144:147], v144 offset:3072
	s_add_u32 s4, s4, s6
	s_addc_u32 s5, s5, s7
	s_mov_b32 m0, s91
	v_lshl_add_u64 v[200:201], s[4:5], 0, v[178:179]
	ds_read_b128 v[148:151], v239 offset:32768
	ds_read_b128 v[152:155], v239 offset:33792
	ds_read_b128 v[156:159], v239 offset:34816
	ds_read_b128 v[160:163], v239 offset:35840
	ds_read_b128 v[164:167], v239 offset:36864
	ds_read_b128 v[168:171], v239 offset:37888
	ds_read_b128 v[172:175], v239 offset:38912
	ds_read_b128 v[196:199], v239 offset:39936
	global_load_lds_dwordx4 v[200:201], off
	v_lshl_add_u64 v[200:201], s[4:5], 0, v[182:183]
	s_mov_b32 m0, s92
	s_nop 0
	global_load_lds_dwordx4 v[200:201], off
	s_add_i32 s4, 0, 0x1c000
	v_add_u32_e32 v212, s4, v236
	ds_read_b128 v[200:203], v212
	ds_read_b128 v[204:207], v212 offset:1024
	ds_read_b128 v[208:211], v212 offset:2048
	ds_read_b128 v[212:215], v212 offset:3072
	s_waitcnt vmcnt(8)
	s_waitcnt lgkmcnt(0)
	v_mfma_f32_16x16x32_bf16 v[126:129], v[132:135], v[148:151], v[126:129]
	v_mfma_f32_16x16x32_bf16 v[122:125], v[140:143], v[148:151], v[122:125]
	v_mfma_f32_16x16x32_bf16 v[110:113], v[132:135], v[156:159], v[110:113]
	v_mfma_f32_16x16x32_bf16 v[106:109], v[140:143], v[156:159], v[106:109]
	s_barrier
	s_setprio 1
	v_mfma_f32_16x16x32_bf16 v[94:97], v[132:135], v[164:167], v[94:97]
	v_mfma_f32_16x16x32_bf16 v[90:93], v[140:143], v[164:167], v[90:93]
	v_mfma_f32_16x16x32_bf16 v[78:81], v[132:135], v[172:175], v[78:81]
	v_mfma_f32_16x16x32_bf16 v[74:77], v[140:143], v[172:175], v[74:77]
	v_mfma_f32_16x16x32_bf16 v[126:129], v[136:139], v[152:155], v[126:129]
	v_mfma_f32_16x16x32_bf16 v[122:125], v[144:147], v[152:155], v[122:125]
	v_mfma_f32_16x16x32_bf16 v[110:113], v[136:139], v[160:163], v[110:113]
	v_mfma_f32_16x16x32_bf16 v[106:109], v[144:147], v[160:163], v[106:109]
	v_mfma_f32_16x16x32_bf16 v[94:97], v[136:139], v[168:171], v[94:97]
	v_mfma_f32_16x16x32_bf16 v[90:93], v[144:147], v[168:171], v[90:93]
	v_mfma_f32_16x16x32_bf16 v[78:81], v[136:139], v[196:199], v[78:81]
	v_mfma_f32_16x16x32_bf16 v[74:77], v[144:147], v[196:199], v[74:77]
	v_mfma_f32_16x16x32_bf16 v[118:121], v[200:203], v[148:151], v[118:121]
	v_mfma_f32_16x16x32_bf16 v[114:117], v[208:211], v[148:151], v[114:117]
	v_mfma_f32_16x16x32_bf16 v[102:105], v[200:203], v[156:159], v[102:105]
	v_mfma_f32_16x16x32_bf16 v[98:101], v[208:211], v[156:159], v[98:101]
	v_mfma_f32_16x16x32_bf16 v[86:89], v[200:203], v[164:167], v[86:89]
	v_mfma_f32_16x16x32_bf16 v[82:85], v[208:211], v[164:167], v[82:85]
	v_mfma_f32_16x16x32_bf16 v[70:73], v[200:203], v[172:175], v[70:73]
	v_mfma_f32_16x16x32_bf16 v[66:69], v[208:211], v[172:175], v[66:69]
	v_mfma_f32_16x16x32_bf16 v[118:121], v[204:207], v[152:155], v[118:121]
	v_mfma_f32_16x16x32_bf16 v[114:117], v[212:215], v[152:155], v[114:117]
	v_mfma_f32_16x16x32_bf16 v[102:105], v[204:207], v[160:163], v[102:105]
	v_mfma_f32_16x16x32_bf16 v[98:101], v[212:215], v[160:163], v[98:101]
	v_mfma_f32_16x16x32_bf16 v[86:89], v[204:207], v[168:171], v[86:89]
	v_mfma_f32_16x16x32_bf16 v[82:85], v[212:215], v[168:171], v[82:85]
	v_mfma_f32_16x16x32_bf16 v[70:73], v[204:207], v[196:199], v[70:73]
	v_mfma_f32_16x16x32_bf16 v[66:69], v[212:215], v[196:199], v[66:69]
	s_setprio 0
	s_barrier
; #define PG8_STAGE(bufoff, gbase, voff) do { _Pragma("unroll") for (int _i = 0; _i < 2; ++_i) \
;         __builtin_amdgcn_global_load_lds((const unsigned*)((const char*)(gbase) + (voff)[_i]), (LAS unsigned*)(lds + (bufoff) + ldsw + _i * 8192), 16, 0, 0); } while (0)
; #define PG8_LDA(dst, b, h) do { _Pragma("unroll") for (int m = 0; m < 4; ++m) _Pragma("unroll") for (int k = 0; k < 2; ++k) dst[m][k] = *(const LAS bf16x8*)(lds + PG8_SA(b, h) + aoff + m * 2048 + k * 1024); } while (0)
; #define PG8_LDB(dst, b, h) do { _Pragma("unroll") for (int n = 0; n < 2; ++n) _Pragma("unroll") for (int k = 0; k < 2; ++k) dst[n][k] = *(const LAS bf16x8*)(lds + PG8_SB(b, h) + boff + n * 2048 + k * 1024); } while (0)
; #define PG8_MMA(ai, bj, At, Bt) do { __builtin_amdgcn_s_setprio(1); _Pragma("unroll") for (int m = 0; m < 4; ++m) _Pragma("unroll") for (int n = 0; n < 2; ++n) _Pragma("unroll") for (int k = 0; k < 2; ++k) \
;         acc[ai][bj][m][n] = __builtin_amdgcn_mfma_f32_16x16x32_bf16(Bt[n][k], At[m][k], acc[ai][bj][m][n], 0, 0, 0); __builtin_amdgcn_s_setprio(0); } while (0)
; #define PG8_WAIT_V(n) asm volatile("s_waitcnt vmcnt(" #n ")" ::: "memory")
; #define PG8_WAIT_L(n) asm volatile("s_waitcnt lgkmcnt(" #n ")" ::: "memory")
; #define PG8_BAR __builtin_amdgcn_s_barrier()
; template <class Epi>
; __device__ __forceinline__ void gemm_phase(LAS unsigned char* lds, const Gemm g, const Sched& S, const Epi& E) {
;     ...
;             PG8_LDB(B1, 1, 1); PG8_STAGE(PG8_SB(1, 0), b3, voffB);
;             PG8_BAR; PG8_WAIT_L(0); PG8_MMA(0, 1, At, B1); PG8_BAR;
;             PG8_LDA(At, 1, 1); PG8_STAGE(PG8_SA(1, 0), a3, voffA);
;             PG8_BAR; PG8_WAIT_L(0); PG8_MMA(1, 0, At, B0); PG8_BAR; PG8_SCHED;
;             PG8_STAGE(PG8_SB(1, 1), b3 + hstepB, voffB);
;             PG8_WAIT_V(6); PG8_BAR; PG8_MMA(1, 1, At, B1); PG8_BAR;
;         }
;     __device__ __forceinline__ void operator()(const Acc& acc, const Unit& u, int wr, int wc, int fr, int fq, const Pre& pre) const {
;         const int tile = u.pn; int mode = 0; float scale0 = 1.f;
;         if (tile < 36) { const int tg = tile % 12; if (tg < 4) { mode = 1; scale0 = 0.08838834764831845f * LOG2E; } else if (tg < 8) mode = 1; }
;         else if (tile < 40) mode = 1;
;         else if (tile < 44) { mode = 1; scale0 = 0.08838834764831845f; }
;         else if (tile >= 52) mode = 2;
	s_add_i32 s5, s8, s88
	v_lshl_add_u64 v[176:177], v[176:177], 0, s[60:61]
	s_mov_b32 m0, s5
	s_nop 0
	global_load_lds_dwordx4 v[176:177], off
	v_lshl_add_u64 v[176:177], v[192:193], 0, s[60:61]
	s_add_i32 m0, s5, 0x2000
	s_nop 0
	global_load_lds_dwordx4 v[176:177], off
	s_mov_b32 m0, s93
	v_lshl_add_u64 v[176:177], v[194:195], 0, s[60:61]
	ds_read_b128 v[148:151], v239 offset:49152
	ds_read_b128 v[152:155], v239 offset:50176
	ds_read_b128 v[156:159], v239 offset:51200
	ds_read_b128 v[160:163], v239 offset:52224
	ds_read_b128 v[164:167], v239 offset:53248
	ds_read_b128 v[168:171], v239 offset:54272
	ds_read_b128 v[172:175], v239 offset:55296
	ds_read_b128 v[196:199], v239 offset:56320
	global_load_lds_dwordx4 v[176:177], off
	v_lshl_add_u64 v[176:177], v[216:217], 0, s[60:61]
	s_mov_b32 m0, s94
	s_nop 0
	global_load_lds_dwordx4 v[176:177], off
	s_add_i32 s4, s4, s88
	v_lshl_add_u64 v[176:177], v[222:223], 0, s[60:61]
	s_mov_b32 m0, s4
	s_nop 0
	global_load_lds_dwordx4 v[176:177], off
	v_lshl_add_u64 v[176:177], v[224:225], 0, s[60:61]
	s_add_i32 m0, s4, 0x2000
	s_nop 0
	global_load_lds_dwordx4 v[176:177], off
	s_waitcnt vmcnt(8)
	s_waitcnt lgkmcnt(0)
	v_mfma_f32_16x16x32_bf16 v[62:65], v[132:135], v[148:151], v[62:65]
	v_mfma_f32_16x16x32_bf16 v[58:61], v[140:143], v[148:151], v[58:61]
	v_mfma_f32_16x16x32_bf16 v[46:49], v[132:135], v[156:159], v[46:49]
	v_mfma_f32_16x16x32_bf16 v[42:45], v[140:143], v[156:159], v[42:45]
	s_barrier
	s_setprio 1
	v_mfma_f32_16x16x32_bf16 v[30:33], v[132:135], v[164:167], v[30:33]
	v_mfma_f32_16x16x32_bf16 v[26:29], v[140:143], v[164:167], v[26:29]
	v_mfma_f32_16x16x32_bf16 v[14:17], v[132:135], v[172:175], v[14:17]
	v_mfma_f32_16x16x32_bf16 v[10:13], v[140:143], v[172:175], v[10:13]
	v_mfma_f32_16x16x32_bf16 v[62:65], v[136:139], v[152:155], v[62:65]
	v_mfma_f32_16x16x32_bf16 v[58:61], v[144:147], v[152:155], v[58:61]
	v_mfma_f32_16x16x32_bf16 v[46:49], v[136:139], v[160:163], v[46:49]
	v_mfma_f32_16x16x32_bf16 v[42:45], v[144:147], v[160:163], v[42:45]
	v_mfma_f32_16x16x32_bf16 v[30:33], v[136:139], v[168:171], v[30:33]
	v_mfma_f32_16x16x32_bf16 v[26:29], v[144:147], v[168:171], v[26:29]
	v_mfma_f32_16x16x32_bf16 v[14:17], v[136:139], v[196:199], v[14:17]
	v_mfma_f32_16x16x32_bf16 v[10:13], v[144:147], v[196:199], v[10:13]
	v_mfma_f32_16x16x32_bf16 v[54:57], v[200:203], v[148:151], v[54:57]
	v_mfma_f32_16x16x32_bf16 v[50:53], v[208:211], v[148:151], v[50:53]
	v_mfma_f32_16x16x32_bf16 v[38:41], v[200:203], v[156:159], v[38:41]
	v_mfma_f32_16x16x32_bf16 v[34:37], v[208:211], v[156:159], v[34:37]
	v_mfma_f32_16x16x32_bf16 v[22:25], v[200:203], v[164:167], v[22:25]
	v_mfma_f32_16x16x32_bf16 v[18:21], v[208:211], v[164:167], v[18:21]
	v_mfma_f32_16x16x32_bf16 v[6:9], v[200:203], v[172:175], v[6:9]
	v_mfma_f32_16x16x32_bf16 v[2:5], v[208:211], v[172:175], v[2:5]
	v_mfma_f32_16x16x32_bf16 v[54:57], v[204:207], v[152:155], v[54:57]
	v_mfma_f32_16x16x32_bf16 v[50:53], v[212:215], v[152:155], v[50:53]
	v_mfma_f32_16x16x32_bf16 v[38:41], v[204:207], v[160:163], v[38:41]
	v_mfma_f32_16x16x32_bf16 v[34:37], v[212:215], v[160:163], v[34:37]
	v_mfma_f32_16x16x32_bf16 v[22:25], v[204:207], v[168:171], v[22:25]
	v_mfma_f32_16x16x32_bf16 v[18:21], v[212:215], v[168:171], v[18:21]
	v_mfma_f32_16x16x32_bf16 v[6:9], v[204:207], v[196:199], v[6:9]
	v_mfma_f32_16x16x32_bf16 v[2:5], v[212:215], v[196:199], v[2:5]
	s_setprio 0
	s_add_u32 s0, s0, 0x100
	s_addc_u32 s1, s1, 0
	s_add_u32 s34, s34, 0x100
	s_addc_u32 s35, s35, 0
	s_cmp_ge_u32 s14, s73
	s_mov_b32 s4, s14
	s_barrier
	s_cbranch_scc0 .LBB0_649
	s_cmp_gt_i32 s3, 35
	s_cbranch_scc0 .LBB0_652
	s_cmp_gt_u32 s3, 51
	s_cselect_b32 s8, 2, 0
	s_cmp_gt_u32 s3, 39
	s_cselect_b64 s[0:1], -1, 0
	s_cmp_lt_u32 s3, 44
	s_cselect_b64 s[14:15], -1, 0
	s_and_b64 s[4:5], s[14:15], exec
	s_cselect_b32 s4, 1, s8
	s_and_b64 vcc, s[0:1], s[14:15]
	v_mov_b32_e32 v132, 0x3db504f3
	v_cndmask_b32_e32 v240, 1.0, v132, vcc
	v_mov_b32_e32 v132, s4
	s_cbranch_execz .LBB0_653
	s_branch .LBB0_654

; #define PG8_STAGE(bufoff, gbase, voff) do { _Pragma("unroll") for (int _i = 0; _i < 2; ++_i) \
;         __builtin_amdgcn_global_load_lds((const unsigned*)((const char*)(gbase) + (voff)[_i]), (LAS unsigned*)(lds + (bufoff) + ldsw + _i * 8192), 16, 0, 0); } while (0)
; #define PG8_LDA(dst, b, h) do { _Pragma("unroll") for (int m = 0; m < 4; ++m) _Pragma("unroll") for (int k = 0; k < 2; ++k) dst[m][k] = *(const LAS bf16x8*)(lds + PG8_SA(b, h) + aoff + m * 2048 + k * 1024); } while (0)
; #define PG8_LDB(dst, b, h) do { _Pragma("unroll") for (int n = 0; n < 2; ++n) _Pragma("unroll") for (int k = 0; k < 2; ++k) dst[n][k] = *(const LAS bf16x8*)(lds + PG8_SB(b, h) + boff + n * 2048 + k * 1024); } while (0)
; #define PG8_MMA(ai, bj, At, Bt) do { __builtin_amdgcn_s_setprio(1); _Pragma("unroll") for (int m = 0; m < 4; ++m) _Pragma("unroll") for (int n = 0; n < 2; ++n) _Pragma("unroll") for (int k = 0; k < 2; ++k) \
;         acc[ai][bj][m][n] = __builtin_amdgcn_mfma_f32_16x16x32_bf16(Bt[n][k], At[m][k], acc[ai][bj][m][n], 0, 0, 0); __builtin_amdgcn_s_setprio(0); } while (0)
; #define PG8_WAIT_L(n) asm volatile("s_waitcnt lgkmcnt(" #n ")" ::: "memory")
; #define PG8_BAR __builtin_amdgcn_s_barrier()
; #define PG8_SCHED __builtin_amdgcn_sched_barrier(0)
; template <class Epi>
; __device__ __forceinline__ void gemm_phase(LAS unsigned char* lds, const Gemm g, const Sched& S, const Epi& E) {
;     ...
;         for (int t = 0; t < nt; t += 2) {
;             const bool last = (t == nt - 2);
;             const char* a1 = cA + (size_t)(t + 1) * kstep;
;             const char* a2 = last ? nA : cA + (size_t)(t + 2) * kstep; const char* b2 = last ? nB : cB + (size_t)(t + 2) * kstep;
;             const char* a3 = a2 + kstep; const char* b3 = b2 + kstep;
;             PG8_LDB(B0, 0, 0); PG8_SCHED; PG8_LDA(At, 0, 0); PG8_STAGE(PG8_SA(1, 1), a1 + hstepA, voffA);
;             PG8_WAIT_L(8); PG8_BAR; PG8_WAIT_L(0); PG8_MMA(0, 0, At, B0); PG8_BAR; PG8_SCHED;
;             PG8_LDB(B1, 0, 1); PG8_STAGE(PG8_SB(0, 0), b2, voffB);
;             PG8_BAR; PG8_WAIT_L(0); PG8_MMA(0, 1, At, B1); PG8_BAR;
;             PG8_LDA(At, 0, 1); PG8_STAGE(PG8_SA(0, 0), a2, voffA);
;             PG8_BAR; PG8_WAIT_L(0); PG8_MMA(1, 0, At, B0); PG8_BAR; PG8_SCHED;
.LBB0_825:
	s_add_i32 s86, s68, 2
	s_add_u32 s70, s4, 0x80
	s_addc_u32 s69, s5, 0
	s_add_i32 s87, 0, 0x10000
	v_add_u32_e32 v144, s87, v145
	ds_read_b128 v[152:155], v144
	ds_read_b128 v[156:159], v144 offset:1024
	ds_read_b128 v[160:163], v144 offset:2048
	ds_read_b128 v[164:167], v144 offset:3072
	s_cmp_eq_u32 s77, s68
	s_cselect_b32 s68, s59, s70
	s_cselect_b32 s69, s57, s69
	s_cselect_b32 s71, s82, s85
	s_cselect_b32 s70, s83, s84
	v_lshl_add_u64 v[192:193], s[4:5], 0, v[136:137]
	s_add_i32 m0, s33, 0xc000
	ds_read_b128 v[168:171], v151
	ds_read_b128 v[172:175], v151 offset:1024
	ds_read_b128 v[176:179], v151 offset:2048
	ds_read_b128 v[180:183], v151 offset:3072
	ds_read_b128 v[184:187], v151 offset:4096
	ds_read_b128 v[188:191], v151 offset:5120
	ds_read_b128 v[196:199], v151 offset:6144
	ds_read_b128 v[200:203], v151 offset:7168
	global_load_lds_dwordx4 v[192:193], off
	v_lshl_add_u64 v[192:193], s[4:5], 0, v[138:139]
	s_add_i32 m0, s33, 0xe000
	s_nop 0
	global_load_lds_dwordx4 v[192:193], off
	s_add_i32 s88, 0, 0x14000
	v_add_u32_e32 v144, s88, v145
	ds_read_b128 v[204:207], v144
	ds_read_b128 v[208:211], v144 offset:1024
	ds_read_b128 v[212:215], v144 offset:2048
	ds_read_b128 v[234:237], v144 offset:3072
	s_waitcnt vmcnt(8)
	s_waitcnt lgkmcnt(0)
	v_mfma_f32_16x16x32_bf16 v[126:129], v[152:155], v[168:171], v[126:129]
	v_mfma_f32_16x16x32_bf16 v[122:125], v[160:163], v[168:171], v[122:125]
	v_mfma_f32_16x16x32_bf16 v[110:113], v[152:155], v[176:179], v[110:113]
	v_mfma_f32_16x16x32_bf16 v[106:109], v[160:163], v[176:179], v[106:109]
	s_barrier
	s_setprio 1
	v_mfma_f32_16x16x32_bf16 v[94:97], v[152:155], v[184:187], v[94:97]
	v_mfma_f32_16x16x32_bf16 v[90:93], v[160:163], v[184:187], v[90:93]
	v_mfma_f32_16x16x32_bf16 v[78:81], v[152:155], v[196:199], v[78:81]
	v_mfma_f32_16x16x32_bf16 v[74:77], v[160:163], v[196:199], v[74:77]
	v_mfma_f32_16x16x32_bf16 v[126:129], v[156:159], v[172:175], v[126:129]
	v_mfma_f32_16x16x32_bf16 v[122:125], v[164:167], v[172:175], v[122:125]
	v_mfma_f32_16x16x32_bf16 v[110:113], v[156:159], v[180:183], v[110:113]
	v_mfma_f32_16x16x32_bf16 v[106:109], v[164:167], v[180:183], v[106:109]
	v_mfma_f32_16x16x32_bf16 v[94:97], v[156:159], v[188:191], v[94:97]
	v_mfma_f32_16x16x32_bf16 v[90:93], v[164:167], v[188:191], v[90:93]
	v_mfma_f32_16x16x32_bf16 v[78:81], v[156:159], v[200:203], v[78:81]
	v_mfma_f32_16x16x32_bf16 v[74:77], v[164:167], v[200:203], v[74:77]
	v_mfma_f32_16x16x32_bf16 v[118:121], v[204:207], v[168:171], v[118:121]
	v_mfma_f32_16x16x32_bf16 v[114:117], v[212:215], v[168:171], v[114:117]
	v_mfma_f32_16x16x32_bf16 v[102:105], v[204:207], v[176:179], v[102:105]
	v_mfma_f32_16x16x32_bf16 v[98:101], v[212:215], v[176:179], v[98:101]
	v_mfma_f32_16x16x32_bf16 v[86:89], v[204:207], v[184:187], v[86:89]
	v_mfma_f32_16x16x32_bf16 v[82:85], v[212:215], v[184:187], v[82:85]
	v_mfma_f32_16x16x32_bf16 v[70:73], v[204:207], v[196:199], v[70:73]
	v_mfma_f32_16x16x32_bf16 v[66:69], v[212:215], v[196:199], v[66:69]
	v_mfma_f32_16x16x32_bf16 v[118:121], v[208:211], v[172:175], v[118:121]
	v_mfma_f32_16x16x32_bf16 v[114:117], v[234:237], v[172:175], v[114:117]
	v_mfma_f32_16x16x32_bf16 v[102:105], v[208:211], v[180:183], v[102:105]
	v_mfma_f32_16x16x32_bf16 v[98:101], v[234:237], v[180:183], v[98:101]
	v_mfma_f32_16x16x32_bf16 v[86:89], v[208:211], v[188:191], v[86:89]
	v_mfma_f32_16x16x32_bf16 v[82:85], v[234:237], v[188:191], v[82:85]
	v_mfma_f32_16x16x32_bf16 v[70:73], v[208:211], v[200:203], v[70:73]
	v_mfma_f32_16x16x32_bf16 v[66:69], v[234:237], v[200:203], v[66:69]
	s_setprio 0
	s_barrier
	s_add_i32 s87, s87, s51
	v_lshl_add_u64 v[192:193], s[70:71], 0, v[0:1]
	s_mov_b32 m0, s87
	s_nop 0
	global_load_lds_dwordx4 v[192:193], off
	v_lshl_add_u64 v[216:217], s[70:71], 0, v[134:135]
	s_add_i32 m0, s87, 0x2000
	s_nop 0
	global_load_lds_dwordx4 v[216:217], off
	s_mov_b32 m0, s33
	v_lshl_add_u64 v[222:223], s[68:69], 0, v[130:131]
	ds_read_b128 v[168:171], v151 offset:16384
	ds_read_b128 v[172:175], v151 offset:17408
	ds_read_b128 v[176:179], v151 offset:18432
	ds_read_b128 v[180:183], v151 offset:19456
	ds_read_b128 v[184:187], v151 offset:20480
	ds_read_b128 v[188:191], v151 offset:21504
	ds_read_b128 v[196:199], v151 offset:22528
	ds_read_b128 v[200:203], v151 offset:23552
	global_load_lds_dwordx4 v[222:223], off
	v_lshl_add_u64 v[224:225], s[68:69], 0, v[132:133]
	s_mov_b32 m0, s48
	s_nop 0
	global_load_lds_dwordx4 v[224:225], off
	s_add_u32 s70, s70, s14
	s_addc_u32 s71, s71, s15
	s_add_i32 s87, s88, s51
	v_lshl_add_u64 v[226:227], s[70:71], 0, v[0:1]
	s_mov_b32 m0, s87
	v_lshl_add_u64 v[228:229], s[70:71], 0, v[134:135]
	global_load_lds_dwordx4 v[226:227], off
	s_add_i32 m0, s87, 0x2000
	s_nop 0
	global_load_lds_dwordx4 v[228:229], off
	s_waitcnt vmcnt(8)
	s_waitcnt lgkmcnt(0)
	v_mfma_f32_16x16x32_bf16 v[62:65], v[152:155], v[168:171], v[62:65]
	v_mfma_f32_16x16x32_bf16 v[58:61], v[160:163], v[168:171], v[58:61]
	v_mfma_f32_16x16x32_bf16 v[46:49], v[152:155], v[176:179], v[46:49]
	v_mfma_f32_16x16x32_bf16 v[42:45], v[160:163], v[176:179], v[42:45]
	s_barrier
; #define PG8_STAGE(bufoff, gbase, voff) do { _Pragma("unroll") for (int _i = 0; _i < 2; ++_i) \
;         __builtin_amdgcn_global_load_lds((const unsigned*)((const char*)(gbase) + (voff)[_i]), (LAS unsigned*)(lds + (bufoff) + ldsw + _i * 8192), 16, 0, 0); } while (0)
; #define PG8_LDA(dst, b, h) do { _Pragma("unroll") for (int m = 0; m < 4; ++m) _Pragma("unroll") for (int k = 0; k < 2; ++k) dst[m][k] = *(const LAS bf16x8*)(lds + PG8_SA(b, h) + aoff + m * 2048 + k * 1024); } while (0)
; #define PG8_LDB(dst, b, h) do { _Pragma("unroll") for (int n = 0; n < 2; ++n) _Pragma("unroll") for (int k = 0; k < 2; ++k) dst[n][k] = *(const LAS bf16x8*)(lds + PG8_SB(b, h) + boff + n * 2048 + k * 1024); } while (0)
; #define PG8_MMA(ai, bj, At, Bt) do { __builtin_amdgcn_s_setprio(1); _Pragma("unroll") for (int m = 0; m < 4; ++m) _Pragma("unroll") for (int n = 0; n < 2; ++n) _Pragma("unroll") for (int k = 0; k < 2; ++k) \
;         acc[ai][bj][m][n] = __builtin_amdgcn_mfma_f32_16x16x32_bf16(Bt[n][k], At[m][k], acc[ai][bj][m][n], 0, 0, 0); __builtin_amdgcn_s_setprio(0); } while (0)
; #define PG8_WAIT_V(n) asm volatile("s_waitcnt vmcnt(" #n ")" ::: "memory")
; #define PG8_WAIT_L(n) asm volatile("s_waitcnt lgkmcnt(" #n ")" ::: "memory")
; #define PG8_BAR __builtin_amdgcn_s_barrier()
; #define PG8_SCHED __builtin_amdgcn_sched_barrier(0)
; template <class Epi>
; __device__ __forceinline__ void gemm_phase(LAS unsigned char* lds, const Gemm g, const Sched& S, const Epi& E) {
;     ...
;             PG8_BAR; PG8_WAIT_L(0); PG8_MMA(1, 0, At, B0); PG8_BAR; PG8_SCHED;
;             PG8_STAGE(PG8_SB(0, 1), b2 + hstepB, voffB);
;             PG8_WAIT_V(6); PG8_BAR; PG8_MMA(1, 1, At, B1); PG8_BAR;
;             PG8_LDB(B0, 1, 0); PG8_SCHED; PG8_LDA(At, 1, 0); PG8_STAGE(PG8_SA(0, 1), a2 + hstepA, voffA);
;             PG8_WAIT_L(8); PG8_BAR; PG8_WAIT_L(0); PG8_MMA(0, 0, At, B0); PG8_BAR; PG8_SCHED;
;             PG8_LDB(B1, 1, 1); PG8_STAGE(PG8_SB(1, 0), b3, voffB);
;             PG8_BAR; PG8_WAIT_L(0); PG8_MMA(0, 1, At, B1); PG8_BAR;
;             PG8_LDA(At, 1, 1); PG8_STAGE(PG8_SA(1, 0), a3, voffA);
;             PG8_BAR; PG8_WAIT_L(0); PG8_MMA(1, 0, At, B0); PG8_BAR; PG8_SCHED;
	s_setprio 1
	v_mfma_f32_16x16x32_bf16 v[30:33], v[152:155], v[184:187], v[30:33]
	v_mfma_f32_16x16x32_bf16 v[26:29], v[160:163], v[184:187], v[26:29]
	v_mfma_f32_16x16x32_bf16 v[14:17], v[152:155], v[196:199], v[14:17]
	v_mfma_f32_16x16x32_bf16 v[10:13], v[160:163], v[196:199], v[10:13]
	v_mfma_f32_16x16x32_bf16 v[62:65], v[156:159], v[172:175], v[62:65]
	v_mfma_f32_16x16x32_bf16 v[58:61], v[164:167], v[172:175], v[58:61]
	v_mfma_f32_16x16x32_bf16 v[46:49], v[156:159], v[180:183], v[46:49]
	v_mfma_f32_16x16x32_bf16 v[42:45], v[164:167], v[180:183], v[42:45]
	v_mfma_f32_16x16x32_bf16 v[30:33], v[156:159], v[188:191], v[30:33]
	v_mfma_f32_16x16x32_bf16 v[26:29], v[164:167], v[188:191], v[26:29]
	v_mfma_f32_16x16x32_bf16 v[14:17], v[156:159], v[200:203], v[14:17]
	v_mfma_f32_16x16x32_bf16 v[10:13], v[164:167], v[200:203], v[10:13]
	v_mfma_f32_16x16x32_bf16 v[54:57], v[204:207], v[168:171], v[54:57]
	v_mfma_f32_16x16x32_bf16 v[50:53], v[212:215], v[168:171], v[50:53]
	v_mfma_f32_16x16x32_bf16 v[38:41], v[204:207], v[176:179], v[38:41]
	v_mfma_f32_16x16x32_bf16 v[34:37], v[212:215], v[176:179], v[34:37]
	v_mfma_f32_16x16x32_bf16 v[22:25], v[204:207], v[184:187], v[22:25]
	v_mfma_f32_16x16x32_bf16 v[18:21], v[212:215], v[184:187], v[18:21]
	v_mfma_f32_16x16x32_bf16 v[6:9], v[204:207], v[196:199], v[6:9]
	v_mfma_f32_16x16x32_bf16 v[2:5], v[212:215], v[196:199], v[2:5]
	v_mfma_f32_16x16x32_bf16 v[54:57], v[208:211], v[172:175], v[54:57]
	v_mfma_f32_16x16x32_bf16 v[50:53], v[234:237], v[172:175], v[50:53]
	v_mfma_f32_16x16x32_bf16 v[38:41], v[208:211], v[180:183], v[38:41]
	v_mfma_f32_16x16x32_bf16 v[34:37], v[234:237], v[180:183], v[34:37]
	v_mfma_f32_16x16x32_bf16 v[22:25], v[208:211], v[188:191], v[22:25]
	v_mfma_f32_16x16x32_bf16 v[18:21], v[234:237], v[188:191], v[18:21]
	v_mfma_f32_16x16x32_bf16 v[6:9], v[208:211], v[200:203], v[6:9]
	v_mfma_f32_16x16x32_bf16 v[2:5], v[234:237], v[200:203], v[2:5]
	s_setprio 0
	s_barrier
	s_add_i32 s70, 0, 0x18000
	v_add_u32_e32 v144, s70, v145
	ds_read_b128 v[152:155], v144
	ds_read_b128 v[156:159], v144 offset:1024
	ds_read_b128 v[160:163], v144 offset:2048
	ds_read_b128 v[164:167], v144 offset:3072
	s_add_u32 s68, s68, s6
	s_addc_u32 s69, s69, s7
	s_mov_b32 m0, s58
	v_lshl_add_u64 v[204:205], s[68:69], 0, v[130:131]
	ds_read_b128 v[168:171], v151 offset:32768
	ds_read_b128 v[172:175], v151 offset:33792
	ds_read_b128 v[176:179], v151 offset:34816
	ds_read_b128 v[180:183], v151 offset:35840
	ds_read_b128 v[184:187], v151 offset:36864
	ds_read_b128 v[188:191], v151 offset:37888
	ds_read_b128 v[196:199], v151 offset:38912
	ds_read_b128 v[200:203], v151 offset:39936
	global_load_lds_dwordx4 v[204:205], off
	v_lshl_add_u64 v[204:205], s[68:69], 0, v[132:133]
	s_mov_b32 m0, s72
	s_nop 0
	global_load_lds_dwordx4 v[204:205], off
	s_add_i32 s68, 0, 0x1c000
	v_add_u32_e32 v144, s68, v145
	ds_read_b128 v[204:207], v144
	ds_read_b128 v[208:211], v144 offset:1024
	ds_read_b128 v[212:215], v144 offset:2048
	ds_read_b128 v[234:237], v144 offset:3072
	s_waitcnt vmcnt(8)
	s_waitcnt lgkmcnt(0)
	v_mfma_f32_16x16x32_bf16 v[126:129], v[152:155], v[168:171], v[126:129]
	v_mfma_f32_16x16x32_bf16 v[122:125], v[160:163], v[168:171], v[122:125]
	v_mfma_f32_16x16x32_bf16 v[110:113], v[152:155], v[176:179], v[110:113]
	v_mfma_f32_16x16x32_bf16 v[106:109], v[160:163], v[176:179], v[106:109]
	s_barrier
	s_setprio 1
	v_mfma_f32_16x16x32_bf16 v[94:97], v[152:155], v[184:187], v[94:97]
	v_mfma_f32_16x16x32_bf16 v[90:93], v[160:163], v[184:187], v[90:93]
	v_mfma_f32_16x16x32_bf16 v[78:81], v[152:155], v[196:199], v[78:81]
	v_mfma_f32_16x16x32_bf16 v[74:77], v[160:163], v[196:199], v[74:77]
	v_mfma_f32_16x16x32_bf16 v[126:129], v[156:159], v[172:175], v[126:129]
	v_mfma_f32_16x16x32_bf16 v[122:125], v[164:167], v[172:175], v[122:125]
	v_mfma_f32_16x16x32_bf16 v[110:113], v[156:159], v[180:183], v[110:113]
	v_mfma_f32_16x16x32_bf16 v[106:109], v[164:167], v[180:183], v[106:109]
	v_mfma_f32_16x16x32_bf16 v[94:97], v[156:159], v[188:191], v[94:97]
	v_mfma_f32_16x16x32_bf16 v[90:93], v[164:167], v[188:191], v[90:93]
	v_mfma_f32_16x16x32_bf16 v[78:81], v[156:159], v[200:203], v[78:81]
	v_mfma_f32_16x16x32_bf16 v[74:77], v[164:167], v[200:203], v[74:77]
	v_mfma_f32_16x16x32_bf16 v[118:121], v[204:207], v[168:171], v[118:121]
	v_mfma_f32_16x16x32_bf16 v[114:117], v[212:215], v[168:171], v[114:117]
	v_mfma_f32_16x16x32_bf16 v[102:105], v[204:207], v[176:179], v[102:105]
	v_mfma_f32_16x16x32_bf16 v[98:101], v[212:215], v[176:179], v[98:101]
	v_mfma_f32_16x16x32_bf16 v[86:89], v[204:207], v[184:187], v[86:89]
	v_mfma_f32_16x16x32_bf16 v[82:85], v[212:215], v[184:187], v[82:85]
	v_mfma_f32_16x16x32_bf16 v[70:73], v[204:207], v[196:199], v[70:73]
	v_mfma_f32_16x16x32_bf16 v[66:69], v[212:215], v[196:199], v[66:69]
	v_mfma_f32_16x16x32_bf16 v[118:121], v[208:211], v[172:175], v[118:121]
	v_mfma_f32_16x16x32_bf16 v[114:117], v[234:237], v[172:175], v[114:117]
	v_mfma_f32_16x16x32_bf16 v[102:105], v[208:211], v[180:183], v[102:105]
	v_mfma_f32_16x16x32_bf16 v[98:101], v[234:237], v[180:183], v[98:101]
	v_mfma_f32_16x16x32_bf16 v[86:89], v[208:211], v[188:191], v[86:89]
	v_mfma_f32_16x16x32_bf16 v[82:85], v[234:237], v[188:191], v[82:85]
	v_mfma_f32_16x16x32_bf16 v[70:73], v[208:211], v[200:203], v[70:73]
	v_mfma_f32_16x16x32_bf16 v[66:69], v[234:237], v[200:203], v[66:69]
	s_setprio 0
	s_barrier
; __device__ __forceinline__ float silu_f(float x) { return x * __builtin_amdgcn_rcpf(1.f + __builtin_amdgcn_exp2f(-LOG2E * x)); }
; __device__ __forceinline__ float pre_get(const Pre& p, int ai, int m, int fr) { return __shfl(p.v[ai], m * 16 + fr); }
; __device__ __forceinline__ float rstd_pre(const float* ss, float v) { return ss ? rsqrtf(v * (1.0f / 2048.0f) + 1e-6f) : 1.0f; }
; #define PG8_STAGE(bufoff, gbase, voff) do { _Pragma("unroll") for (int _i = 0; _i < 2; ++_i) \
;         __builtin_amdgcn_global_load_lds((const unsigned*)((const char*)(gbase) + (voff)[_i]), (LAS unsigned*)(lds + (bufoff) + ldsw + _i * 8192), 16, 0, 0); } while (0)
; #define PG8_LDA(dst, b, h) do { _Pragma("unroll") for (int m = 0; m < 4; ++m) _Pragma("unroll") for (int k = 0; k < 2; ++k) dst[m][k] = *(const LAS bf16x8*)(lds + PG8_SA(b, h) + aoff + m * 2048 + k * 1024); } while (0)
; #define PG8_WAIT_V(n) asm volatile("s_waitcnt vmcnt(" #n ")" ::: "memory")
; #define PG8_BAR __builtin_amdgcn_s_barrier()
; template <class Epi>
; __device__ __forceinline__ void gemm_phase(LAS unsigned char* lds, const Gemm g, const Sched& S, const Epi& E) {
;     ...
;             PG8_LDB(B1, 1, 1); PG8_STAGE(PG8_SB(1, 0), b3, voffB);
;             PG8_BAR; PG8_WAIT_L(0); PG8_MMA(0, 1, At, B1); PG8_BAR;
;             PG8_LDA(At, 1, 1); PG8_STAGE(PG8_SA(1, 0), a3, voffA);
;             PG8_BAR; PG8_WAIT_L(0); PG8_MMA(1, 0, At, B0); PG8_BAR; PG8_SCHED;
;             PG8_STAGE(PG8_SB(1, 1), b3 + hstepB, voffB);
;             PG8_WAIT_V(6); PG8_BAR; PG8_MMA(1, 1, At, B1); PG8_BAR;
;         }
;     __device__ __forceinline__ void operator()(const Acc& acc, const Unit& u, int wr, int wc, int fr, int fq, const Pre& pre) const {
;         const int row0 = u.pm * 256 + wr * 64 + fr, col0 = u.pn * 128 + wc * 32 + 8 * fq;
;         float rsq[2][4];
; #pragma unroll
;         for (int ai = 0; ai < 2; ++ai)
; #pragma unroll
;             for (int m = 0; m < 4; ++m) rsq[ai][m] = rstd_pre(ss, pre_get(pre, ai, m, fr));
; #pragma unroll
;         for (int ai = 0; ai < 2; ++ai)
; #pragma unroll
;             for (int m = 0; m < 4; ++m) {
;                 f32x4 v0, v1; const float rs = rsq[ai][m];
; #pragma unroll
;                 for (int e = 0; e < 4; ++e) { v0[e] = silu_f(acc[ai][0][m][0][e] * rs) * (acc[ai][1][m][0][e] * rs); v1[e] = silu_f(acc[ai][0][m][1][e] * rs) * (acc[ai][1][m][1][e] * rs); }
	s_add_i32 s69, s70, s51
	v_lshl_add_u64 v[192:193], v[192:193], 0, s[60:61]
	s_mov_b32 m0, s69
	s_nop 0
	global_load_lds_dwordx4 v[192:193], off
	v_lshl_add_u64 v[192:193], v[216:217], 0, s[60:61]
	s_add_i32 m0, s69, 0x2000
	s_nop 0
	global_load_lds_dwordx4 v[192:193], off
	s_mov_b32 m0, s75
	v_lshl_add_u64 v[192:193], v[222:223], 0, s[60:61]
	ds_read_b128 v[168:171], v151 offset:49152
	ds_read_b128 v[172:175], v151 offset:50176
	ds_read_b128 v[176:179], v151 offset:51200
	ds_read_b128 v[180:183], v151 offset:52224
	ds_read_b128 v[184:187], v151 offset:53248
	ds_read_b128 v[188:191], v151 offset:54272
	ds_read_b128 v[196:199], v151 offset:55296
	ds_read_b128 v[200:203], v151 offset:56320
	global_load_lds_dwordx4 v[192:193], off
	v_lshl_add_u64 v[192:193], v[224:225], 0, s[60:61]
	s_mov_b32 m0, s76
	s_nop 0
	global_load_lds_dwordx4 v[192:193], off
	s_add_i32 s68, s68, s51
	v_lshl_add_u64 v[192:193], v[226:227], 0, s[60:61]
	s_mov_b32 m0, s68
	s_nop 0
	global_load_lds_dwordx4 v[192:193], off
	v_lshl_add_u64 v[192:193], v[228:229], 0, s[60:61]
	s_add_i32 m0, s68, 0x2000
	s_nop 0
	global_load_lds_dwordx4 v[192:193], off
	s_waitcnt vmcnt(8)
	s_waitcnt lgkmcnt(0)
	v_mfma_f32_16x16x32_bf16 v[62:65], v[152:155], v[168:171], v[62:65]
	v_mfma_f32_16x16x32_bf16 v[58:61], v[160:163], v[168:171], v[58:61]
	v_mfma_f32_16x16x32_bf16 v[46:49], v[152:155], v[176:179], v[46:49]
	v_mfma_f32_16x16x32_bf16 v[42:45], v[160:163], v[176:179], v[42:45]
	s_barrier
	s_setprio 1
	v_mfma_f32_16x16x32_bf16 v[30:33], v[152:155], v[184:187], v[30:33]
	v_mfma_f32_16x16x32_bf16 v[26:29], v[160:163], v[184:187], v[26:29]
	v_mfma_f32_16x16x32_bf16 v[14:17], v[152:155], v[196:199], v[14:17]
	v_mfma_f32_16x16x32_bf16 v[10:13], v[160:163], v[196:199], v[10:13]
	v_mfma_f32_16x16x32_bf16 v[62:65], v[156:159], v[172:175], v[62:65]
	v_mfma_f32_16x16x32_bf16 v[58:61], v[164:167], v[172:175], v[58:61]
	v_mfma_f32_16x16x32_bf16 v[46:49], v[156:159], v[180:183], v[46:49]
	v_mfma_f32_16x16x32_bf16 v[42:45], v[164:167], v[180:183], v[42:45]
	v_mfma_f32_16x16x32_bf16 v[30:33], v[156:159], v[188:191], v[30:33]
	v_mfma_f32_16x16x32_bf16 v[26:29], v[164:167], v[188:191], v[26:29]
	v_mfma_f32_16x16x32_bf16 v[14:17], v[156:159], v[200:203], v[14:17]
	v_mfma_f32_16x16x32_bf16 v[10:13], v[164:167], v[200:203], v[10:13]
	v_mfma_f32_16x16x32_bf16 v[54:57], v[204:207], v[168:171], v[54:57]
	v_mfma_f32_16x16x32_bf16 v[50:53], v[212:215], v[168:171], v[50:53]
	v_mfma_f32_16x16x32_bf16 v[38:41], v[204:207], v[176:179], v[38:41]
	v_mfma_f32_16x16x32_bf16 v[34:37], v[212:215], v[176:179], v[34:37]
	v_mfma_f32_16x16x32_bf16 v[22:25], v[204:207], v[184:187], v[22:25]
	v_mfma_f32_16x16x32_bf16 v[18:21], v[212:215], v[184:187], v[18:21]
	v_mfma_f32_16x16x32_bf16 v[6:9], v[204:207], v[196:199], v[6:9]
	v_mfma_f32_16x16x32_bf16 v[2:5], v[212:215], v[196:199], v[2:5]
	v_mfma_f32_16x16x32_bf16 v[54:57], v[208:211], v[172:175], v[54:57]
	v_mfma_f32_16x16x32_bf16 v[50:53], v[234:237], v[172:175], v[50:53]
	v_mfma_f32_16x16x32_bf16 v[38:41], v[208:211], v[180:183], v[38:41]
	v_mfma_f32_16x16x32_bf16 v[34:37], v[234:237], v[180:183], v[34:37]
	v_mfma_f32_16x16x32_bf16 v[22:25], v[208:211], v[188:191], v[22:25]
	v_mfma_f32_16x16x32_bf16 v[18:21], v[234:237], v[188:191], v[18:21]
	v_mfma_f32_16x16x32_bf16 v[6:9], v[208:211], v[200:203], v[6:9]
	v_mfma_f32_16x16x32_bf16 v[2:5], v[234:237], v[200:203], v[2:5]
	s_setprio 0
	s_add_u32 s4, s4, 0x100
	s_addc_u32 s5, s5, 0
	s_add_u32 s84, s84, 0x100
	s_addc_u32 s85, s85, 0
	s_cmp_ge_u32 s86, s73
	s_mov_b32 s68, s86
	s_barrier
	s_cbranch_scc0 .LBB0_825
	v_and_or_b32 v144, v220, 64, v141
	v_lshlrev_b32_e32 v160, 2, v144
	ds_bpermute_b32 v155, v160, v142
	ds_bpermute_b32 v154, v160, v142 offset:64
	s_mov_b32 s4, 0x358637bd
	v_mov_b64_e32 v[156:157], s[4:5]
	s_mov_b32 s8, 0x3a000000
	v_lshl_add_u32 v153, s81, 8, v143
	s_waitcnt lgkmcnt(0)
	v_pk_fma_f32 v[158:159], v[154:155], s[8:9], v[156:157] op_sel_hi:[1,0,0]
	s_mov_b32 s81, s80
	v_mul_f32_e32 v144, 0x4b800000, v159
	v_cmp_gt_f32_e64 s[4:5], s97, v159
	v_cmp_gt_f32_e32 vcc, s97, v158
	s_mov_b64 s[68:69], s[66:67]
	v_cndmask_b32_e64 v144, v159, v144, s[4:5]
	v_rsq_f32_e32 v144, v144
	ds_bpermute_b32 v159, v160, v142 offset:128
	v_mul_f32_e32 v146, 0x45800000, v144
	v_cndmask_b32_e64 v144, v144, v146, s[4:5]
	v_cndmask_b32_e64 v154, v144, 1.0, s[34:35]
	v_mul_f32_e32 v144, 0x4b800000, v158
	v_cndmask_b32_e32 v144, v158, v144, vcc
	ds_bpermute_b32 v158, v160, v142 offset:192
	v_rsq_f32_e32 v144, v144
	s_waitcnt lgkmcnt(0)
	v_pk_fma_f32 v[158:159], v[158:159], s[8:9], v[156:157] op_sel_hi:[1,0,0]
	s_nop 0
	v_mul_f32_e32 v142, 0x4b800000, v159
	v_cmp_gt_f32_e64 s[4:5], s97, v159
	v_mul_f32_e32 v146, 0x45800000, v144
	v_cndmask_b32_e32 v144, v144, v146, vcc
	v_cndmask_b32_e64 v142, v159, v142, s[4:5]
	v_rsq_f32_e32 v142, v142
	v_cndmask_b32_e64 v152, v144, 1.0, s[34:35]
	v_cmp_gt_f32_e32 vcc, s97, v158
	ds_bpermute_b32 v159, v160, v140
	v_mul_f32_e32 v144, 0x45800000, v142
	v_cndmask_b32_e64 v142, v142, v144, s[4:5]
	v_cndmask_b32_e64 v150, v142, 1.0, s[34:35]
	v_mul_f32_e32 v142, 0x4b800000, v158
	v_cndmask_b32_e32 v142, v158, v142, vcc
	v_rsq_f32_e32 v142, v142
	ds_bpermute_b32 v158, v160, v140 offset:64
	v_pk_mul_f32 v[110:111], v[110:111], v[152:153] op_sel_hi:[1,0]
	v_pk_mul_f32 v[102:103], v[102:103], v[152:153] op_sel_hi:[1,0]
	v_mul_f32_e32 v144, 0x45800000, v142
	v_cndmask_b32_e32 v142, v142, v144, vcc
	s_waitcnt lgkmcnt(0)
; __device__ __forceinline__ float silu_f(float x) { return x * __builtin_amdgcn_rcpf(1.f + __builtin_amdgcn_exp2f(-LOG2E * x)); }
; __device__ __forceinline__ u32x4 pk8(const f32x4 a, const f32x4 b) { u32x4 w; w.x = pk2(a[0], a[1]); w.y = pk2(a[2], a[3]); w.z = pk2(b[0], b[1]); w.w = pk2(b[2], b[3]); return w; }
; __device__ __forceinline__ float pre_get(const Pre& p, int ai, int m, int fr) { return __shfl(p.v[ai], m * 16 + fr); }
; __device__ __forceinline__ float rstd_pre(const float* ss, float v) { return ss ? rsqrtf(v * (1.0f / 2048.0f) + 1e-6f) : 1.0f; }
;     __device__ __forceinline__ void operator()(const Acc& acc, const Unit& u, int wr, int wc, int fr, int fq, const Pre& pre) const {
;         const int row0 = u.pm * 256 + wr * 64 + fr, col0 = u.pn * 128 + wc * 32 + 8 * fq;
;         float rsq[2][4];
; #pragma unroll
;         for (int ai = 0; ai < 2; ++ai)
; #pragma unroll
;             for (int m = 0; m < 4; ++m) rsq[ai][m] = rstd_pre(ss, pre_get(pre, ai, m, fr));
; #pragma unroll
;         for (int ai = 0; ai < 2; ++ai)
; #pragma unroll
;             for (int m = 0; m < 4; ++m) {
;                 f32x4 v0, v1; const float rs = rsq[ai][m];
; #pragma unroll
;                 for (int e = 0; e < 4; ++e) { v0[e] = silu_f(acc[ai][0][m][0][e] * rs) * (acc[ai][1][m][0][e] * rs); v1[e] = silu_f(acc[ai][0][m][1][e] * rs) * (acc[ai][1][m][1][e] * rs); }
;                 *(u32x4*)(O + (size_t)(row0 + ai * 128 + m * 16) * ldc + col0) = pk8(v0, v1);
	v_pk_fma_f32 v[158:159], v[158:159], s[8:9], v[156:157] op_sel_hi:[1,0,0]
	v_cndmask_b32_e64 v148, v142, 1.0, s[34:35]
	v_mul_f32_e32 v142, 0x4b800000, v159
	v_cmp_gt_f32_e64 s[4:5], s97, v159
	v_cmp_gt_f32_e32 vcc, s97, v158
	v_pk_mul_f32 v[106:107], v[106:107], v[152:153] op_sel_hi:[1,0]
	v_cndmask_b32_e64 v142, v159, v142, s[4:5]
	v_rsq_f32_e32 v142, v142
	ds_bpermute_b32 v159, v160, v140 offset:128
	v_pk_mul_f32 v[98:99], v[98:99], v[152:153] op_sel_hi:[1,0]
	v_pk_mul_f32 v[104:105], v[104:105], v[152:153] op_sel_hi:[1,0]
	v_mul_f32_e32 v144, 0x45800000, v142
	v_cndmask_b32_e64 v142, v142, v144, s[4:5]
	v_cndmask_b32_e64 v146, v142, 1.0, s[34:35]
	v_mul_f32_e32 v142, 0x4b800000, v158
	v_cndmask_b32_e32 v142, v158, v142, vcc
	ds_bpermute_b32 v158, v160, v140 offset:192
	v_rsq_f32_e32 v142, v142
	v_pk_mul_f32 v[100:101], v[100:101], v[152:153] op_sel_hi:[1,0]
	v_pk_mul_f32 v[94:95], v[94:95], v[150:151] op_sel_hi:[1,0]
	v_pk_mul_f32 v[86:87], v[86:87], v[150:151] op_sel_hi:[1,0]
	s_waitcnt lgkmcnt(0)
	v_pk_fma_f32 v[156:157], v[158:159], s[8:9], v[156:157] op_sel_hi:[1,0,0]
	v_mul_f32_e32 v144, 0x45800000, v142
	v_mul_f32_e32 v140, 0x4b800000, v157
	v_cmp_gt_f32_e64 s[4:5], s97, v157
	v_cndmask_b32_e32 v142, v142, v144, vcc
	v_cndmask_b32_e64 v144, v142, 1.0, s[34:35]
	v_cndmask_b32_e64 v140, v157, v140, s[4:5]
	v_rsq_f32_e32 v140, v140
	v_cmp_gt_f32_e32 vcc, s97, v156
	v_pk_mul_f32 v[90:91], v[90:91], v[150:151] op_sel_hi:[1,0]
	v_pk_mul_f32 v[82:83], v[82:83], v[150:151] op_sel_hi:[1,0]
	v_mul_f32_e32 v142, 0x45800000, v140
	v_cndmask_b32_e64 v140, v140, v142, s[4:5]
	v_cndmask_b32_e64 v142, v140, 1.0, s[34:35]
	v_mul_f32_e32 v140, 0x4b800000, v156
	v_cndmask_b32_e32 v140, v156, v140, vcc
	v_rsq_f32_e32 v140, v140
	v_lshl_or_b32 v156, s55, 7, v149
	v_ashrrev_i32_e32 v157, 31, v156
	v_pk_mul_f32 v[88:89], v[88:89], v[150:151] op_sel_hi:[1,0]
	v_mul_f32_e32 v155, 0x45800000, v140
	v_pk_mul_f32 v[126:127], v[126:127], v[154:155] op_sel_hi:[1,0]
	v_cndmask_b32_e32 v140, v140, v155, vcc
	v_mul_f32_e32 v155, 0xbfb8aa3b, v126
	v_exp_f32_e32 v155, v155
	v_pk_mul_f32 v[84:85], v[84:85], v[150:151] op_sel_hi:[1,0]
	v_pk_mul_f32 v[78:79], v[78:79], v[148:149] op_sel_hi:[1,0]
	v_pk_mul_f32 v[70:71], v[70:71], v[148:149] op_sel_hi:[1,0]
	v_add_f32_e32 v155, 1.0, v155
	v_rcp_f32_e32 v158, v155
	v_mul_f32_e32 v155, 0xbfb8aa3b, v127
	v_exp_f32_e32 v155, v155
	v_pk_mul_f32 v[74:75], v[74:75], v[148:149] op_sel_hi:[1,0]
	v_pk_mul_f32 v[66:67], v[66:67], v[148:149] op_sel_hi:[1,0]
	v_pk_mul_f32 v[72:73], v[72:73], v[148:149] op_sel_hi:[1,0]
	v_add_f32_e32 v155, 1.0, v155
	v_rcp_f32_e32 v159, v155
	v_pk_mul_f32 v[118:119], v[118:119], v[154:155] op_sel_hi:[1,0]
	v_pk_mul_f32 v[122:123], v[122:123], v[154:155] op_sel_hi:[1,0]
	v_pk_mul_f32 v[114:115], v[114:115], v[154:155] op_sel_hi:[1,0]
	v_pk_mul_f32 v[126:127], v[126:127], v[158:159]
	v_pk_mul_f32 v[120:121], v[120:121], v[154:155] op_sel_hi:[1,0]
	v_pk_mul_f32 v[118:119], v[118:119], v[126:127]
	v_mul_f32_e32 v126, 0xbfb8aa3b, v122
	v_mul_f32_e32 v127, 0xbfb8aa3b, v123
	v_exp_f32_e32 v126, v126
	v_exp_f32_e32 v127, v127
	v_pk_mul_f32 v[116:117], v[116:117], v[154:155] op_sel_hi:[1,0]
	v_cvt_pk_bf16_f32 v118, v118, v119
	v_add_f32_e32 v126, 1.0, v126
	v_add_f32_e32 v127, 1.0, v127
	v_rcp_f32_e32 v126, v126
	v_rcp_f32_e32 v127, v127
	v_pk_mul_f32 v[68:69], v[68:69], v[148:149] op_sel_hi:[1,0]
	v_pk_mul_f32 v[62:63], v[62:63], v[146:147] op_sel_hi:[1,0]
	v_pk_mul_f32 v[54:55], v[54:55], v[146:147] op_sel_hi:[1,0]
	v_pk_mul_f32 v[122:123], v[122:123], v[126:127]
	v_pk_mul_f32 v[58:59], v[58:59], v[146:147] op_sel_hi:[1,0]
	v_pk_mul_f32 v[114:115], v[114:115], v[122:123]
	v_pk_mul_f32 v[122:123], v[128:129], v[154:155] op_sel_hi:[1,0]
	v_pk_mul_f32 v[50:51], v[50:51], v[146:147] op_sel_hi:[1,0]
	v_mul_f32_e32 v126, 0xbfb8aa3b, v122
	v_mul_f32_e32 v127, 0xbfb8aa3b, v123
	v_exp_f32_e32 v126, v126
	v_exp_f32_e32 v127, v127
	v_pk_mul_f32 v[56:57], v[56:57], v[146:147] op_sel_hi:[1,0]
	v_pk_mul_f32 v[52:53], v[52:53], v[146:147] op_sel_hi:[1,0]
	v_add_f32_e32 v126, 1.0, v126
	v_add_f32_e32 v127, 1.0, v127
	v_rcp_f32_e32 v126, v126
	v_rcp_f32_e32 v127, v127
	v_pk_mul_f32 v[46:47], v[46:47], v[144:145] op_sel_hi:[1,0]
	v_pk_mul_f32 v[38:39], v[38:39], v[144:145] op_sel_hi:[1,0]
	v_pk_mul_f32 v[42:43], v[42:43], v[144:145] op_sel_hi:[1,0]
	v_pk_mul_f32 v[122:123], v[122:123], v[126:127]
	v_pk_mul_f32 v[34:35], v[34:35], v[144:145] op_sel_hi:[1,0]
	v_pk_mul_f32 v[120:121], v[120:121], v[122:123]
	v_pk_mul_f32 v[122:123], v[124:125], v[154:155] op_sel_hi:[1,0]
	v_cvt_pk_bf16_f32 v119, v120, v121
	v_mul_f32_e32 v124, 0xbfb8aa3b, v122
	v_mul_f32_e32 v125, 0xbfb8aa3b, v123
	v_exp_f32_e32 v124, v124
	v_exp_f32_e32 v125, v125
	v_cvt_pk_bf16_f32 v120, v114, v115
	v_ashrrev_i32_e32 v114, 31, v153
	v_add_f32_e32 v124, 1.0, v124
	v_add_f32_e32 v125, 1.0, v125
	v_rcp_f32_e32 v124, v124
	v_rcp_f32_e32 v125, v125
	v_pk_mul_f32 v[40:41], v[40:41], v[144:145] op_sel_hi:[1,0]
	v_pk_mul_f32 v[36:37], v[36:37], v[144:145] op_sel_hi:[1,0]
	v_pk_mul_f32 v[30:31], v[30:31], v[142:143] op_sel_hi:[1,0]
	v_pk_mul_f32 v[122:123], v[122:123], v[124:125]
	v_pk_mul_f32 v[22:23], v[22:23], v[142:143] op_sel_hi:[1,0]
	v_pk_mul_f32 v[116:117], v[116:117], v[122:123]
	v_pk_mul_f32 v[26:27], v[26:27], v[142:143] op_sel_hi:[1,0]
	v_cvt_pk_bf16_f32 v121, v116, v117
	v_mul_lo_u32 v116, s12, v114
	v_mul_lo_u32 v117, s13, v153
	v_mad_u64_u32 v[114:115], s[4:5], s12, v153, 0
	v_add3_u32 v115, v115, v116, v117
	v_mul_f32_e32 v117, 0xbfb8aa3b, v110
	v_exp_f32_e32 v117, v117
	v_lshl_add_u64 v[122:123], v[114:115], 1, s[62:63]
	v_lshlrev_b64 v[114:115], 1, v[156:157]
; __device__ __forceinline__ float silu_f(float x) { return x * __builtin_amdgcn_rcpf(1.f + __builtin_amdgcn_exp2f(-LOG2E * x)); }
; __device__ __forceinline__ u32x4 pk8(const f32x4 a, const f32x4 b) { u32x4 w; w.x = pk2(a[0], a[1]); w.y = pk2(a[2], a[3]); w.z = pk2(b[0], b[1]); w.w = pk2(b[2], b[3]); return w; }
; __device__ __forceinline__ float pre_get(const Pre& p, int ai, int m, int fr) { return __shfl(p.v[ai], m * 16 + fr); }
; __device__ __forceinline__ float rstd_pre(const float* ss, float v) { return ss ? rsqrtf(v * (1.0f / 2048.0f) + 1e-6f) : 1.0f; }
;     __device__ __forceinline__ void operator()(const Acc& acc, const Unit& u, int wr, int wc, int fr, int fq, const Pre& pre) const {
;     ...
;         for (int ai = 0; ai < 2; ++ai)
; #pragma unroll
;             for (int m = 0; m < 4; ++m) rsq[ai][m] = rstd_pre(ss, pre_get(pre, ai, m, fr));
; #pragma unroll
;         for (int ai = 0; ai < 2; ++ai)
; #pragma unroll
;             for (int m = 0; m < 4; ++m) {
;                 f32x4 v0, v1; const float rs = rsq[ai][m];
; #pragma unroll
;                 for (int e = 0; e < 4; ++e) { v0[e] = silu_f(acc[ai][0][m][0][e] * rs) * (acc[ai][1][m][0][e] * rs); v1[e] = silu_f(acc[ai][0][m][1][e] * rs) * (acc[ai][1][m][1][e] * rs); }
;                 *(u32x4*)(O + (size_t)(row0 + ai * 128 + m * 16) * ldc + col0) = pk8(v0, v1);
	v_lshl_add_u64 v[122:123], v[122:123], 0, v[114:115]
	v_add_f32_e32 v117, 1.0, v117
	global_store_dwordx4 v[122:123], v[118:121], off
	v_pk_mul_f32 v[18:19], v[18:19], v[142:143] op_sel_hi:[1,0]
	v_pk_mul_f32 v[24:25], v[24:25], v[142:143] op_sel_hi:[1,0]
	v_rcp_f32_e32 v118, v117
	v_mul_f32_e32 v117, 0xbfb8aa3b, v111
	v_exp_f32_e32 v117, v117
	v_pk_mul_f32 v[20:21], v[20:21], v[142:143] op_sel_hi:[1,0]
	v_cndmask_b32_e64 v140, v140, 1.0, s[34:35]
	v_pk_mul_f32 v[14:15], v[14:15], v[140:141] op_sel_hi:[1,0]
	v_add_f32_e32 v117, 1.0, v117
	v_rcp_f32_e32 v119, v117
	v_pk_mul_f32 v[6:7], v[6:7], v[140:141] op_sel_hi:[1,0]
	v_pk_mul_f32 v[10:11], v[10:11], v[140:141] op_sel_hi:[1,0]
	v_pk_mul_f32 v[2:3], v[2:3], v[140:141] op_sel_hi:[1,0]
	v_pk_mul_f32 v[110:111], v[110:111], v[118:119]
	v_pk_mul_f32 v[8:9], v[8:9], v[140:141] op_sel_hi:[1,0]
	v_pk_mul_f32 v[102:103], v[102:103], v[110:111]
	v_mul_f32_e32 v110, 0xbfb8aa3b, v106
	v_mul_f32_e32 v111, 0xbfb8aa3b, v107
	v_exp_f32_e32 v110, v110
	v_exp_f32_e32 v111, v111
	v_pk_mul_f32 v[4:5], v[4:5], v[140:141] op_sel_hi:[1,0]
	s_and_b64 vcc, exec, s[0:1]
	v_add_f32_e32 v110, 1.0, v110
	v_add_f32_e32 v111, 1.0, v111
	v_rcp_f32_e32 v110, v110
	v_rcp_f32_e32 v111, v111
	s_mov_b32 s55, s79
	v_pk_mul_f32 v[106:107], v[106:107], v[110:111]
	s_nop 0
	v_pk_mul_f32 v[106:107], v[98:99], v[106:107]
	v_pk_mul_f32 v[98:99], v[112:113], v[152:153] op_sel_hi:[1,0]
	s_nop 0
	v_mul_f32_e32 v110, 0xbfb8aa3b, v98
	v_mul_f32_e32 v111, 0xbfb8aa3b, v99
	v_exp_f32_e32 v110, v110
	v_exp_f32_e32 v111, v111
	v_add_f32_e32 v110, 1.0, v110
	v_add_f32_e32 v111, 1.0, v111
	v_rcp_f32_e32 v110, v110
	v_rcp_f32_e32 v111, v111
	s_nop 0
	v_pk_mul_f32 v[98:99], v[98:99], v[110:111]
	s_nop 0
	v_pk_mul_f32 v[104:105], v[104:105], v[98:99]
	v_pk_mul_f32 v[98:99], v[108:109], v[152:153] op_sel_hi:[1,0]
	s_nop 0
	v_mul_f32_e32 v108, 0xbfb8aa3b, v98
	v_mul_f32_e32 v109, 0xbfb8aa3b, v99
	v_exp_f32_e32 v108, v108
	v_exp_f32_e32 v109, v109
	v_add_f32_e32 v108, 1.0, v108
	v_add_f32_e32 v109, 1.0, v109
	v_rcp_f32_e32 v108, v108
	v_rcp_f32_e32 v109, v109
	s_nop 0
	v_pk_mul_f32 v[98:99], v[98:99], v[108:109]
	s_nop 0
	v_pk_mul_f32 v[108:109], v[100:101], v[98:99]
	v_cvt_pk_bf16_f32 v98, v102, v103
	v_or_b32_e32 v102, 16, v153
	v_cvt_pk_bf16_f32 v99, v104, v105
	v_mul_lo_u32 v104, s13, v102
	v_mad_u64_u32 v[102:103], s[4:5], s12, v102, 0
	v_add3_u32 v103, v103, v116, v104
	v_lshl_add_u64 v[102:103], v[102:103], 1, s[62:63]
	v_cvt_pk_bf16_f32 v100, v106, v107
	v_cvt_pk_bf16_f32 v101, v108, v109
	v_lshl_add_u64 v[102:103], v[102:103], 0, v[114:115]
	global_store_dwordx4 v[102:103], v[98:101], off
	s_nop 1
	v_mul_f32_e32 v98, 0xbfb8aa3b, v94
	v_mul_f32_e32 v99, 0xbfb8aa3b, v95
	v_exp_f32_e32 v98, v98
	v_exp_f32_e32 v99, v99
	v_add_f32_e32 v98, 1.0, v98
	v_add_f32_e32 v99, 1.0, v99
	v_rcp_f32_e32 v98, v98
	v_rcp_f32_e32 v99, v99
	s_nop 0
	v_pk_mul_f32 v[94:95], v[94:95], v[98:99]
	s_nop 0
	v_pk_mul_f32 v[86:87], v[86:87], v[94:95]
	v_mul_f32_e32 v94, 0xbfb8aa3b, v90
	v_mul_f32_e32 v95, 0xbfb8aa3b, v91
	v_exp_f32_e32 v94, v94
	v_exp_f32_e32 v95, v95
	v_add_f32_e32 v94, 1.0, v94
	v_add_f32_e32 v95, 1.0, v95
	v_rcp_f32_e32 v94, v94
	v_rcp_f32_e32 v95, v95
	s_nop 0
	v_pk_mul_f32 v[90:91], v[90:91], v[94:95]
	s_nop 0
	v_pk_mul_f32 v[90:91], v[82:83], v[90:91]
	v_pk_mul_f32 v[82:83], v[96:97], v[150:151] op_sel_hi:[1,0]
	s_nop 0
	v_mul_f32_e32 v94, 0xbfb8aa3b, v82
	v_mul_f32_e32 v95, 0xbfb8aa3b, v83
	v_exp_f32_e32 v94, v94
	v_exp_f32_e32 v95, v95
	v_add_f32_e32 v94, 1.0, v94
	v_add_f32_e32 v95, 1.0, v95
	v_rcp_f32_e32 v94, v94
	v_rcp_f32_e32 v95, v95
	s_nop 0
	v_pk_mul_f32 v[82:83], v[82:83], v[94:95]
	s_nop 0
	v_pk_mul_f32 v[88:89], v[88:89], v[82:83]
	v_pk_mul_f32 v[82:83], v[92:93], v[150:151] op_sel_hi:[1,0]
	s_nop 0
	v_mul_f32_e32 v92, 0xbfb8aa3b, v82
	v_mul_f32_e32 v93, 0xbfb8aa3b, v83
	v_exp_f32_e32 v92, v92
	v_exp_f32_e32 v93, v93
	v_add_f32_e32 v92, 1.0, v92
	v_add_f32_e32 v93, 1.0, v93
	v_rcp_f32_e32 v92, v92
	v_rcp_f32_e32 v93, v93
	s_nop 0
	v_pk_mul_f32 v[82:83], v[82:83], v[92:93]
	s_nop 0
	v_pk_mul_f32 v[92:93], v[84:85], v[82:83]
	v_cvt_pk_bf16_f32 v82, v86, v87
	v_or_b32_e32 v86, 32, v153
	v_cvt_pk_bf16_f32 v83, v88, v89
	v_mul_lo_u32 v88, s13, v86
	v_mad_u64_u32 v[86:87], s[4:5], s12, v86, 0
	v_add3_u32 v87, v87, v116, v88
	v_lshl_add_u64 v[86:87], v[86:87], 1, s[62:63]
	v_cvt_pk_bf16_f32 v84, v90, v91
	v_cvt_pk_bf16_f32 v85, v92, v93
	v_lshl_add_u64 v[86:87], v[86:87], 0, v[114:115]
	global_store_dwordx4 v[86:87], v[82:85], off
	s_nop 1
	v_mul_f32_e32 v82, 0xbfb8aa3b, v78
	v_mul_f32_e32 v83, 0xbfb8aa3b, v79
	v_exp_f32_e32 v82, v82
	v_exp_f32_e32 v83, v83
	v_add_f32_e32 v82, 1.0, v82
	v_add_f32_e32 v83, 1.0, v83
	v_rcp_f32_e32 v82, v82
	v_rcp_f32_e32 v83, v83
	s_nop 0
	v_pk_mul_f32 v[78:79], v[78:79], v[82:83]
	s_nop 0
	v_pk_mul_f32 v[70:71], v[70:71], v[78:79]
	v_mul_f32_e32 v78, 0xbfb8aa3b, v74
	v_mul_f32_e32 v79, 0xbfb8aa3b, v75
	v_exp_f32_e32 v78, v78
	v_exp_f32_e32 v79, v79
	v_add_f32_e32 v78, 1.0, v78
	v_add_f32_e32 v79, 1.0, v79
	v_rcp_f32_e32 v78, v78
	v_rcp_f32_e32 v79, v79
	s_nop 0
	v_pk_mul_f32 v[74:75], v[74:75], v[78:79]
	s_nop 0
	v_pk_mul_f32 v[74:75], v[66:67], v[74:75]
	v_pk_mul_f32 v[66:67], v[80:81], v[148:149] op_sel_hi:[1,0]
	s_nop 0
	v_mul_f32_e32 v78, 0xbfb8aa3b, v66
	v_mul_f32_e32 v79, 0xbfb8aa3b, v67
	v_exp_f32_e32 v78, v78
	v_exp_f32_e32 v79, v79
	v_add_f32_e32 v78, 1.0, v78
	v_add_f32_e32 v79, 1.0, v79
	v_rcp_f32_e32 v78, v78
	v_rcp_f32_e32 v79, v79
	s_nop 0
	v_pk_mul_f32 v[66:67], v[66:67], v[78:79]
	s_nop 0
	v_pk_mul_f32 v[72:73], v[72:73], v[66:67]
	v_pk_mul_f32 v[66:67], v[76:77], v[148:149] op_sel_hi:[1,0]
; __device__ __forceinline__ float silu_f(float x) { return x * __builtin_amdgcn_rcpf(1.f + __builtin_amdgcn_exp2f(-LOG2E * x)); }
; __device__ __forceinline__ u32x4 pk8(const f32x4 a, const f32x4 b) { u32x4 w; w.x = pk2(a[0], a[1]); w.y = pk2(a[2], a[3]); w.z = pk2(b[0], b[1]); w.w = pk2(b[2], b[3]); return w; }
; __device__ __forceinline__ float pre_get(const Pre& p, int ai, int m, int fr) { return __shfl(p.v[ai], m * 16 + fr); }
; __device__ __forceinline__ float rstd_pre(const float* ss, float v) { return ss ? rsqrtf(v * (1.0f / 2048.0f) + 1e-6f) : 1.0f; }
;     __device__ __forceinline__ void operator()(const Acc& acc, const Unit& u, int wr, int wc, int fr, int fq, const Pre& pre) const {
;     ...
;         for (int ai = 0; ai < 2; ++ai)
; #pragma unroll
;             for (int m = 0; m < 4; ++m) rsq[ai][m] = rstd_pre(ss, pre_get(pre, ai, m, fr));
; #pragma unroll
;         for (int ai = 0; ai < 2; ++ai)
; #pragma unroll
;             for (int m = 0; m < 4; ++m) {
;                 f32x4 v0, v1; const float rs = rsq[ai][m];
; #pragma unroll
;                 for (int e = 0; e < 4; ++e) { v0[e] = silu_f(acc[ai][0][m][0][e] * rs) * (acc[ai][1][m][0][e] * rs); v1[e] = silu_f(acc[ai][0][m][1][e] * rs) * (acc[ai][1][m][1][e] * rs); }
;                 *(u32x4*)(O + (size_t)(row0 + ai * 128 + m * 16) * ldc + col0) = pk8(v0, v1);
	s_nop 0
	v_mul_f32_e32 v76, 0xbfb8aa3b, v66
	v_mul_f32_e32 v77, 0xbfb8aa3b, v67
	v_exp_f32_e32 v76, v76
	v_exp_f32_e32 v77, v77
	v_add_f32_e32 v76, 1.0, v76
	v_add_f32_e32 v77, 1.0, v77
	v_rcp_f32_e32 v76, v76
	v_rcp_f32_e32 v77, v77
	s_nop 0
	v_pk_mul_f32 v[66:67], v[66:67], v[76:77]
	s_nop 0
	v_pk_mul_f32 v[76:77], v[68:69], v[66:67]
	v_cvt_pk_bf16_f32 v66, v70, v71
	v_or_b32_e32 v70, 48, v153
	v_cvt_pk_bf16_f32 v67, v72, v73
	v_mul_lo_u32 v72, s13, v70
	v_mad_u64_u32 v[70:71], s[4:5], s12, v70, 0
	v_add3_u32 v71, v71, v116, v72
	v_lshl_add_u64 v[70:71], v[70:71], 1, s[62:63]
	v_cvt_pk_bf16_f32 v68, v74, v75
	v_cvt_pk_bf16_f32 v69, v76, v77
	v_lshl_add_u64 v[70:71], v[70:71], 0, v[114:115]
	global_store_dwordx4 v[70:71], v[66:69], off
	s_nop 1
	v_mul_f32_e32 v66, 0xbfb8aa3b, v62
	v_mul_f32_e32 v67, 0xbfb8aa3b, v63
	v_exp_f32_e32 v66, v66
	v_exp_f32_e32 v67, v67
	v_add_u32_e32 v68, 0x80, v153
	v_add_f32_e32 v66, 1.0, v66
	v_add_f32_e32 v67, 1.0, v67
	v_rcp_f32_e32 v66, v66
	v_rcp_f32_e32 v67, v67
	s_nop 0
	v_pk_mul_f32 v[62:63], v[62:63], v[66:67]
	s_nop 0
	v_pk_mul_f32 v[54:55], v[54:55], v[62:63]
	v_mul_f32_e32 v62, 0xbfb8aa3b, v58
	v_mul_f32_e32 v63, 0xbfb8aa3b, v59
	v_exp_f32_e32 v62, v62
	v_exp_f32_e32 v63, v63
	v_add_f32_e32 v62, 1.0, v62
	v_add_f32_e32 v63, 1.0, v63
	v_rcp_f32_e32 v62, v62
	v_rcp_f32_e32 v63, v63
	s_nop 0
	v_pk_mul_f32 v[58:59], v[58:59], v[62:63]
	s_nop 0
	v_pk_mul_f32 v[58:59], v[50:51], v[58:59]
	v_pk_mul_f32 v[50:51], v[64:65], v[146:147] op_sel_hi:[1,0]
	s_nop 0
	v_mul_f32_e32 v62, 0xbfb8aa3b, v50
	v_mul_f32_e32 v63, 0xbfb8aa3b, v51
	v_exp_f32_e32 v62, v62
	v_exp_f32_e32 v63, v63
	v_add_f32_e32 v62, 1.0, v62
	v_add_f32_e32 v63, 1.0, v63
	v_rcp_f32_e32 v62, v62
	v_rcp_f32_e32 v63, v63
	s_nop 0
	v_pk_mul_f32 v[50:51], v[50:51], v[62:63]
	s_nop 0
	v_pk_mul_f32 v[56:57], v[56:57], v[50:51]
	v_pk_mul_f32 v[50:51], v[60:61], v[146:147] op_sel_hi:[1,0]
	s_nop 0
	v_mul_f32_e32 v60, 0xbfb8aa3b, v50
	v_mul_f32_e32 v61, 0xbfb8aa3b, v51
	v_exp_f32_e32 v60, v60
	v_exp_f32_e32 v61, v61
	v_add_f32_e32 v60, 1.0, v60
	v_add_f32_e32 v61, 1.0, v61
	v_rcp_f32_e32 v60, v60
	v_rcp_f32_e32 v61, v61
	s_nop 0
	v_pk_mul_f32 v[50:51], v[50:51], v[60:61]
	s_nop 0
	v_pk_mul_f32 v[60:61], v[52:53], v[50:51]
	v_cvt_pk_bf16_f32 v50, v54, v55
	v_ashrrev_i32_e32 v54, 31, v68
	v_cvt_pk_bf16_f32 v51, v56, v57
	v_mul_lo_u32 v56, s12, v54
	v_mul_lo_u32 v57, s13, v68
	v_mad_u64_u32 v[54:55], s[4:5], s12, v68, 0
	v_add3_u32 v55, v55, v56, v57
	v_lshl_add_u64 v[54:55], v[54:55], 1, s[62:63]
	v_cvt_pk_bf16_f32 v52, v58, v59
	v_cvt_pk_bf16_f32 v53, v60, v61
	v_lshl_add_u64 v[54:55], v[54:55], 0, v[114:115]
	global_store_dwordx4 v[54:55], v[50:53], off
	s_nop 1
	v_mul_f32_e32 v50, 0xbfb8aa3b, v46
	v_mul_f32_e32 v51, 0xbfb8aa3b, v47
	v_exp_f32_e32 v50, v50
	v_exp_f32_e32 v51, v51
	v_add_f32_e32 v50, 1.0, v50
	v_add_f32_e32 v51, 1.0, v51
	v_rcp_f32_e32 v50, v50
	v_rcp_f32_e32 v51, v51
	s_nop 0
	v_pk_mul_f32 v[46:47], v[46:47], v[50:51]
	s_nop 0
	v_pk_mul_f32 v[38:39], v[38:39], v[46:47]
	v_mul_f32_e32 v46, 0xbfb8aa3b, v42
	v_mul_f32_e32 v47, 0xbfb8aa3b, v43
	v_exp_f32_e32 v46, v46
	v_exp_f32_e32 v47, v47
	v_add_f32_e32 v46, 1.0, v46
	v_add_f32_e32 v47, 1.0, v47
	v_rcp_f32_e32 v46, v46
	v_rcp_f32_e32 v47, v47
	s_nop 0
	v_pk_mul_f32 v[42:43], v[42:43], v[46:47]
	s_nop 0
	v_pk_mul_f32 v[42:43], v[34:35], v[42:43]
	v_pk_mul_f32 v[34:35], v[48:49], v[144:145] op_sel_hi:[1,0]
	s_nop 0
	v_mul_f32_e32 v46, 0xbfb8aa3b, v34
	v_mul_f32_e32 v47, 0xbfb8aa3b, v35
	v_exp_f32_e32 v46, v46
	v_exp_f32_e32 v47, v47
	v_add_f32_e32 v46, 1.0, v46
	v_add_f32_e32 v47, 1.0, v47
	v_rcp_f32_e32 v46, v46
	v_rcp_f32_e32 v47, v47
	s_nop 0
	v_pk_mul_f32 v[34:35], v[34:35], v[46:47]
	s_nop 0
	v_pk_mul_f32 v[40:41], v[40:41], v[34:35]
	v_pk_mul_f32 v[34:35], v[44:45], v[144:145] op_sel_hi:[1,0]
	s_nop 0
	v_mul_f32_e32 v44, 0xbfb8aa3b, v34
	v_mul_f32_e32 v45, 0xbfb8aa3b, v35
	v_exp_f32_e32 v44, v44
	v_exp_f32_e32 v45, v45
	v_add_f32_e32 v44, 1.0, v44
	v_add_f32_e32 v45, 1.0, v45
	v_rcp_f32_e32 v44, v44
	v_rcp_f32_e32 v45, v45
	s_nop 0
	v_pk_mul_f32 v[34:35], v[34:35], v[44:45]
	s_nop 0
	v_pk_mul_f32 v[44:45], v[36:37], v[34:35]
	v_cvt_pk_bf16_f32 v34, v38, v39
	v_add_u32_e32 v38, 0x90, v153
	v_ashrrev_i32_e32 v39, 31, v38
; __device__ __forceinline__ float silu_f(float x) { return x * __builtin_amdgcn_rcpf(1.f + __builtin_amdgcn_exp2f(-LOG2E * x)); }
; __device__ __forceinline__ u32x4 pk8(const f32x4 a, const f32x4 b) { u32x4 w; w.x = pk2(a[0], a[1]); w.y = pk2(a[2], a[3]); w.z = pk2(b[0], b[1]); w.w = pk2(b[2], b[3]); return w; }
; template <class Epi>
; __device__ __forceinline__ void gemm_phase(LAS unsigned char* lds, const Gemm g, const Sched& S, const Epi& E) {
;     ...
;         E(acc, cur, wr, wc, fr, fq, pre);
;         if (!has_next) break;
;     __device__ __forceinline__ void operator()(const Acc& acc, const Unit& u, int wr, int wc, int fr, int fq, const Pre& pre) const {
;     ...
;         for (int ai = 0; ai < 2; ++ai)
; #pragma unroll
;             for (int m = 0; m < 4; ++m) {
;                 f32x4 v0, v1; const float rs = rsq[ai][m];
; #pragma unroll
;                 for (int e = 0; e < 4; ++e) { v0[e] = silu_f(acc[ai][0][m][0][e] * rs) * (acc[ai][1][m][0][e] * rs); v1[e] = silu_f(acc[ai][0][m][1][e] * rs) * (acc[ai][1][m][1][e] * rs); }
;                 *(u32x4*)(O + (size_t)(row0 + ai * 128 + m * 16) * ldc + col0) = pk8(v0, v1);
;             }
	v_cvt_pk_bf16_f32 v35, v40, v41
	v_mul_lo_u32 v40, s12, v39
	v_mul_lo_u32 v41, s13, v38
	v_mad_u64_u32 v[38:39], s[4:5], s12, v38, 0
	v_add3_u32 v39, v39, v40, v41
	v_lshl_add_u64 v[38:39], v[38:39], 1, s[62:63]
	v_cvt_pk_bf16_f32 v36, v42, v43
	v_cvt_pk_bf16_f32 v37, v44, v45
	v_lshl_add_u64 v[38:39], v[38:39], 0, v[114:115]
	global_store_dwordx4 v[38:39], v[34:37], off
	s_nop 1
	v_mul_f32_e32 v34, 0xbfb8aa3b, v30
	v_mul_f32_e32 v35, 0xbfb8aa3b, v31
	v_exp_f32_e32 v34, v34
	v_exp_f32_e32 v35, v35
	v_add_f32_e32 v34, 1.0, v34
	v_add_f32_e32 v35, 1.0, v35
	v_rcp_f32_e32 v34, v34
	v_rcp_f32_e32 v35, v35
	s_nop 0
	v_pk_mul_f32 v[30:31], v[30:31], v[34:35]
	s_nop 0
	v_pk_mul_f32 v[22:23], v[22:23], v[30:31]
	v_mul_f32_e32 v30, 0xbfb8aa3b, v26
	v_mul_f32_e32 v31, 0xbfb8aa3b, v27
	v_exp_f32_e32 v30, v30
	v_exp_f32_e32 v31, v31
	v_add_f32_e32 v30, 1.0, v30
	v_add_f32_e32 v31, 1.0, v31
	v_rcp_f32_e32 v30, v30
	v_rcp_f32_e32 v31, v31
	s_nop 0
	v_pk_mul_f32 v[26:27], v[26:27], v[30:31]
	s_nop 0
	v_pk_mul_f32 v[26:27], v[18:19], v[26:27]
	v_pk_mul_f32 v[18:19], v[32:33], v[142:143] op_sel_hi:[1,0]
	s_nop 0
	v_mul_f32_e32 v30, 0xbfb8aa3b, v18
	v_mul_f32_e32 v31, 0xbfb8aa3b, v19
	v_exp_f32_e32 v30, v30
	v_exp_f32_e32 v31, v31
	v_add_f32_e32 v30, 1.0, v30
	v_add_f32_e32 v31, 1.0, v31
	v_rcp_f32_e32 v30, v30
	v_rcp_f32_e32 v31, v31
	s_nop 0
	v_pk_mul_f32 v[18:19], v[18:19], v[30:31]
	s_nop 0
	v_pk_mul_f32 v[24:25], v[24:25], v[18:19]
	v_pk_mul_f32 v[18:19], v[28:29], v[142:143] op_sel_hi:[1,0]
	s_nop 0
	v_mul_f32_e32 v28, 0xbfb8aa3b, v18
	v_mul_f32_e32 v29, 0xbfb8aa3b, v19
	v_exp_f32_e32 v28, v28
	v_exp_f32_e32 v29, v29
	v_add_f32_e32 v28, 1.0, v28
	v_add_f32_e32 v29, 1.0, v29
	v_rcp_f32_e32 v28, v28
	v_rcp_f32_e32 v29, v29
	s_nop 0
	v_pk_mul_f32 v[18:19], v[18:19], v[28:29]
	s_nop 0
	v_pk_mul_f32 v[28:29], v[20:21], v[18:19]
	v_cvt_pk_bf16_f32 v18, v22, v23
	v_add_u32_e32 v22, 0xa0, v153
	v_ashrrev_i32_e32 v23, 31, v22
	v_cvt_pk_bf16_f32 v19, v24, v25
	v_mul_lo_u32 v24, s12, v23
	v_mul_lo_u32 v25, s13, v22
	v_mad_u64_u32 v[22:23], s[4:5], s12, v22, 0
	v_add3_u32 v23, v23, v24, v25
	v_lshl_add_u64 v[22:23], v[22:23], 1, s[62:63]
	v_cvt_pk_bf16_f32 v20, v26, v27
	v_cvt_pk_bf16_f32 v21, v28, v29
	v_lshl_add_u64 v[22:23], v[22:23], 0, v[114:115]
	global_store_dwordx4 v[22:23], v[18:21], off
	s_nop 1
	v_mul_f32_e32 v18, 0xbfb8aa3b, v14
	v_mul_f32_e32 v19, 0xbfb8aa3b, v15
	v_exp_f32_e32 v18, v18
	v_exp_f32_e32 v19, v19
	v_add_f32_e32 v18, 1.0, v18
	v_add_f32_e32 v19, 1.0, v19
	v_rcp_f32_e32 v18, v18
	v_rcp_f32_e32 v19, v19
	s_nop 0
	v_pk_mul_f32 v[14:15], v[14:15], v[18:19]
	s_nop 0
	v_pk_mul_f32 v[6:7], v[6:7], v[14:15]
	v_mul_f32_e32 v14, 0xbfb8aa3b, v10
	v_mul_f32_e32 v15, 0xbfb8aa3b, v11
	v_exp_f32_e32 v14, v14
	v_exp_f32_e32 v15, v15
	v_add_f32_e32 v14, 1.0, v14
	v_add_f32_e32 v15, 1.0, v15
	v_rcp_f32_e32 v14, v14
	v_rcp_f32_e32 v15, v15
	s_nop 0
	v_pk_mul_f32 v[10:11], v[10:11], v[14:15]
	s_nop 0
	v_pk_mul_f32 v[10:11], v[2:3], v[10:11]
	v_pk_mul_f32 v[2:3], v[16:17], v[140:141] op_sel_hi:[1,0]
	s_nop 0
	v_mul_f32_e32 v14, 0xbfb8aa3b, v2
	v_mul_f32_e32 v15, 0xbfb8aa3b, v3
	v_exp_f32_e32 v14, v14
	v_exp_f32_e32 v15, v15
	v_add_f32_e32 v14, 1.0, v14
	v_add_f32_e32 v15, 1.0, v15
	v_rcp_f32_e32 v14, v14
	v_rcp_f32_e32 v15, v15
	s_nop 0
	v_pk_mul_f32 v[2:3], v[2:3], v[14:15]
	s_nop 0
	v_pk_mul_f32 v[8:9], v[8:9], v[2:3]
	v_pk_mul_f32 v[2:3], v[12:13], v[140:141] op_sel_hi:[1,0]
	s_nop 0
	v_mul_f32_e32 v12, 0xbfb8aa3b, v2
	v_mul_f32_e32 v13, 0xbfb8aa3b, v3
	v_exp_f32_e32 v12, v12
	v_exp_f32_e32 v13, v13
	v_add_f32_e32 v12, 1.0, v12
	v_add_f32_e32 v13, 1.0, v13
	v_rcp_f32_e32 v12, v12
	v_rcp_f32_e32 v13, v13
	s_nop 0
	v_pk_mul_f32 v[2:3], v[2:3], v[12:13]
	s_nop 0
	v_pk_mul_f32 v[12:13], v[4:5], v[2:3]
	v_cvt_pk_bf16_f32 v2, v6, v7
	v_add_u32_e32 v6, 0xb0, v153
	v_ashrrev_i32_e32 v7, 31, v6
	v_cvt_pk_bf16_f32 v3, v8, v9
	v_mul_lo_u32 v8, s12, v7
	v_mul_lo_u32 v9, s13, v6
	v_mad_u64_u32 v[6:7], s[4:5], s12, v6, 0
	v_add3_u32 v7, v7, v8, v9
	v_lshl_add_u64 v[6:7], v[6:7], 1, s[62:63]
	v_cvt_pk_bf16_f32 v4, v10, v11
	v_cvt_pk_bf16_f32 v5, v12, v13
	v_lshl_add_u64 v[6:7], v[6:7], 0, v[114:115]
	s_mov_b64 s[4:5], s[64:65]
	global_store_dwordx4 v[6:7], v[2:5], off
	s_cbranch_vccz .LBB0_813
	s_branch .LBB0_828
